# GEMM k-loop rewritten: BK=64 full-128B-line LDS-DMA, A-halves share W slice, register-pipelined fragments
# speedup vs baseline: 1.0896x; 1.0896x over previous
; __device__ __forceinline__ int ltid() { int t = threadIdx.x; asm volatile("" : "+v"(t)); return t; }
; #define WAIT_V(n) asm volatile("s_waitcnt vmcnt(%0)" ::"n"(n) : "memory")
; #define RAW_BARRIER() do { asm volatile("s_waitcnt lgkmcnt(0)" ::: "memory"); __builtin_amdgcn_s_barrier(); } while (0)
; __device__ __forceinline__ void gb_issue(const u16* ga, const u16* gw, size_t a64, size_t w64, int ko, u16* __restrict__ wr, int wave) {
; #pragma unroll
;   for (int i = 0; i < 4; i++)
;     __builtin_amdgcn_global_load_lds((const unsigned*)(ga + i * a64 + ko), (lds_u32*)(wr + (i * 4 + wave) * 512), 16, 0, 0);
; #pragma unroll
;   for (int i = 0; i < 2; i++)
;     __builtin_amdgcn_global_load_lds((const unsigned*)(gw + i * w64 + ko), (lds_u32*)(wr + 256 * GST + (i * 4 + wave) * 512), 16, 0, 0);
; }
; template <class F>
; __device__ __forceinline__ void gemm_big(const ALbf& al, const u16* __restrict__ Wt, int K, int m0, int n0, const F& f, u16* sm) {
;   const int tid = ltid(), lane = tid & 63, wave = tid >> 6;
;   const int wm = wave >> 1, wn = wave & 1;
;   const int rsw = GSW(lane & 15, lane >> 4);
;   f32x4 acc[4][8];
; #pragma unroll
;   for (int i = 0; i < 4; i++)
; #pragma unroll
;     for (int j = 0; j < 8; j++) acc[i][j] = (f32x4){0.f, 0.f, 0.f, 0.f};
;   const int srow = lane >> 2;
;   const int scol = ((lane & 3) ^ ((0 - (srow >> 2)) & 3)) * 8;
;   const u16* ga = al.A + (size_t)(m0 + wave * 16 + srow) * al.lda + scol;
;   const u16* gw = Wt + (size_t)(n0 + wave * 16 + srow) * K + scol;
;   const size_t a64 = (size_t)64 * al.lda, w64 = (size_t)64 * K;
;   const int nk = K >> 5;
;   WAIT_V(0);
;   gb_issue(ga, gw, a64, w64, 0, sm, wave);
;   gb_issue(ga, gw, a64, w64, 32, sm + GB_STAGE_EL, wave);
;   WAIT_V(6);
;   RAW_BARRIER();
.LBB0_194:
	v_mov_b32_e32 v138, v132
	s_lshl_b32 s8, s13, 8
	v_lshrrev_b32_e32 v0, 2, v138
	v_bfe_u32 v140, v138, 4, 2
	v_sub_u32_e32 v0, 0, v0
	v_bitop3_b32 v0, v140, v0, 3 bitop3:0x78
	v_lshlrev_b32_e32 v6, 4, v0
	v_lshrrev_b32_e32 v0, 4, v138
	v_ashrrev_i32_e32 v4, 6, v138
	v_sub_u32_e32 v8, 0, v0
	s_and_b32 s15, s8, 0x3f00
	s_lshl_b32 s8, s13, 1
	v_bfe_u32 v7, v138, 2, 4
	v_xor_b32_e32 v2, v138, v8
	v_lshlrev_b32_e32 v9, 4, v4
	s_load_dwordx16 s[60:75], s[0:1], 0x1a0
	s_and_b32 s14, s8, 0xffffff80
	v_or_b32_e32 v3, v7, v9
	v_lshlrev_b32_e32 v2, 4, v2
	v_add_u32_e32 v0, s15, v3
	v_and_b32_e32 v134, 48, v2
	v_add_u32_e32 v2, s14, v3
	v_ashrrev_i32_e32 v1, 31, v0
	v_ashrrev_i32_e32 v3, 31, v2
	v_lshlrev_b64 v[0:1], 11, v[0:1]
	v_lshlrev_b64 v[2:3], 11, v[2:3]
	v_lshl_add_u64 v[0:1], s[30:31], 0, v[0:1]
	s_waitcnt lgkmcnt(0)
	v_lshl_add_u64 v[2:3], s[68:69], 0, v[2:3]
	v_lshl_add_u64 v[0:1], v[0:1], 0, v[134:135]
	v_lshl_add_u64 v[2:3], v[2:3], 0, v[134:135]
	v_lshlrev_b32_e32 v134, 10, v4
	v_add_u32_e32 v10, 0x1000, v134
	v_readfirstlane_b32 s8, v134
	s_waitcnt vmcnt(0)
	s_mov_b32 m0, s8
	v_readfirstlane_b32 s8, v10
	v_add_u32_e32 v10, 0x2000, v134
	v_lshl_add_u64 v[4:5], v[0:1], 0, s[96:97]
	s_mov_b32 m0, s8
	v_readfirstlane_b32 s8, v10
	v_lshl_add_u64 v[4:5], v[0:1], 0, s[86:87]
	s_mov_b32 m0, s8
	s_mov_b64 s[8:9], 0x60000
	v_add_u32_e32 v10, 0x3000, v134
	v_lshl_add_u64 v[4:5], v[0:1], 0, s[8:9]
	v_readfirstlane_b32 s8, v10
	s_mov_b32 m0, s8
	v_add_u32_e32 v10, 0x5000, v134
	v_add_u32_e32 v4, 0x4000, v134
	s_mov_b64 s[10:11], 0x20040
	v_readfirstlane_b32 s8, v4
	s_mov_b32 m0, s8
	v_readfirstlane_b32 s8, v10
	v_add_u32_e32 v10, 0x6000, v134
	v_lshl_add_u64 v[4:5], v[2:3], 0, s[96:97]
	s_mov_b32 m0, s8
	v_readfirstlane_b32 s8, v10
	v_add_u32_e32 v10, 0x7000, v134
	v_lshl_add_u64 v[4:5], v[0:1], 0, 64
	s_mov_b32 m0, s8
	v_readfirstlane_b32 s8, v10
	v_lshl_add_u64 v[4:5], v[0:1], 0, s[10:11]
	s_mov_b32 m0, s8
	s_mov_b64 s[8:9], 0x40040
	v_add_u32_e32 v10, 0x8000, v134
	v_lshl_add_u64 v[4:5], v[0:1], 0, s[8:9]
	v_readfirstlane_b32 s8, v10
	s_mov_b32 m0, s8
	s_mov_b64 s[8:9], 0x60040
	v_add_u32_e32 v4, 0x9000, v134
	v_lshl_add_u64 v[0:1], v[0:1], 0, s[8:9]
	v_readfirstlane_b32 s8, v4
	v_add_u32_e32 v4, 0xa000, v134
	s_mov_b32 m0, s8
	v_readfirstlane_b32 s8, v4
	v_lshl_add_u64 v[0:1], v[2:3], 0, 64
	s_mov_b32 m0, s8
	s_and_b32 s6, s4, 0xffffff80
	v_lshl_add_u64 v[0:1], v[2:3], 0, s[10:11]
	v_add_u32_e32 v2, 0xb000, v134
	s_and_b32 s7, s12, 0x3f00
	v_readfirstlane_b32 s8, v2
	s_mov_b32 m0, s8
	v_bitop3_b32 v2, v138, 3, v8 bitop3:0x48
	v_lshlrev_b32_e32 v0, 6, v138
	v_and_or_b32 v143, v0, s80, v6
	v_lshlrev_b32_e32 v0, 1, v138
	v_and_b32_e32 v1, 0x43, v138
	v_and_or_b32 v0, v0, 24, v1
	v_lshrrev_b32_e32 v1, 1, v138
	v_and_b32_e32 v1, 2, v1
	v_sub_u32_e32 v1, 0, v1
	v_bitop3_b32 v1, v1, v140, 2 bitop3:0x6c
	v_lshlrev_b32_e32 v1, 4, v1
	v_lshl_or_b32 v144, v0, 6, v1
	v_or_b32_e32 v0, 4, v0
	v_lshlrev_b32_e32 v1, 6, v0
	v_lshrrev_b32_e32 v0, 2, v0
	v_sub_u32_e32 v0, 0, v0
	v_bitop3_b32 v0, v0, v140, 3 bitop3:0x6c
	v_lshl_or_b32 v145, v0, 4, v1
	v_or_b32_e32 v0, s6, v7
	v_add_u32_e32 v0, v0, v9
	v_ashrrev_i32_e32 v1, 31, v0
	v_lshlrev_b64 v[0:1], 11, v[0:1]
	v_lshlrev_b32_e32 v2, 4, v2
	v_or_b32_e32 v0, v0, v2
	v_lshl_add_u64 v[128:129], s[68:69], 0, v[0:1]
	v_or_b32_e32 v0, s7, v7
	v_add_u32_e32 v0, v0, v9
	v_ashrrev_i32_e32 v1, 31, v0
	s_waitcnt vmcnt(6)
	v_lshlrev_b64 v[0:1], 11, v[0:1]
	s_waitcnt lgkmcnt(0)
	v_or_b32_e32 v0, v0, v2
	v_lshl_add_u64 v[130:131], s[30:31], 0, v[0:1]
	v_mov_b32_e32 v0, 0
	s_mov_b32 s16, 0
	s_mov_b64 s[6:7], 0
	s_mov_b32 s17, 0
	v_mov_b32_e32 v1, v0
	v_mov_b32_e32 v2, v0
	v_mov_b32_e32 v3, v0
	v_mov_b32_e32 v4, v0
	v_mov_b32_e32 v5, v0
	v_mov_b32_e32 v6, v0
	v_mov_b32_e32 v7, v0
	v_mov_b32_e32 v32, v0
	v_mov_b32_e32 v33, v0
	v_mov_b32_e32 v34, v0
	v_mov_b32_e32 v35, v0
	v_mov_b32_e32 v36, v0
	v_mov_b32_e32 v37, v0
	v_mov_b32_e32 v38, v0
	v_mov_b32_e32 v39, v0
	v_mov_b32_e32 v8, v0
	v_mov_b32_e32 v9, v0
	v_mov_b32_e32 v10, v0
	v_mov_b32_e32 v11, v0
	v_mov_b32_e32 v12, v0
	v_mov_b32_e32 v13, v0
	v_mov_b32_e32 v14, v0
	v_mov_b32_e32 v15, v0
	v_mov_b32_e32 v48, v0
	v_mov_b32_e32 v49, v0
	v_mov_b32_e32 v50, v0
	v_mov_b32_e32 v51, v0
	v_mov_b32_e32 v52, v0
	v_mov_b32_e32 v53, v0
	v_mov_b32_e32 v54, v0
	v_mov_b32_e32 v55, v0
	v_mov_b32_e32 v16, v0
	v_mov_b32_e32 v17, v0
	v_mov_b32_e32 v18, v0
	v_mov_b32_e32 v19, v0
	v_mov_b32_e32 v20, v0
	v_mov_b32_e32 v21, v0
	v_mov_b32_e32 v22, v0
	v_mov_b32_e32 v23, v0
	v_mov_b32_e32 v64, v0
	v_mov_b32_e32 v65, v0
	v_mov_b32_e32 v66, v0
	v_mov_b32_e32 v67, v0
	v_mov_b32_e32 v68, v0
	v_mov_b32_e32 v69, v0
	v_mov_b32_e32 v70, v0
	v_mov_b32_e32 v71, v0
	v_mov_b32_e32 v24, v0
	v_mov_b32_e32 v25, v0
	v_mov_b32_e32 v26, v0
	v_mov_b32_e32 v27, v0
	v_mov_b32_e32 v28, v0
	v_mov_b32_e32 v29, v0
	v_mov_b32_e32 v30, v0
	v_mov_b32_e32 v31, v0
	v_mov_b32_e32 v80, v0
	v_mov_b32_e32 v81, v0
	v_mov_b32_e32 v82, v0
	v_mov_b32_e32 v83, v0
	v_mov_b32_e32 v84, v0
	v_mov_b32_e32 v85, v0
	v_mov_b32_e32 v86, v0
	v_mov_b32_e32 v87, v0
	v_mov_b32_e32 v40, v0
	v_mov_b32_e32 v41, v0
	v_mov_b32_e32 v42, v0
	v_mov_b32_e32 v43, v0
	v_mov_b32_e32 v44, v0
	v_mov_b32_e32 v45, v0
	v_mov_b32_e32 v46, v0
	v_mov_b32_e32 v47, v0
	v_mov_b32_e32 v96, v0
	v_mov_b32_e32 v97, v0
	v_mov_b32_e32 v98, v0
	v_mov_b32_e32 v99, v0
	v_mov_b32_e32 v100, v0
	v_mov_b32_e32 v101, v0
	v_mov_b32_e32 v102, v0
	v_mov_b32_e32 v103, v0
	v_mov_b32_e32 v56, v0
	v_mov_b32_e32 v57, v0
	v_mov_b32_e32 v58, v0
	v_mov_b32_e32 v59, v0
	v_mov_b32_e32 v60, v0
	v_mov_b32_e32 v61, v0
	v_mov_b32_e32 v62, v0
	v_mov_b32_e32 v63, v0
	v_mov_b32_e32 v104, v0
; __device__ __forceinline__ void gb_step(const u16* ga, const u16* gw, size_t a64, size_t w64, int ko, bool issue, ...
;   if (issue) {
; #pragma unroll
;     for (int i = 0; i < 4; i++)
;       __builtin_amdgcn_global_load_lds((const unsigned*)(ga + i * a64 + ko), (lds_u32*)(wr + (i * 4 + wave) * 512), 16, 0, 0);
; #pragma unroll
;     for (int i = 0; i < 2; i++)
;       __builtin_amdgcn_global_load_lds((const unsigned*)(gw + i * w64 + ko), (lds_u32*)(wr + 256 * GST + (i * 4 + wave) * 512), 16, 0, 0);
;   }
;   const unsigned rdb = (unsigned)(size_t)(__attribute__((address_space(3))) const char*)rd;
;   const unsigned ab = rdb + (unsigned)(((wm * 128 + (lane & 15)) * GST + rsw) * 2);
;   const int wr0 = wn * 64 + (((lane & 15) >> 2) << 3) + (lane & 3);
;   const unsigned bb0 = rdb + (unsigned)((256 * GST + wr0 * GST + GSW(wr0, lane >> 4)) * 2);
;   const unsigned bb1 = rdb + (unsigned)((256 * GST + (wr0 + 4) * GST + GSW(wr0 + 4, lane >> 4)) * 2);
;   bf16x8 wf0, wf1, wf2, wf3, xf0, xf1, xf2, xf3, xf4, xf5, xf6, xf7;
;     ...
;   DSR(wf0, bb0, 0); DSR(wf1, bb1, 0); DSR(wf2, bb0, 2048); DSR(wf3, bb1, 2048);
;   DSR(xf0, ab, 0); DSR(xf1, ab, 1024); DSR(xf2, ab, 2048); DSR(xf3, ab, 3072);
;   DSR(xf4, ab, 4096); DSR(xf5, ab, 5120); DSR(xf6, ab, 6144); DSR(xf7, ab, 7168);
;     ...
;   asm volatile("s_waitcnt lgkmcnt(7)" : "+v"(wf0), "+v"(wf1), "+v"(wf2), "+v"(wf3), "+v"(xf0) : : "memory");
;   MM(0, xf0)
;   asm volatile("s_waitcnt lgkmcnt(6)" : "+v"(xf1) : : "memory");
;   MM(1, xf1)
;   asm volatile("s_waitcnt lgkmcnt(5)" : "+v"(xf2) : : "memory");
;   MM(2, xf2)
; template <class F>
; __device__ __forceinline__ void gemm_big(const ALbf& al, const u16* __restrict__ Wt, int K, int m0, int n0, const F& f, u16* sm) {
;     ...
; #pragma unroll
;   for (int i = 0; i < 4; i++)
; #pragma unroll
;     for (int j = 0; j < 8; j++) acc[i][j] = (f32x4){0.f, 0.f, 0.f, 0.f};
;   const int srow = lane >> 2;
;   const int scol = ((lane & 3) ^ ((0 - (srow >> 2)) & 3)) * 8;
;   const u16* ga = al.A + (size_t)(m0 + wave * 16 + srow) * al.lda + scol;
;   const u16* gw = Wt + (size_t)(n0 + wave * 16 + srow) * K + scol;
;   const size_t a64 = (size_t)64 * al.lda, w64 = (size_t)64 * K;
;   const int nk = K >> 5;
;   WAIT_V(0);
;   gb_issue(ga, gw, a64, w64, 0, sm, wave);
;   gb_issue(ga, gw, a64, w64, 32, sm + GB_STAGE_EL, wave);
;   WAIT_V(6);
;   RAW_BARRIER();
	v_mov_b32_e32 v105, v0
	v_mov_b32_e32 v106, v0
	v_mov_b32_e32 v107, v0
	v_mov_b32_e32 v108, v0
	v_mov_b32_e32 v109, v0
	v_mov_b32_e32 v110, v0
	v_mov_b32_e32 v111, v0
	v_mov_b32_e32 v72, v0
	v_mov_b32_e32 v73, v0
	v_mov_b32_e32 v74, v0
	v_mov_b32_e32 v75, v0
	v_mov_b32_e32 v76, v0
	v_mov_b32_e32 v77, v0
	v_mov_b32_e32 v78, v0
	v_mov_b32_e32 v79, v0
	v_mov_b32_e32 v112, v0
	v_mov_b32_e32 v113, v0
	v_mov_b32_e32 v114, v0
	v_mov_b32_e32 v115, v0
	v_mov_b32_e32 v116, v0
	v_mov_b32_e32 v117, v0
	v_mov_b32_e32 v118, v0
	v_mov_b32_e32 v119, v0
	v_mov_b32_e32 v88, v0
	v_mov_b32_e32 v89, v0
	v_mov_b32_e32 v90, v0
	v_mov_b32_e32 v91, v0
	v_mov_b32_e32 v92, v0
	v_mov_b32_e32 v93, v0
	v_mov_b32_e32 v94, v0
	v_mov_b32_e32 v95, v0
	v_mov_b32_e32 v120, v0
	v_mov_b32_e32 v121, v0
	v_mov_b32_e32 v122, v0
	v_mov_b32_e32 v123, v0
	v_mov_b32_e32 v124, v0
	v_mov_b32_e32 v125, v0
	v_mov_b32_e32 v126, v0
	v_mov_b32_e32 v127, v0
	v_readfirstlane_b32 s6, v130
	v_readfirstlane_b32 s7, v131
	v_readfirstlane_b32 s8, v128
	v_readfirstlane_b32 s9, v129
	v_readfirstlane_b32 s17, v134
	v_and_b32_e32 v176, 63, v132
	v_lshrrev_b32_e32 v177, 6, v132
	v_lshrrev_b32_e32 v178, 3, v176
	v_and_b32_e32 v179, 7, v176
	v_lshrrev_b32_e32 v180, 4, v176
	v_and_b32_e32 v181, 1, v177
	v_lshrrev_b32_e32 v182, 1, v177
	v_lshl_add_u32 v183, v181, 2, v180
	v_xor_b32_e32 v183, v179, v183
	v_lshl_add_u32 v184, v177, 3, v178
	v_lshlrev_b32_e32 v188, 11, v184
	v_lshl_add_u32 v128, v183, 4, v188
	v_add_u32_e32 v129, 0x10000, v128
	v_add_u32_e32 v130, 0x40000, v128
	v_add_u32_e32 v131, 0x50000, v128
	v_bfe_u32 v185, v178, 1, 1
	v_lshl_or_b32 v185, v181, 1, v185
	v_lshl_or_b32 v185, v182, 2, v185
	v_xor_b32_e32 v185, v179, v185
	v_lshl_add_u32 v134, v185, 4, v188
	v_add_u32_e32 v143, 0x10000, v134
	v_add_u32_e32 v196, 0x20000, v134
	v_add_u32_e32 v197, 0x30000, v134
	v_and_b32_e32 v186, 15, v176
	v_bfe_u32 v187, v176, 1, 3
	v_xor_b32_e32 v187, v180, v187
	v_lshlrev_b32_e32 v187, 4, v187
	v_lshl_add_u32 v188, v182, 6, v186
	v_lshl_add_u32 v219, v188, 7, v187
	v_xor_b32_e32 v228, 64, v219
	v_lshrrev_b32_e32 v189, 2, v186
	v_lshlrev_b32_e32 v189, 3, v189
	v_and_b32_e32 v188, 3, v186
	v_add_u32_e32 v189, v189, v188
	v_lshl_add_u32 v189, v181, 6, v189
	v_lshl_add_u32 v231, v189, 7, v187
	v_xor_b32_e32 v216, 64, v231
	s_lshl_b32 s11, s17, 5
	s_sub_u32 s6, s6, s11
	s_subb_u32 s7, s7, 0
	s_sub_u32 s8, s8, s11
	s_subb_u32 s9, s9, 0
	s_add_u32 m0, s17, 0x8000
	s_nop 0
	global_load_lds_dwordx4 v128, s[6:7]
	s_add_u32 m0, s17, 0x9000
	s_nop 0
	global_load_lds_dwordx4 v129, s[6:7]
	s_add_u32 m0, s17, 0xa000
	s_nop 0
	global_load_lds_dwordx4 v130, s[6:7]
	s_add_u32 m0, s17, 0xb000
	s_nop 0
	global_load_lds_dwordx4 v131, s[6:7]
	s_add_u32 s6, s6, 0x20000
	s_addc_u32 s7, s7, 0
	s_add_u32 m0, s17, 0xc000
	s_nop 0
	global_load_lds_dwordx4 v128, s[6:7]
	s_add_u32 m0, s17, 0xd000
	s_nop 0
	global_load_lds_dwordx4 v129, s[6:7]
	s_add_u32 m0, s17, 0xe000
	s_nop 0
	global_load_lds_dwordx4 v130, s[6:7]
	s_add_u32 m0, s17, 0xf000
	s_nop 0
	global_load_lds_dwordx4 v131, s[6:7]
	s_add_u32 s6, s6, 0xfffe0080
	s_addc_u32 s7, s7, -1
	s_add_u32 m0, s17, 0x0
	s_nop 0
	global_load_lds_dwordx4 v134, s[8:9]
	s_add_u32 m0, s17, 0x1000
	s_nop 0
	global_load_lds_dwordx4 v143, s[8:9]
	s_add_u32 m0, s17, 0x2000
	s_nop 0
	global_load_lds_dwordx4 v196, s[8:9]
	s_add_u32 m0, s17, 0x3000
	s_nop 0
	global_load_lds_dwordx4 v197, s[8:9]
	s_add_u32 s8, s8, 0x80
	s_addc_u32 s9, s9, 0
	s_add_u32 m0, s17, 0x4000
	s_nop 0
	global_load_lds_dwordx4 v134, s[8:9]
	s_add_u32 m0, s17, 0x5000
	s_nop 0
	global_load_lds_dwordx4 v143, s[8:9]
	s_add_u32 m0, s17, 0x6000
	s_nop 0
	global_load_lds_dwordx4 v196, s[8:9]
	s_add_u32 m0, s17, 0x7000
	s_nop 0
	global_load_lds_dwordx4 v197, s[8:9]
	s_add_u32 s8, s8, 0x80
	s_addc_u32 s9, s9, 0
	s_waitcnt vmcnt(0)
	s_barrier
	s_mov_b32 s10, 0
	s_mov_b32 s16, 0
	ds_read_b128 v[144:147], v219 offset:32768
	ds_read_b128 v[148:151], v219 offset:34816
	ds_read_b128 v[152:155], v219 offset:36864
	ds_read_b128 v[156:159], v219 offset:38912
	ds_read_b128 v[160:163], v228 offset:32768
	ds_read_b128 v[164:167], v228 offset:34816
	ds_read_b128 v[168:171], v228 offset:36864
	ds_read_b128 v[172:175], v228 offset:38912
	v_add_u32_e32 v248, s10, v231
	ds_read_b128 v[236:239], v248 offset:0
	ds_read_b128 v[240:243], v248 offset:512
	ds_read_b128 v[244:247], v248 offset:4096
	ds_read_b128 v[248:251], v248 offset:4608
	s_waitcnt lgkmcnt(0)
	s_barrier
.Lgz0_loop:
	s_cmp_lt_u32 s16, 15
	s_cselect_b64 vcc, -1, 0
	v_add_u32_e32 v212, s10, v216
	ds_read_b128 v[252:255], v212 offset:0
	ds_read_b128 v[204:207], v212 offset:512
	ds_read_b128 v[208:211], v212 offset:4096
	ds_read_b128 v[212:215], v212 offset:4608
	v_mfma_f32_16x16x32_bf16 v[124:127], v[236:239], v[144:147], v[124:127]
	ds_read_b128 v[176:179], v219 offset:49152
	v_mfma_f32_16x16x32_bf16 v[120:123], v[240:243], v[144:147], v[120:123]
	ds_read_b128 v[180:183], v219 offset:51200
	v_mfma_f32_16x16x32_bf16 v[92:95], v[244:247], v[144:147], v[92:95]
	ds_read_b128 v[184:187], v219 offset:53248
	v_mfma_f32_16x16x32_bf16 v[88:91], v[248:251], v[144:147], v[88:91]
	ds_read_b128 v[188:191], v219 offset:55296
	v_mfma_f32_16x16x32_bf16 v[116:119], v[236:239], v[148:151], v[116:119]
	ds_read_b128 v[192:195], v228 offset:49152
	v_mfma_f32_16x16x32_bf16 v[112:115], v[240:243], v[148:151], v[112:115]
	ds_read_b128 v[220:223], v228 offset:51200
	v_mfma_f32_16x16x32_bf16 v[76:79], v[244:247], v[148:151], v[76:79]
	ds_read_b128 v[224:227], v228 offset:53248
	v_mfma_f32_16x16x32_bf16 v[72:75], v[248:251], v[148:151], v[72:75]
	ds_read_b128 v[232:235], v228 offset:55296
	s_add_u32 m0, s17, 0x8000
	v_mfma_f32_16x16x32_bf16 v[108:111], v[236:239], v[152:155], v[108:111]
	s_cbranch_vccz .Lgz0_a0
	global_load_lds_dwordx4 v128, s[6:7]
; __device__ __forceinline__ void gb_step(const u16* ga, const u16* gw, size_t a64, size_t w64, int ko, bool issue, ...
;   if (issue) {
; #pragma unroll
;     for (int i = 0; i < 4; i++)
;       __builtin_amdgcn_global_load_lds((const unsigned*)(ga + i * a64 + ko), (lds_u32*)(wr + (i * 4 + wave) * 512), 16, 0, 0);
; #pragma unroll
;     for (int i = 0; i < 2; i++)
;       __builtin_amdgcn_global_load_lds((const unsigned*)(gw + i * w64 + ko), (lds_u32*)(wr + 256 * GST + (i * 4 + wave) * 512), 16, 0, 0);
;   }
;   const unsigned rdb = (unsigned)(size_t)(__attribute__((address_space(3))) const char*)rd;
;   const unsigned ab = rdb + (unsigned)(((wm * 128 + (lane & 15)) * GST + rsw) * 2);
;   const int wr0 = wn * 64 + (((lane & 15) >> 2) << 3) + (lane & 3);
;   const unsigned bb0 = rdb + (unsigned)((256 * GST + wr0 * GST + GSW(wr0, lane >> 4)) * 2);
;   const unsigned bb1 = rdb + (unsigned)((256 * GST + (wr0 + 4) * GST + GSW(wr0 + 4, lane >> 4)) * 2);
;   bf16x8 wf0, wf1, wf2, wf3, xf0, xf1, xf2, xf3, xf4, xf5, xf6, xf7;
;     ...
;   DSR(wf0, bb0, 0); DSR(wf1, bb1, 0); DSR(wf2, bb0, 2048); DSR(wf3, bb1, 2048);
;   DSR(xf0, ab, 0); DSR(xf1, ab, 1024); DSR(xf2, ab, 2048); DSR(xf3, ab, 3072);
;   DSR(xf4, ab, 4096); DSR(xf5, ab, 5120); DSR(xf6, ab, 6144); DSR(xf7, ab, 7168);
;     ...
;   asm volatile("s_waitcnt lgkmcnt(7)" : "+v"(wf0), "+v"(wf1), "+v"(wf2), "+v"(wf3), "+v"(xf0) : : "memory");
;   MM(0, xf0)
;   asm volatile("s_waitcnt lgkmcnt(6)" : "+v"(xf1) : : "memory");
;   MM(1, xf1)
;   asm volatile("s_waitcnt lgkmcnt(5)" : "+v"(xf2) : : "memory");
;   MM(2, xf2)
;   asm volatile("s_waitcnt lgkmcnt(4)" : "+v"(xf3) : : "memory");
;   MM(3, xf3)
;   asm volatile("s_waitcnt lgkmcnt(3)" : "+v"(xf4) : : "memory");
;   MM(4, xf4)
;   asm volatile("s_waitcnt lgkmcnt(2)" : "+v"(xf5) : : "memory");
;   MM(5, xf5)
;   asm volatile("s_waitcnt lgkmcnt(1)" : "+v"(xf6) : : "memory");
;   MM(6, xf6)
;   asm volatile("s_waitcnt lgkmcnt(0)" : "+v"(xf7) : : "memory");
;   MM(7, xf7)
; template <class F>
; __device__ __forceinline__ void gemm_big(const ALbf& al, const u16* __restrict__ Wt, int K, int m0, int n0, const F& f, u16* sm) {
;     ...
;   for (int kt = 0; kt < nk; ++kt) {
;     const int nxt2 = (cur >= 1) ? cur - 1 : 2;
;     gb_step(ga, gw, a64, w64, (kt + 2) * 32, kt + 2 < nk, sm + cur * GB_STAGE_EL, sm + nxt2 * GB_STAGE_EL, wave, wm, wn, lane, rsw, acc);
.Lgz0_a0:
	v_mfma_f32_16x16x32_bf16 v[104:107], v[240:243], v[152:155], v[104:107]
	s_add_u32 m0, s17, 0x9000
	v_mfma_f32_16x16x32_bf16 v[60:63], v[244:247], v[152:155], v[60:63]
	s_cbranch_vccz .Lgz0_a1
	global_load_lds_dwordx4 v129, s[6:7]
.Lgz0_a1:
	v_mfma_f32_16x16x32_bf16 v[56:59], v[248:251], v[152:155], v[56:59]
	s_add_u32 m0, s17, 0xa000
	v_mfma_f32_16x16x32_bf16 v[100:103], v[236:239], v[156:159], v[100:103]
	s_cbranch_vccz .Lgz0_a2
	global_load_lds_dwordx4 v130, s[6:7]
.Lgz0_a2:
	v_mfma_f32_16x16x32_bf16 v[96:99], v[240:243], v[156:159], v[96:99]
	s_add_u32 m0, s17, 0xb000
	v_mfma_f32_16x16x32_bf16 v[44:47], v[244:247], v[156:159], v[44:47]
	s_cbranch_vccz .Lgz0_a3
	global_load_lds_dwordx4 v131, s[6:7]
.Lgz0_a3:
	v_mfma_f32_16x16x32_bf16 v[40:43], v[248:251], v[156:159], v[40:43]
	s_waitcnt lgkmcnt(8)
	v_mfma_f32_16x16x32_bf16 v[124:127], v[252:255], v[160:163], v[124:127]
	v_mfma_f32_16x16x32_bf16 v[120:123], v[204:207], v[160:163], v[120:123]
	v_mfma_f32_16x16x32_bf16 v[92:95], v[208:211], v[160:163], v[92:95]
	v_mfma_f32_16x16x32_bf16 v[88:91], v[212:215], v[160:163], v[88:91]
	v_mfma_f32_16x16x32_bf16 v[116:119], v[252:255], v[164:167], v[116:119]
	v_mfma_f32_16x16x32_bf16 v[112:115], v[204:207], v[164:167], v[112:115]
	v_mfma_f32_16x16x32_bf16 v[76:79], v[208:211], v[164:167], v[76:79]
	v_mfma_f32_16x16x32_bf16 v[72:75], v[212:215], v[164:167], v[72:75]
	v_mfma_f32_16x16x32_bf16 v[108:111], v[252:255], v[168:171], v[108:111]
	v_mfma_f32_16x16x32_bf16 v[104:107], v[204:207], v[168:171], v[104:107]
	v_mfma_f32_16x16x32_bf16 v[60:63], v[208:211], v[168:171], v[60:63]
	v_mfma_f32_16x16x32_bf16 v[56:59], v[212:215], v[168:171], v[56:59]
	v_mfma_f32_16x16x32_bf16 v[100:103], v[252:255], v[172:175], v[100:103]
	v_mfma_f32_16x16x32_bf16 v[96:99], v[204:207], v[172:175], v[96:99]
	v_mfma_f32_16x16x32_bf16 v[44:47], v[208:211], v[172:175], v[44:47]
	v_mfma_f32_16x16x32_bf16 v[40:43], v[212:215], v[172:175], v[40:43]
	s_waitcnt vmcnt(0)
	s_waitcnt lgkmcnt(0)
	s_add_u32 s6, s6, 0x20000
	s_addc_u32 s7, s7, 0
	s_xor_b32 s11, s10, 0x4000
	s_barrier
	v_mfma_f32_16x16x32_bf16 v[84:87], v[236:239], v[176:179], v[84:87]
	ds_read_b128 v[144:147], v219 offset:32768
	v_mfma_f32_16x16x32_bf16 v[80:83], v[240:243], v[176:179], v[80:83]
	ds_read_b128 v[148:151], v219 offset:34816
	v_mfma_f32_16x16x32_bf16 v[28:31], v[244:247], v[176:179], v[28:31]
	ds_read_b128 v[152:155], v219 offset:36864
	v_mfma_f32_16x16x32_bf16 v[24:27], v[248:251], v[176:179], v[24:27]
	ds_read_b128 v[156:159], v219 offset:38912
	v_mfma_f32_16x16x32_bf16 v[68:71], v[236:239], v[180:183], v[68:71]
	ds_read_b128 v[160:163], v228 offset:32768
	v_mfma_f32_16x16x32_bf16 v[64:67], v[240:243], v[180:183], v[64:67]
	ds_read_b128 v[164:167], v228 offset:34816
	v_mfma_f32_16x16x32_bf16 v[20:23], v[244:247], v[180:183], v[20:23]
	ds_read_b128 v[168:171], v228 offset:36864
	v_mfma_f32_16x16x32_bf16 v[16:19], v[248:251], v[180:183], v[16:19]
	ds_read_b128 v[172:175], v228 offset:38912
	s_add_u32 m0, s17, 0xc000
	v_mfma_f32_16x16x32_bf16 v[52:55], v[236:239], v[184:187], v[52:55]
	s_cbranch_vccz .Lgz0_b0
	global_load_lds_dwordx4 v128, s[6:7]
.Lgz0_b0:
	v_mfma_f32_16x16x32_bf16 v[48:51], v[240:243], v[184:187], v[48:51]
	s_add_u32 m0, s17, 0xd000
	v_mfma_f32_16x16x32_bf16 v[12:15], v[244:247], v[184:187], v[12:15]
	s_cbranch_vccz .Lgz0_b1
	global_load_lds_dwordx4 v129, s[6:7]
.Lgz0_b1:
	v_mfma_f32_16x16x32_bf16 v[8:11], v[248:251], v[184:187], v[8:11]
	s_add_u32 m0, s17, 0xe000
	v_mfma_f32_16x16x32_bf16 v[36:39], v[236:239], v[188:191], v[36:39]
	s_cbranch_vccz .Lgz0_b2
	global_load_lds_dwordx4 v130, s[6:7]
.Lgz0_b2:
	v_mfma_f32_16x16x32_bf16 v[32:35], v[240:243], v[188:191], v[32:35]
	s_add_u32 m0, s17, 0xf000
	v_mfma_f32_16x16x32_bf16 v[4:7], v[244:247], v[188:191], v[4:7]
	s_cbranch_vccz .Lgz0_b3
	global_load_lds_dwordx4 v131, s[6:7]
.Lgz0_b3:
	v_mfma_f32_16x16x32_bf16 v[0:3], v[248:251], v[188:191], v[0:3]
	v_add_u32_e32 v248, s11, v231
	v_mfma_f32_16x16x32_bf16 v[84:87], v[252:255], v[192:195], v[84:87]
	ds_read_b128 v[236:239], v248 offset:0
	v_mfma_f32_16x16x32_bf16 v[80:83], v[204:207], v[192:195], v[80:83]
	ds_read_b128 v[240:243], v248 offset:512
	v_mfma_f32_16x16x32_bf16 v[28:31], v[208:211], v[192:195], v[28:31]
	ds_read_b128 v[244:247], v248 offset:4096
	v_mfma_f32_16x16x32_bf16 v[24:27], v[212:215], v[192:195], v[24:27]
	ds_read_b128 v[248:251], v248 offset:4608
	v_mfma_f32_16x16x32_bf16 v[68:71], v[252:255], v[220:223], v[68:71]
	v_mfma_f32_16x16x32_bf16 v[64:67], v[204:207], v[220:223], v[64:67]
	s_cmp_lt_u32 s16, 14
	s_cbranch_scc0 .Lgz0_w0
	s_add_u32 m0, s17, s10
	s_add_u32 m0, m0, 0x0
	s_nop 0
	global_load_lds_dwordx4 v134, s[8:9]
.Lgz0_w0:
	v_mfma_f32_16x16x32_bf16 v[20:23], v[208:211], v[220:223], v[20:23]
	v_mfma_f32_16x16x32_bf16 v[16:19], v[212:215], v[220:223], v[16:19]
	s_cmp_lt_u32 s16, 14
	s_cbranch_scc0 .Lgz0_w1
	s_add_u32 m0, s17, s10
	s_add_u32 m0, m0, 0x1000
	s_nop 0
	global_load_lds_dwordx4 v143, s[8:9]
.Lgz0_w1:
	v_mfma_f32_16x16x32_bf16 v[52:55], v[252:255], v[224:227], v[52:55]
	v_mfma_f32_16x16x32_bf16 v[48:51], v[204:207], v[224:227], v[48:51]
	s_cmp_lt_u32 s16, 14
	s_cbranch_scc0 .Lgz0_w2
	s_add_u32 m0, s17, s10
	s_add_u32 m0, m0, 0x2000
	s_nop 0
	global_load_lds_dwordx4 v196, s[8:9]
.Lgz0_w2:
	v_mfma_f32_16x16x32_bf16 v[12:15], v[208:211], v[224:227], v[12:15]
	v_mfma_f32_16x16x32_bf16 v[8:11], v[212:215], v[224:227], v[8:11]
	s_cmp_lt_u32 s16, 14
	s_cbranch_scc0 .Lgz0_w3
	s_add_u32 m0, s17, s10
	s_add_u32 m0, m0, 0x3000
	s_nop 0
	global_load_lds_dwordx4 v197, s[8:9]
.Lgz0_w3:
	v_mfma_f32_16x16x32_bf16 v[36:39], v[252:255], v[232:235], v[36:39]
	v_mfma_f32_16x16x32_bf16 v[32:35], v[204:207], v[232:235], v[32:35]
	v_mfma_f32_16x16x32_bf16 v[4:7], v[208:211], v[232:235], v[4:7]
	v_mfma_f32_16x16x32_bf16 v[0:3], v[212:215], v[232:235], v[0:3]
	s_cmp_lt_u32 s16, 14
	s_cbranch_scc0 .Lgz0_v0
	s_waitcnt vmcnt(4)
	s_branch .Lgz0_vj
.Lgz0_v0:
	s_waitcnt vmcnt(0)
.Lgz0_vj:
	s_waitcnt lgkmcnt(0)
	s_add_u32 s6, s6, 0xfffe0080
	s_addc_u32 s7, s7, -1
	s_add_u32 s8, s8, 0x80
	s_addc_u32 s9, s9, 0
	s_mov_b32 s10, s11
	s_add_u32 s16, s16, 1
	s_cmp_lt_u32 s16, 16
	s_barrier
	s_cbranch_scc1 .Lgz0_loop
	v_mov_b32_e32 v204, 0x3ab69700
	v_mov_b32_e32 v205, 0xffffea00
	v_mov_b32_e32 v206, 0x41b17218
	v_mov_b32_e32 v207, 0xd000
	v_mov_b32_e32 v208, 0xf00
	v_mov_b32_e32 v209, 0x7f800000
	v_mov_b32_e32 v210, 0xffffffc0
	v_mov_b32_e32 v211, 0xffffffe0
	v_mov_b32_e32 v212, 0x7fc00000
	v_mov_b32_e32 v213, 0xac00
	v_mov_b32_e32 v214, 0x800
	v_mov_b32_e32 v215, 0x140
	v_mov_b32_e32 v216, 0x130
	s_nop 7
	s_branch .LBB0_193

; __device__ __forceinline__ int ltid() { int t = threadIdx.x; asm volatile("" : "+v"(t)); return t; }
; #define WAIT_V(n) asm volatile("s_waitcnt vmcnt(%0)" ::"n"(n) : "memory")
; #define RAW_BARRIER() do { asm volatile("s_waitcnt lgkmcnt(0)" ::: "memory"); __builtin_amdgcn_s_barrier(); } while (0)
; __device__ __forceinline__ void gb_issue(const u16* ga, const u16* gw, size_t a64, size_t w64, int ko, u16* __restrict__ wr, int wave) {
; #pragma unroll
;   for (int i = 0; i < 4; i++)
;     __builtin_amdgcn_global_load_lds((const unsigned*)(ga + i * a64 + ko), (lds_u32*)(wr + (i * 4 + wave) * 512), 16, 0, 0);
; #pragma unroll
;   for (int i = 0; i < 2; i++)
;     __builtin_amdgcn_global_load_lds((const unsigned*)(gw + i * w64 + ko), (lds_u32*)(wr + 256 * GST + (i * 4 + wave) * 512), 16, 0, 0);
; }
; template <class F>
; __device__ __forceinline__ void gemm_big(const ALbf& al, const u16* __restrict__ Wt, int K, int m0, int n0, const F& f, u16* sm) {
;   const int tid = ltid(), lane = tid & 63, wave = tid >> 6;
;   const int wm = wave >> 1, wn = wave & 1;
;   const int rsw = GSW(lane & 15, lane >> 4);
;   f32x4 acc[4][8];
; #pragma unroll
;   for (int i = 0; i < 4; i++)
; #pragma unroll
;     for (int j = 0; j < 8; j++) acc[i][j] = (f32x4){0.f, 0.f, 0.f, 0.f};
;   const int srow = lane >> 2;
;   const int scol = ((lane & 3) ^ ((0 - (srow >> 2)) & 3)) * 8;
;   const u16* ga = al.A + (size_t)(m0 + wave * 16 + srow) * al.lda + scol;
;   const u16* gw = Wt + (size_t)(n0 + wave * 16 + srow) * K + scol;
;   const size_t a64 = (size_t)64 * al.lda, w64 = (size_t)64 * K;
;   const int nk = K >> 5;
;   WAIT_V(0);
;   gb_issue(ga, gw, a64, w64, 0, sm, wave);
;   gb_issue(ga, gw, a64, w64, 32, sm + GB_STAGE_EL, wave);
;   WAIT_V(6);
;   RAW_BARRIER();
.LBB0_218:
	v_mov_b32_e32 v138, v132
	s_lshl_b32 s12, s17, 8
	v_lshrrev_b32_e32 v0, 2, v138
	v_bfe_u32 v140, v138, 4, 2
	v_sub_u32_e32 v0, 0, v0
	v_bitop3_b32 v0, v140, v0, 3 bitop3:0x78
	v_lshlrev_b32_e32 v6, 4, v0
	v_lshrrev_b32_e32 v0, 4, v138
	v_ashrrev_i32_e32 v4, 6, v138
	v_sub_u32_e32 v8, 0, v0
	s_and_b32 s61, s12, 0x3f00
	s_lshl_b32 s12, s17, 1
	v_bfe_u32 v7, v138, 2, 4
	v_xor_b32_e32 v2, v138, v8
	v_lshlrev_b32_e32 v9, 4, v4
	s_load_dwordx16 s[64:79], s[0:1], 0x160
	s_and_b32 s60, s12, 0xffffff80
	v_or_b32_e32 v3, v7, v9
	v_lshlrev_b32_e32 v2, 4, v2
	v_add_u32_e32 v0, s61, v3
	v_and_b32_e32 v134, 48, v2
	v_add_u32_e32 v2, s60, v3
	v_ashrrev_i32_e32 v1, 31, v0
	v_ashrrev_i32_e32 v3, 31, v2
	v_lshlrev_b64 v[0:1], 11, v[0:1]
	v_lshlrev_b64 v[2:3], 11, v[2:3]
	s_waitcnt lgkmcnt(0)
	v_lshl_add_u64 v[0:1], s[30:31], 0, v[0:1]
	v_lshl_add_u64 v[2:3], s[74:75], 0, v[2:3]
	v_lshl_add_u64 v[0:1], v[0:1], 0, v[134:135]
	v_lshl_add_u64 v[2:3], v[2:3], 0, v[134:135]
	v_lshlrev_b32_e32 v134, 10, v4
	v_add_u32_e32 v10, 0x1000, v134
	v_readfirstlane_b32 s12, v134
	s_waitcnt vmcnt(0)
	s_mov_b32 m0, s12
	v_readfirstlane_b32 s12, v10
	v_add_u32_e32 v10, 0x2000, v134
	v_lshl_add_u64 v[4:5], v[0:1], 0, s[96:97]
	s_mov_b32 m0, s12
	v_readfirstlane_b32 s12, v10
	v_lshl_add_u64 v[4:5], v[0:1], 0, s[86:87]
	s_mov_b32 m0, s12
	s_mov_b64 s[12:13], 0x60000
	v_add_u32_e32 v10, 0x3000, v134
	v_lshl_add_u64 v[4:5], v[0:1], 0, s[12:13]
	v_readfirstlane_b32 s12, v10
	s_mov_b32 m0, s12
	v_add_u32_e32 v10, 0x5000, v134
	v_add_u32_e32 v4, 0x4000, v134
	s_mov_b64 s[14:15], 0x20040
	v_readfirstlane_b32 s12, v4
	s_mov_b32 m0, s12
	v_readfirstlane_b32 s12, v10
	v_add_u32_e32 v10, 0x6000, v134
	v_lshl_add_u64 v[4:5], v[2:3], 0, s[96:97]
	s_mov_b32 m0, s12
	v_readfirstlane_b32 s12, v10
	v_add_u32_e32 v10, 0x7000, v134
	v_lshl_add_u64 v[4:5], v[0:1], 0, 64
	s_mov_b32 m0, s12
	v_readfirstlane_b32 s12, v10
	v_lshl_add_u64 v[4:5], v[0:1], 0, s[14:15]
	s_mov_b32 m0, s12
	s_mov_b64 s[12:13], 0x40040
	v_add_u32_e32 v10, 0x8000, v134
	v_lshl_add_u64 v[4:5], v[0:1], 0, s[12:13]
	v_readfirstlane_b32 s12, v10
	s_mov_b32 m0, s12
	s_mov_b64 s[12:13], 0x60040
	v_add_u32_e32 v4, 0x9000, v134
	v_lshl_add_u64 v[0:1], v[0:1], 0, s[12:13]
	v_readfirstlane_b32 s12, v4
	v_add_u32_e32 v4, 0xa000, v134
	s_mov_b32 m0, s12
	v_readfirstlane_b32 s12, v4
	v_lshl_add_u64 v[0:1], v[2:3], 0, 64
	s_mov_b32 m0, s12
	s_and_b32 s10, s4, 0xffffff80
	v_lshl_add_u64 v[0:1], v[2:3], 0, s[14:15]
	v_add_u32_e32 v2, 0xb000, v134
	s_and_b32 s11, s16, 0x3f00
	v_readfirstlane_b32 s12, v2
	s_mov_b32 m0, s12
	v_bitop3_b32 v2, v138, 3, v8 bitop3:0x48
	v_lshlrev_b32_e32 v0, 6, v138
	v_and_or_b32 v143, v0, s80, v6
	v_lshlrev_b32_e32 v0, 1, v138
	v_and_b32_e32 v1, 0x43, v138
	v_and_or_b32 v0, v0, 24, v1
	v_lshrrev_b32_e32 v1, 1, v138
	v_and_b32_e32 v1, 2, v1
	v_sub_u32_e32 v1, 0, v1
	v_bitop3_b32 v1, v1, v140, 2 bitop3:0x6c
	v_lshlrev_b32_e32 v1, 4, v1
	v_lshl_or_b32 v144, v0, 6, v1
	v_or_b32_e32 v0, 4, v0
	v_lshlrev_b32_e32 v1, 6, v0
	v_lshrrev_b32_e32 v0, 2, v0
	v_sub_u32_e32 v0, 0, v0
	v_bitop3_b32 v0, v0, v140, 3 bitop3:0x6c
	v_lshl_or_b32 v145, v0, 4, v1
	v_or_b32_e32 v0, s10, v7
	v_add_u32_e32 v0, v0, v9
	v_ashrrev_i32_e32 v1, 31, v0
	v_lshlrev_b64 v[0:1], 11, v[0:1]
	v_lshlrev_b32_e32 v2, 4, v2
	v_or_b32_e32 v0, v0, v2
	v_lshl_add_u64 v[128:129], s[74:75], 0, v[0:1]
	v_or_b32_e32 v0, s11, v7
	v_add_u32_e32 v0, v0, v9
	v_ashrrev_i32_e32 v1, 31, v0
	s_waitcnt vmcnt(6)
	v_lshlrev_b64 v[0:1], 11, v[0:1]
	s_waitcnt lgkmcnt(0)
	v_or_b32_e32 v0, v0, v2
	v_lshl_add_u64 v[130:131], s[30:31], 0, v[0:1]
	v_mov_b32_e32 v0, 0
	s_mov_b32 s94, 0
	s_mov_b64 s[10:11], 0
	s_mov_b32 s95, 0
	v_mov_b32_e32 v1, v0
	v_mov_b32_e32 v2, v0
	v_mov_b32_e32 v3, v0
	v_mov_b32_e32 v4, v0
	v_mov_b32_e32 v5, v0
	v_mov_b32_e32 v6, v0
	v_mov_b32_e32 v7, v0
	v_mov_b32_e32 v48, v0
	v_mov_b32_e32 v49, v0
	v_mov_b32_e32 v50, v0
	v_mov_b32_e32 v51, v0
	v_mov_b32_e32 v52, v0
	v_mov_b32_e32 v53, v0
	v_mov_b32_e32 v54, v0
	v_mov_b32_e32 v55, v0
	v_mov_b32_e32 v8, v0
	v_mov_b32_e32 v9, v0
	v_mov_b32_e32 v10, v0
	v_mov_b32_e32 v11, v0
	v_mov_b32_e32 v12, v0
	v_mov_b32_e32 v13, v0
	v_mov_b32_e32 v14, v0
	v_mov_b32_e32 v15, v0
	v_mov_b32_e32 v64, v0
	v_mov_b32_e32 v65, v0
	v_mov_b32_e32 v66, v0
	v_mov_b32_e32 v67, v0
	v_mov_b32_e32 v72, v0
	v_mov_b32_e32 v73, v0
	v_mov_b32_e32 v74, v0
	v_mov_b32_e32 v75, v0
	v_mov_b32_e32 v16, v0
	v_mov_b32_e32 v17, v0
	v_mov_b32_e32 v18, v0
	v_mov_b32_e32 v19, v0
	v_mov_b32_e32 v20, v0
	v_mov_b32_e32 v21, v0
	v_mov_b32_e32 v22, v0
	v_mov_b32_e32 v23, v0
	v_mov_b32_e32 v80, v0
	v_mov_b32_e32 v81, v0
	v_mov_b32_e32 v82, v0
	v_mov_b32_e32 v83, v0
	v_mov_b32_e32 v84, v0
	v_mov_b32_e32 v85, v0
	v_mov_b32_e32 v86, v0
	v_mov_b32_e32 v87, v0
	v_mov_b32_e32 v24, v0
	v_mov_b32_e32 v25, v0
	v_mov_b32_e32 v26, v0
	v_mov_b32_e32 v27, v0
	v_mov_b32_e32 v28, v0
	v_mov_b32_e32 v29, v0
	v_mov_b32_e32 v30, v0
	v_mov_b32_e32 v31, v0
	v_mov_b32_e32 v88, v0
	v_mov_b32_e32 v89, v0
	v_mov_b32_e32 v90, v0
	v_mov_b32_e32 v91, v0
	v_mov_b32_e32 v92, v0
	v_mov_b32_e32 v93, v0
	v_mov_b32_e32 v94, v0
	v_mov_b32_e32 v95, v0
	v_mov_b32_e32 v32, v0
	v_mov_b32_e32 v33, v0
	v_mov_b32_e32 v34, v0
	v_mov_b32_e32 v35, v0
	v_mov_b32_e32 v36, v0
	v_mov_b32_e32 v37, v0
	v_mov_b32_e32 v38, v0
	v_mov_b32_e32 v39, v0
	v_mov_b32_e32 v96, v0
	v_mov_b32_e32 v97, v0
	v_mov_b32_e32 v98, v0
	v_mov_b32_e32 v99, v0
	v_mov_b32_e32 v100, v0
	v_mov_b32_e32 v101, v0
	v_mov_b32_e32 v102, v0
	v_mov_b32_e32 v103, v0
	v_mov_b32_e32 v40, v0
	v_mov_b32_e32 v41, v0
	v_mov_b32_e32 v42, v0
	v_mov_b32_e32 v43, v0
	v_mov_b32_e32 v44, v0
	v_mov_b32_e32 v45, v0
	v_mov_b32_e32 v46, v0
; __device__ __forceinline__ void gb_step(const u16* ga, const u16* gw, size_t a64, size_t w64, int ko, bool issue, ...
;   if (issue) {
; #pragma unroll
;     for (int i = 0; i < 4; i++)
;       __builtin_amdgcn_global_load_lds((const unsigned*)(ga + i * a64 + ko), (lds_u32*)(wr + (i * 4 + wave) * 512), 16, 0, 0);
; #pragma unroll
;     for (int i = 0; i < 2; i++)
;       __builtin_amdgcn_global_load_lds((const unsigned*)(gw + i * w64 + ko), (lds_u32*)(wr + 256 * GST + (i * 4 + wave) * 512), 16, 0, 0);
;   }
;   const unsigned rdb = (unsigned)(size_t)(__attribute__((address_space(3))) const char*)rd;
;   const unsigned ab = rdb + (unsigned)(((wm * 128 + (lane & 15)) * GST + rsw) * 2);
;   const int wr0 = wn * 64 + (((lane & 15) >> 2) << 3) + (lane & 3);
;   const unsigned bb0 = rdb + (unsigned)((256 * GST + wr0 * GST + GSW(wr0, lane >> 4)) * 2);
;   const unsigned bb1 = rdb + (unsigned)((256 * GST + (wr0 + 4) * GST + GSW(wr0 + 4, lane >> 4)) * 2);
;   bf16x8 wf0, wf1, wf2, wf3, xf0, xf1, xf2, xf3, xf4, xf5, xf6, xf7;
;     ...
;   DSR(wf0, bb0, 0); DSR(wf1, bb1, 0); DSR(wf2, bb0, 2048); DSR(wf3, bb1, 2048);
;   DSR(xf0, ab, 0); DSR(xf1, ab, 1024); DSR(xf2, ab, 2048); DSR(xf3, ab, 3072);
;   DSR(xf4, ab, 4096); DSR(xf5, ab, 5120); DSR(xf6, ab, 6144); DSR(xf7, ab, 7168);
;     ...
;   asm volatile("s_waitcnt lgkmcnt(7)" : "+v"(wf0), "+v"(wf1), "+v"(wf2), "+v"(wf3), "+v"(xf0) : : "memory");
;   MM(0, xf0)
;   asm volatile("s_waitcnt lgkmcnt(6)" : "+v"(xf1) : : "memory");
;   MM(1, xf1)
;   asm volatile("s_waitcnt lgkmcnt(5)" : "+v"(xf2) : : "memory");
;   MM(2, xf2)
; template <class F>
; __device__ __forceinline__ void gemm_big(const ALbf& al, const u16* __restrict__ Wt, int K, int m0, int n0, const F& f, u16* sm) {
;     ...
; #pragma unroll
;   for (int i = 0; i < 4; i++)
; #pragma unroll
;     for (int j = 0; j < 8; j++) acc[i][j] = (f32x4){0.f, 0.f, 0.f, 0.f};
;   const int srow = lane >> 2;
;   const int scol = ((lane & 3) ^ ((0 - (srow >> 2)) & 3)) * 8;
;   const u16* ga = al.A + (size_t)(m0 + wave * 16 + srow) * al.lda + scol;
;   const u16* gw = Wt + (size_t)(n0 + wave * 16 + srow) * K + scol;
;   const size_t a64 = (size_t)64 * al.lda, w64 = (size_t)64 * K;
;   const int nk = K >> 5;
;   WAIT_V(0);
;   gb_issue(ga, gw, a64, w64, 0, sm, wave);
;   gb_issue(ga, gw, a64, w64, 32, sm + GB_STAGE_EL, wave);
;   WAIT_V(6);
;   RAW_BARRIER();
	v_mov_b32_e32 v47, v0
	v_mov_b32_e32 v104, v0
	v_mov_b32_e32 v105, v0
	v_mov_b32_e32 v106, v0
	v_mov_b32_e32 v107, v0
	v_mov_b32_e32 v108, v0
	v_mov_b32_e32 v109, v0
	v_mov_b32_e32 v110, v0
	v_mov_b32_e32 v111, v0
	v_mov_b32_e32 v56, v0
	v_mov_b32_e32 v57, v0
	v_mov_b32_e32 v58, v0
	v_mov_b32_e32 v59, v0
	v_mov_b32_e32 v60, v0
	v_mov_b32_e32 v61, v0
	v_mov_b32_e32 v62, v0
	v_mov_b32_e32 v63, v0
	v_mov_b32_e32 v112, v0
	v_mov_b32_e32 v113, v0
	v_mov_b32_e32 v114, v0
	v_mov_b32_e32 v115, v0
	v_mov_b32_e32 v116, v0
	v_mov_b32_e32 v117, v0
	v_mov_b32_e32 v118, v0
	v_mov_b32_e32 v119, v0
	v_mov_b32_e32 v68, v0
	v_mov_b32_e32 v69, v0
	v_mov_b32_e32 v70, v0
	v_mov_b32_e32 v71, v0
	v_mov_b32_e32 v76, v0
	v_mov_b32_e32 v77, v0
	v_mov_b32_e32 v78, v0
	v_mov_b32_e32 v79, v0
	v_mov_b32_e32 v120, v0
	v_mov_b32_e32 v121, v0
	v_mov_b32_e32 v122, v0
	v_mov_b32_e32 v123, v0
	v_mov_b32_e32 v124, v0
	v_mov_b32_e32 v125, v0
	v_mov_b32_e32 v126, v0
	v_mov_b32_e32 v127, v0
	v_readfirstlane_b32 s10, v130
	v_readfirstlane_b32 s11, v131
	v_readfirstlane_b32 s12, v128
	v_readfirstlane_b32 s13, v129
	v_readfirstlane_b32 s95, v134
	v_and_b32_e32 v176, 63, v132
	v_lshrrev_b32_e32 v177, 6, v132
	v_lshrrev_b32_e32 v178, 3, v176
	v_and_b32_e32 v179, 7, v176
	v_lshrrev_b32_e32 v180, 4, v176
	v_and_b32_e32 v181, 1, v177
	v_lshrrev_b32_e32 v182, 1, v177
	v_lshl_add_u32 v183, v181, 2, v180
	v_xor_b32_e32 v183, v179, v183
	v_lshl_add_u32 v184, v177, 3, v178
	v_lshlrev_b32_e32 v188, 11, v184
	v_lshl_add_u32 v128, v183, 4, v188
	v_add_u32_e32 v129, 0x10000, v128
	v_add_u32_e32 v130, 0x40000, v128
	v_add_u32_e32 v131, 0x50000, v128
	v_bfe_u32 v185, v178, 1, 1
	v_lshl_or_b32 v185, v181, 1, v185
	v_lshl_or_b32 v185, v182, 2, v185
	v_xor_b32_e32 v185, v179, v185
	v_lshl_add_u32 v134, v185, 4, v188
	v_add_u32_e32 v143, 0x10000, v134
	v_add_u32_e32 v196, 0x20000, v134
	v_add_u32_e32 v197, 0x30000, v134
	v_and_b32_e32 v186, 15, v176
	v_bfe_u32 v187, v176, 1, 3
	v_xor_b32_e32 v187, v180, v187
	v_lshlrev_b32_e32 v187, 4, v187
	v_lshl_add_u32 v188, v182, 6, v186
	v_lshl_add_u32 v219, v188, 7, v187
	v_xor_b32_e32 v228, 64, v219
	v_lshrrev_b32_e32 v189, 2, v186
	v_lshlrev_b32_e32 v189, 3, v189
	v_and_b32_e32 v188, 3, v186
	v_add_u32_e32 v189, v189, v188
	v_lshl_add_u32 v189, v181, 6, v189
	v_lshl_add_u32 v231, v189, 7, v187
	v_xor_b32_e32 v216, 64, v231
	s_lshl_b32 s15, s95, 5
	s_sub_u32 s10, s10, s15
	s_subb_u32 s11, s11, 0
	s_sub_u32 s12, s12, s15
	s_subb_u32 s13, s13, 0
	s_add_u32 m0, s95, 0x8000
	s_nop 0
	global_load_lds_dwordx4 v128, s[10:11]
	s_add_u32 m0, s95, 0x9000
	s_nop 0
	global_load_lds_dwordx4 v129, s[10:11]
	s_add_u32 m0, s95, 0xa000
	s_nop 0
	global_load_lds_dwordx4 v130, s[10:11]
	s_add_u32 m0, s95, 0xb000
	s_nop 0
	global_load_lds_dwordx4 v131, s[10:11]
	s_add_u32 s10, s10, 0x20000
	s_addc_u32 s11, s11, 0
	s_add_u32 m0, s95, 0xc000
	s_nop 0
	global_load_lds_dwordx4 v128, s[10:11]
	s_add_u32 m0, s95, 0xd000
	s_nop 0
	global_load_lds_dwordx4 v129, s[10:11]
	s_add_u32 m0, s95, 0xe000
	s_nop 0
	global_load_lds_dwordx4 v130, s[10:11]
	s_add_u32 m0, s95, 0xf000
	s_nop 0
	global_load_lds_dwordx4 v131, s[10:11]
	s_add_u32 s10, s10, 0xfffe0080
	s_addc_u32 s11, s11, -1
	s_add_u32 m0, s95, 0x0
	s_nop 0
	global_load_lds_dwordx4 v134, s[12:13]
	s_add_u32 m0, s95, 0x1000
	s_nop 0
	global_load_lds_dwordx4 v143, s[12:13]
	s_add_u32 m0, s95, 0x2000
	s_nop 0
	global_load_lds_dwordx4 v196, s[12:13]
	s_add_u32 m0, s95, 0x3000
	s_nop 0
	global_load_lds_dwordx4 v197, s[12:13]
	s_add_u32 s12, s12, 0x80
	s_addc_u32 s13, s13, 0
	s_add_u32 m0, s95, 0x4000
	s_nop 0
	global_load_lds_dwordx4 v134, s[12:13]
	s_add_u32 m0, s95, 0x5000
	s_nop 0
	global_load_lds_dwordx4 v143, s[12:13]
	s_add_u32 m0, s95, 0x6000
	s_nop 0
	global_load_lds_dwordx4 v196, s[12:13]
	s_add_u32 m0, s95, 0x7000
	s_nop 0
	global_load_lds_dwordx4 v197, s[12:13]
	s_add_u32 s12, s12, 0x80
	s_addc_u32 s13, s13, 0
	s_waitcnt vmcnt(0)
	s_barrier
	s_mov_b32 s14, 0
	s_mov_b32 s94, 0
	ds_read_b128 v[144:147], v219 offset:32768
	ds_read_b128 v[148:151], v219 offset:34816
	ds_read_b128 v[152:155], v219 offset:36864
	ds_read_b128 v[156:159], v219 offset:38912
	ds_read_b128 v[160:163], v228 offset:32768
	ds_read_b128 v[164:167], v228 offset:34816
	ds_read_b128 v[168:171], v228 offset:36864
	ds_read_b128 v[172:175], v228 offset:38912
	v_add_u32_e32 v248, s14, v231
	ds_read_b128 v[236:239], v248 offset:0
	ds_read_b128 v[240:243], v248 offset:512
	ds_read_b128 v[244:247], v248 offset:4096
	ds_read_b128 v[248:251], v248 offset:4608
	s_waitcnt lgkmcnt(0)
	s_barrier
.Lgz1_loop:
	s_cmp_lt_u32 s94, 15
	s_cselect_b64 vcc, -1, 0
	v_add_u32_e32 v212, s14, v216
	ds_read_b128 v[252:255], v212 offset:0
	ds_read_b128 v[204:207], v212 offset:512
	ds_read_b128 v[208:211], v212 offset:4096
	ds_read_b128 v[212:215], v212 offset:4608
	v_mfma_f32_16x16x32_bf16 v[124:127], v[236:239], v[144:147], v[124:127]
	ds_read_b128 v[176:179], v219 offset:49152
	v_mfma_f32_16x16x32_bf16 v[120:123], v[240:243], v[144:147], v[120:123]
	ds_read_b128 v[180:183], v219 offset:51200
	v_mfma_f32_16x16x32_bf16 v[76:79], v[244:247], v[144:147], v[76:79]
	ds_read_b128 v[184:187], v219 offset:53248
	v_mfma_f32_16x16x32_bf16 v[68:71], v[248:251], v[144:147], v[68:71]
	ds_read_b128 v[188:191], v219 offset:55296
	v_mfma_f32_16x16x32_bf16 v[116:119], v[236:239], v[148:151], v[116:119]
	ds_read_b128 v[192:195], v228 offset:49152
	v_mfma_f32_16x16x32_bf16 v[112:115], v[240:243], v[148:151], v[112:115]
	ds_read_b128 v[220:223], v228 offset:51200
	v_mfma_f32_16x16x32_bf16 v[60:63], v[244:247], v[148:151], v[60:63]
	ds_read_b128 v[224:227], v228 offset:53248
	v_mfma_f32_16x16x32_bf16 v[56:59], v[248:251], v[148:151], v[56:59]
	ds_read_b128 v[232:235], v228 offset:55296
	s_add_u32 m0, s95, 0x8000
	v_mfma_f32_16x16x32_bf16 v[108:111], v[236:239], v[152:155], v[108:111]
	s_cbranch_vccz .Lgz1_a0
	global_load_lds_dwordx4 v128, s[10:11]
; #define DSR(dst, addr, off) asm volatile("ds_read_b128 %0, %1 offset:%2" : "=v"(dst) : "v"(addr), "n"(off) : "memory")
; #define MM(j, xf)                                                                     \
;   acc[0][j] = MFMA16(wf0, xf, acc[0][j]); acc[1][j] = MFMA16(wf1, xf, acc[1][j]);      \
;   acc[2][j] = MFMA16(wf2, xf, acc[2][j]); acc[3][j] = MFMA16(wf3, xf, acc[3][j]);
; __device__ __forceinline__ void gb_step(const u16* ga, const u16* gw, size_t a64, size_t w64, int ko, bool issue, ...
;   if (issue) {
; #pragma unroll
;     for (int i = 0; i < 4; i++)
;       __builtin_amdgcn_global_load_lds((const unsigned*)(ga + i * a64 + ko), (lds_u32*)(wr + (i * 4 + wave) * 512), 16, 0, 0);
; #pragma unroll
;     for (int i = 0; i < 2; i++)
;       __builtin_amdgcn_global_load_lds((const unsigned*)(gw + i * w64 + ko), (lds_u32*)(wr + 256 * GST + (i * 4 + wave) * 512), 16, 0, 0);
;   }
;   const unsigned rdb = (unsigned)(size_t)(__attribute__((address_space(3))) const char*)rd;
;   const unsigned ab = rdb + (unsigned)(((wm * 128 + (lane & 15)) * GST + rsw) * 2);
;   const int wr0 = wn * 64 + (((lane & 15) >> 2) << 3) + (lane & 3);
;   const unsigned bb0 = rdb + (unsigned)((256 * GST + wr0 * GST + GSW(wr0, lane >> 4)) * 2);
;   const unsigned bb1 = rdb + (unsigned)((256 * GST + (wr0 + 4) * GST + GSW(wr0 + 4, lane >> 4)) * 2);
;   bf16x8 wf0, wf1, wf2, wf3, xf0, xf1, xf2, xf3, xf4, xf5, xf6, xf7;
;     ...
;   DSR(wf0, bb0, 0); DSR(wf1, bb1, 0); DSR(wf2, bb0, 2048); DSR(wf3, bb1, 2048);
;   DSR(xf0, ab, 0); DSR(xf1, ab, 1024); DSR(xf2, ab, 2048); DSR(xf3, ab, 3072);
;   DSR(xf4, ab, 4096); DSR(xf5, ab, 5120); DSR(xf6, ab, 6144); DSR(xf7, ab, 7168);
;     ...
;   asm volatile("s_waitcnt lgkmcnt(7)" : "+v"(wf0), "+v"(wf1), "+v"(wf2), "+v"(wf3), "+v"(xf0) : : "memory");
;   MM(0, xf0)
;   asm volatile("s_waitcnt lgkmcnt(6)" : "+v"(xf1) : : "memory");
;   MM(1, xf1)
;   asm volatile("s_waitcnt lgkmcnt(5)" : "+v"(xf2) : : "memory");
;   MM(2, xf2)
;   asm volatile("s_waitcnt lgkmcnt(4)" : "+v"(xf3) : : "memory");
;   MM(3, xf3)
;   asm volatile("s_waitcnt lgkmcnt(3)" : "+v"(xf4) : : "memory");
;   MM(4, xf4)
;   asm volatile("s_waitcnt lgkmcnt(2)" : "+v"(xf5) : : "memory");
;   MM(5, xf5)
;   asm volatile("s_waitcnt lgkmcnt(1)" : "+v"(xf6) : : "memory");
;   MM(6, xf6)
;   asm volatile("s_waitcnt lgkmcnt(0)" : "+v"(xf7) : : "memory");
;   MM(7, xf7)
.Lgz1_a0:
	v_mfma_f32_16x16x32_bf16 v[104:107], v[240:243], v[152:155], v[104:107]
	s_add_u32 m0, s95, 0x9000
	v_mfma_f32_16x16x32_bf16 v[44:47], v[244:247], v[152:155], v[44:47]
	s_cbranch_vccz .Lgz1_a1
	global_load_lds_dwordx4 v129, s[10:11]
.Lgz1_a1:
	v_mfma_f32_16x16x32_bf16 v[40:43], v[248:251], v[152:155], v[40:43]
	s_add_u32 m0, s95, 0xa000
	v_mfma_f32_16x16x32_bf16 v[100:103], v[236:239], v[156:159], v[100:103]
	s_cbranch_vccz .Lgz1_a2
	global_load_lds_dwordx4 v130, s[10:11]
.Lgz1_a2:
	v_mfma_f32_16x16x32_bf16 v[96:99], v[240:243], v[156:159], v[96:99]
	s_add_u32 m0, s95, 0xb000
	v_mfma_f32_16x16x32_bf16 v[36:39], v[244:247], v[156:159], v[36:39]
	s_cbranch_vccz .Lgz1_a3
	global_load_lds_dwordx4 v131, s[10:11]
.Lgz1_a3:
	v_mfma_f32_16x16x32_bf16 v[32:35], v[248:251], v[156:159], v[32:35]
	s_waitcnt lgkmcnt(8)
	v_mfma_f32_16x16x32_bf16 v[124:127], v[252:255], v[160:163], v[124:127]
	v_mfma_f32_16x16x32_bf16 v[120:123], v[204:207], v[160:163], v[120:123]
	v_mfma_f32_16x16x32_bf16 v[76:79], v[208:211], v[160:163], v[76:79]
	v_mfma_f32_16x16x32_bf16 v[68:71], v[212:215], v[160:163], v[68:71]
	v_mfma_f32_16x16x32_bf16 v[116:119], v[252:255], v[164:167], v[116:119]
	v_mfma_f32_16x16x32_bf16 v[112:115], v[204:207], v[164:167], v[112:115]
	v_mfma_f32_16x16x32_bf16 v[60:63], v[208:211], v[164:167], v[60:63]
	v_mfma_f32_16x16x32_bf16 v[56:59], v[212:215], v[164:167], v[56:59]
	v_mfma_f32_16x16x32_bf16 v[108:111], v[252:255], v[168:171], v[108:111]
	v_mfma_f32_16x16x32_bf16 v[104:107], v[204:207], v[168:171], v[104:107]
	v_mfma_f32_16x16x32_bf16 v[44:47], v[208:211], v[168:171], v[44:47]
	v_mfma_f32_16x16x32_bf16 v[40:43], v[212:215], v[168:171], v[40:43]
	v_mfma_f32_16x16x32_bf16 v[100:103], v[252:255], v[172:175], v[100:103]
	v_mfma_f32_16x16x32_bf16 v[96:99], v[204:207], v[172:175], v[96:99]
	v_mfma_f32_16x16x32_bf16 v[36:39], v[208:211], v[172:175], v[36:39]
	v_mfma_f32_16x16x32_bf16 v[32:35], v[212:215], v[172:175], v[32:35]
	s_waitcnt vmcnt(0)
	s_waitcnt lgkmcnt(0)
	s_add_u32 s10, s10, 0x20000
	s_addc_u32 s11, s11, 0
	s_xor_b32 s15, s14, 0x4000
	s_barrier
	v_mfma_f32_16x16x32_bf16 v[92:95], v[236:239], v[176:179], v[92:95]
	ds_read_b128 v[144:147], v219 offset:32768
	v_mfma_f32_16x16x32_bf16 v[88:91], v[240:243], v[176:179], v[88:91]
	ds_read_b128 v[148:151], v219 offset:34816
	v_mfma_f32_16x16x32_bf16 v[28:31], v[244:247], v[176:179], v[28:31]
	ds_read_b128 v[152:155], v219 offset:36864
	v_mfma_f32_16x16x32_bf16 v[24:27], v[248:251], v[176:179], v[24:27]
	ds_read_b128 v[156:159], v219 offset:38912
	v_mfma_f32_16x16x32_bf16 v[84:87], v[236:239], v[180:183], v[84:87]
	ds_read_b128 v[160:163], v228 offset:32768
	v_mfma_f32_16x16x32_bf16 v[80:83], v[240:243], v[180:183], v[80:83]
	ds_read_b128 v[164:167], v228 offset:34816
	v_mfma_f32_16x16x32_bf16 v[20:23], v[244:247], v[180:183], v[20:23]
	ds_read_b128 v[168:171], v228 offset:36864
	v_mfma_f32_16x16x32_bf16 v[16:19], v[248:251], v[180:183], v[16:19]
	ds_read_b128 v[172:175], v228 offset:38912
	s_add_u32 m0, s95, 0xc000
	v_mfma_f32_16x16x32_bf16 v[72:75], v[236:239], v[184:187], v[72:75]
	s_cbranch_vccz .Lgz1_b0
	global_load_lds_dwordx4 v128, s[10:11]
.Lgz1_b0:
	v_mfma_f32_16x16x32_bf16 v[64:67], v[240:243], v[184:187], v[64:67]
	s_add_u32 m0, s95, 0xd000
	v_mfma_f32_16x16x32_bf16 v[12:15], v[244:247], v[184:187], v[12:15]
	s_cbranch_vccz .Lgz1_b1
	global_load_lds_dwordx4 v129, s[10:11]
.Lgz1_b1:
	v_mfma_f32_16x16x32_bf16 v[8:11], v[248:251], v[184:187], v[8:11]
	s_add_u32 m0, s95, 0xe000
	v_mfma_f32_16x16x32_bf16 v[52:55], v[236:239], v[188:191], v[52:55]
	s_cbranch_vccz .Lgz1_b2
	global_load_lds_dwordx4 v130, s[10:11]
.Lgz1_b2:
	v_mfma_f32_16x16x32_bf16 v[48:51], v[240:243], v[188:191], v[48:51]
	s_add_u32 m0, s95, 0xf000
	v_mfma_f32_16x16x32_bf16 v[4:7], v[244:247], v[188:191], v[4:7]
	s_cbranch_vccz .Lgz1_b3
	global_load_lds_dwordx4 v131, s[10:11]
.Lgz1_b3:
	v_mfma_f32_16x16x32_bf16 v[0:3], v[248:251], v[188:191], v[0:3]
	v_add_u32_e32 v248, s15, v231
	v_mfma_f32_16x16x32_bf16 v[92:95], v[252:255], v[192:195], v[92:95]
	ds_read_b128 v[236:239], v248 offset:0
	v_mfma_f32_16x16x32_bf16 v[88:91], v[204:207], v[192:195], v[88:91]
	ds_read_b128 v[240:243], v248 offset:512
	v_mfma_f32_16x16x32_bf16 v[28:31], v[208:211], v[192:195], v[28:31]
	ds_read_b128 v[244:247], v248 offset:4096
	v_mfma_f32_16x16x32_bf16 v[24:27], v[212:215], v[192:195], v[24:27]
	ds_read_b128 v[248:251], v248 offset:4608
	v_mfma_f32_16x16x32_bf16 v[84:87], v[252:255], v[220:223], v[84:87]
	v_mfma_f32_16x16x32_bf16 v[80:83], v[204:207], v[220:223], v[80:83]
	s_cmp_lt_u32 s94, 14
	s_cbranch_scc0 .Lgz1_w0
	s_add_u32 m0, s95, s14
	s_add_u32 m0, m0, 0x0
	s_nop 0
	global_load_lds_dwordx4 v134, s[12:13]
.Lgz1_w0:
	v_mfma_f32_16x16x32_bf16 v[20:23], v[208:211], v[220:223], v[20:23]
	v_mfma_f32_16x16x32_bf16 v[16:19], v[212:215], v[220:223], v[16:19]
	s_cmp_lt_u32 s94, 14
	s_cbranch_scc0 .Lgz1_w1
	s_add_u32 m0, s95, s14
	s_add_u32 m0, m0, 0x1000
	s_nop 0
	global_load_lds_dwordx4 v143, s[12:13]
.Lgz1_w1:
	v_mfma_f32_16x16x32_bf16 v[72:75], v[252:255], v[224:227], v[72:75]
	v_mfma_f32_16x16x32_bf16 v[64:67], v[204:207], v[224:227], v[64:67]
	s_cmp_lt_u32 s94, 14
	s_cbranch_scc0 .Lgz1_w2
	s_add_u32 m0, s95, s14
	s_add_u32 m0, m0, 0x2000
	s_nop 0
	global_load_lds_dwordx4 v196, s[12:13]
.Lgz1_w2:
	v_mfma_f32_16x16x32_bf16 v[12:15], v[208:211], v[224:227], v[12:15]
	v_mfma_f32_16x16x32_bf16 v[8:11], v[212:215], v[224:227], v[8:11]
	s_cmp_lt_u32 s94, 14
	s_cbranch_scc0 .Lgz1_w3
	s_add_u32 m0, s95, s14
	s_add_u32 m0, m0, 0x3000
	s_nop 0
	global_load_lds_dwordx4 v197, s[12:13]
.Lgz1_w3:
	v_mfma_f32_16x16x32_bf16 v[52:55], v[252:255], v[232:235], v[52:55]
	v_mfma_f32_16x16x32_bf16 v[48:51], v[204:207], v[232:235], v[48:51]
	v_mfma_f32_16x16x32_bf16 v[4:7], v[208:211], v[232:235], v[4:7]
	v_mfma_f32_16x16x32_bf16 v[0:3], v[212:215], v[232:235], v[0:3]
	s_cmp_lt_u32 s94, 14
	s_cbranch_scc0 .Lgz1_v0
	s_waitcnt vmcnt(4)
	s_branch .Lgz1_vj

; #define WAIT_V(n) asm volatile("s_waitcnt vmcnt(%0)" ::"n"(n) : "memory")
; #define RAW_BARRIER() do { asm volatile("s_waitcnt lgkmcnt(0)" ::: "memory"); __builtin_amdgcn_s_barrier(); } while (0)
; template <class F>
; __device__ __forceinline__ void gemm_big(const ALbf& al, const u16* __restrict__ Wt, int K, int m0, int n0, const F& f, u16* sm) {
;     ...
;   for (int kt = 0; kt < nk; ++kt) {
;     const int nxt2 = (cur >= 1) ? cur - 1 : 2;
;     gb_step(ga, gw, a64, w64, (kt + 2) * 32, kt + 2 < nk, sm + cur * GB_STAGE_EL, sm + nxt2 * GB_STAGE_EL, wave, wm, wn, lane, rsw, acc);
;     if (kt + 2 < nk) WAIT_V(6); else WAIT_V(0);
;     RAW_BARRIER();
;     cur = (cur == 2) ? 0 : cur + 1;
;   }
.Lgz1_vj:
	s_waitcnt lgkmcnt(0)
	s_add_u32 s10, s10, 0xfffe0080
	s_addc_u32 s11, s11, -1
	s_add_u32 s12, s12, 0x80
	s_addc_u32 s13, s13, 0
	s_mov_b32 s14, s15
	s_add_u32 s94, s94, 1
	s_cmp_lt_u32 s94, 16
	s_barrier
	s_cbranch_scc1 .Lgz1_loop
	v_mov_b32_e32 v204, 0x3ab69700
	v_mov_b32_e32 v205, 0xffffea00
	v_mov_b32_e32 v206, 0x41b17218
	v_mov_b32_e32 v207, 0xd000
	v_mov_b32_e32 v208, 0xf00
	v_mov_b32_e32 v209, 0x7f800000
	v_mov_b32_e32 v210, 0xffffffc0
	v_mov_b32_e32 v211, 0xffffffe0
	v_mov_b32_e32 v212, 0x7fc00000
	v_mov_b32_e32 v213, 0xac00
	v_mov_b32_e32 v214, 0x800
	v_mov_b32_e32 v215, 0x140
	v_mov_b32_e32 v216, 0x130
	s_nop 7
	s_branch .LBB0_217

; __device__ __forceinline__ int ltid() { int t = threadIdx.x; asm volatile("" : "+v"(t)); return t; }
; #define WAIT_V(n) asm volatile("s_waitcnt vmcnt(%0)" ::"n"(n) : "memory")
; #define RAW_BARRIER() do { asm volatile("s_waitcnt lgkmcnt(0)" ::: "memory"); __builtin_amdgcn_s_barrier(); } while (0)
; __device__ __forceinline__ void gb_issue(const u16* ga, const u16* gw, size_t a64, size_t w64, int ko, u16* __restrict__ wr, int wave) {
; #pragma unroll
;   for (int i = 0; i < 4; i++)
;     __builtin_amdgcn_global_load_lds((const unsigned*)(ga + i * a64 + ko), (lds_u32*)(wr + (i * 4 + wave) * 512), 16, 0, 0);
; #pragma unroll
;   for (int i = 0; i < 2; i++)
;     __builtin_amdgcn_global_load_lds((const unsigned*)(gw + i * w64 + ko), (lds_u32*)(wr + 256 * GST + (i * 4 + wave) * 512), 16, 0, 0);
; }
; template <class F>
; __device__ __forceinline__ void gemm_big(const ALbf& al, const u16* __restrict__ Wt, int K, int m0, int n0, const F& f, u16* sm) {
;   const int tid = ltid(), lane = tid & 63, wave = tid >> 6;
;   const int wm = wave >> 1, wn = wave & 1;
;   const int rsw = GSW(lane & 15, lane >> 4);
;   f32x4 acc[4][8];
; #pragma unroll
;   for (int i = 0; i < 4; i++)
; #pragma unroll
;     for (int j = 0; j < 8; j++) acc[i][j] = (f32x4){0.f, 0.f, 0.f, 0.f};
;   const int srow = lane >> 2;
;   const int scol = ((lane & 3) ^ ((0 - (srow >> 2)) & 3)) * 8;
;   const u16* ga = al.A + (size_t)(m0 + wave * 16 + srow) * al.lda + scol;
;   const u16* gw = Wt + (size_t)(n0 + wave * 16 + srow) * K + scol;
;   const size_t a64 = (size_t)64 * al.lda, w64 = (size_t)64 * K;
;   const int nk = K >> 5;
;   WAIT_V(0);
;   gb_issue(ga, gw, a64, w64, 0, sm, wave);
;   gb_issue(ga, gw, a64, w64, 32, sm + GB_STAGE_EL, wave);
;   WAIT_V(6);
;   RAW_BARRIER();
.LBB0_242:
	v_mov_b32_e32 v138, v132
	s_lshl_b32 s10, s17, 8
	v_lshrrev_b32_e32 v0, 2, v138
	v_bfe_u32 v140, v138, 4, 2
	v_sub_u32_e32 v0, 0, v0
	v_bitop3_b32 v0, v140, v0, 3 bitop3:0x78
	v_lshlrev_b32_e32 v6, 4, v0
	v_lshrrev_b32_e32 v0, 4, v138
	v_ashrrev_i32_e32 v4, 6, v138
	v_sub_u32_e32 v8, 0, v0
	s_and_b32 s61, s10, 0x3f00
	s_lshl_b32 s10, s17, 1
	v_bfe_u32 v7, v138, 2, 4
	v_xor_b32_e32 v2, v138, v8
	v_lshlrev_b32_e32 v9, 4, v4
	s_load_dwordx16 s[64:79], s[0:1], 0x160
	s_and_b32 s60, s10, 0xffffff80
	v_or_b32_e32 v3, v7, v9
	v_lshlrev_b32_e32 v2, 4, v2
	v_add_u32_e32 v0, s61, v3
	v_and_b32_e32 v134, 48, v2
	v_add_u32_e32 v2, s60, v3
	v_ashrrev_i32_e32 v1, 31, v0
	v_ashrrev_i32_e32 v3, 31, v2
	v_lshlrev_b64 v[0:1], 13, v[0:1]
	v_lshlrev_b64 v[2:3], 13, v[2:3]
	v_lshl_add_u64 v[0:1], s[22:23], 0, v[0:1]
	s_waitcnt lgkmcnt(0)
	v_lshl_add_u64 v[2:3], s[76:77], 0, v[2:3]
	v_lshl_add_u64 v[0:1], v[0:1], 0, v[134:135]
	v_lshl_add_u64 v[2:3], v[2:3], 0, v[134:135]
	v_lshlrev_b32_e32 v134, 10, v4
	v_add_u32_e32 v10, 0x1000, v134
	v_readfirstlane_b32 s10, v134
	s_waitcnt vmcnt(0)
	s_mov_b32 m0, s10
	v_readfirstlane_b32 s10, v10
	v_lshl_add_u64 v[4:5], v[0:1], 0, s[92:93]
	s_mov_b32 m0, s10
	s_mov_b64 s[10:11], 0x100000
	v_add_u32_e32 v10, 0x2000, v134
	v_lshl_add_u64 v[4:5], v[0:1], 0, s[10:11]
	v_readfirstlane_b32 s10, v10
	s_mov_b32 m0, s10
	s_mov_b64 s[10:11], 0x180000
	v_add_u32_e32 v10, 0x3000, v134
	v_lshl_add_u64 v[4:5], v[0:1], 0, s[10:11]
	v_readfirstlane_b32 s10, v10
	s_mov_b32 m0, s10
	v_add_u32_e32 v10, 0x5000, v134
	v_add_u32_e32 v4, 0x4000, v134
	s_mov_b64 s[14:15], 0x80040
	v_readfirstlane_b32 s10, v4
	s_mov_b32 m0, s10
	v_readfirstlane_b32 s10, v10
	v_add_u32_e32 v10, 0x6000, v134
	v_lshl_add_u64 v[4:5], v[2:3], 0, s[92:93]
	s_mov_b32 m0, s10
	v_readfirstlane_b32 s10, v10
	v_add_u32_e32 v10, 0x7000, v134
	v_lshl_add_u64 v[4:5], v[0:1], 0, 64
	s_mov_b32 m0, s10
	v_readfirstlane_b32 s10, v10
	v_lshl_add_u64 v[4:5], v[0:1], 0, s[14:15]
	s_mov_b32 m0, s10
	s_mov_b64 s[10:11], 0x100040
	v_add_u32_e32 v10, 0x8000, v134
	v_lshl_add_u64 v[4:5], v[0:1], 0, s[10:11]
	v_readfirstlane_b32 s10, v10
	s_mov_b32 m0, s10
	s_mov_b64 s[10:11], 0x180040
	v_add_u32_e32 v4, 0x9000, v134
	v_lshl_add_u64 v[0:1], v[0:1], 0, s[10:11]
	v_readfirstlane_b32 s10, v4
	v_add_u32_e32 v4, 0xa000, v134
	s_mov_b32 m0, s10
	v_readfirstlane_b32 s10, v4
	v_lshl_add_u64 v[0:1], v[2:3], 0, 64
	s_mov_b32 m0, s10
	s_and_b32 s12, s4, 0xffffff80
	v_lshl_add_u64 v[0:1], v[2:3], 0, s[14:15]
	v_add_u32_e32 v2, 0xb000, v134
	s_and_b32 s13, s16, 0x3f00
	v_readfirstlane_b32 s10, v2
	s_mov_b32 m0, s10
	v_bitop3_b32 v2, v138, 3, v8 bitop3:0x48
	v_lshlrev_b32_e32 v0, 6, v138
	v_and_or_b32 v143, v0, s80, v6
	v_lshlrev_b32_e32 v0, 1, v138
	v_and_b32_e32 v1, 0x43, v138
	v_and_or_b32 v0, v0, 24, v1
	v_lshrrev_b32_e32 v1, 1, v138
	v_and_b32_e32 v1, 2, v1
	v_sub_u32_e32 v1, 0, v1
	v_bitop3_b32 v1, v1, v140, 2 bitop3:0x6c
	v_lshlrev_b32_e32 v1, 4, v1
	v_lshl_or_b32 v144, v0, 6, v1
	v_or_b32_e32 v0, 4, v0
	v_lshlrev_b32_e32 v1, 6, v0
	v_lshrrev_b32_e32 v0, 2, v0
	v_sub_u32_e32 v0, 0, v0
	v_bitop3_b32 v0, v0, v140, 3 bitop3:0x6c
	v_lshl_or_b32 v145, v0, 4, v1
	v_or_b32_e32 v0, s12, v7
	v_add_u32_e32 v0, v0, v9
	v_ashrrev_i32_e32 v1, 31, v0
	v_lshlrev_b64 v[0:1], 13, v[0:1]
	v_lshlrev_b32_e32 v2, 4, v2
	v_or_b32_e32 v0, v0, v2
	v_lshl_add_u64 v[128:129], s[76:77], 0, v[0:1]
	v_or_b32_e32 v0, s13, v7
	v_add_u32_e32 v0, v0, v9
	v_ashrrev_i32_e32 v1, 31, v0
	s_waitcnt vmcnt(6)
	v_lshlrev_b64 v[0:1], 13, v[0:1]
	s_waitcnt lgkmcnt(0)
	v_or_b32_e32 v0, v0, v2
	v_lshl_add_u64 v[130:131], s[22:23], 0, v[0:1]
	v_mov_b32_e32 v0, 0
	s_mov_b32 s94, 0
	s_mov_b64 s[10:11], 0
	s_mov_b32 s95, 0
	v_mov_b32_e32 v1, v0
	v_mov_b32_e32 v2, v0
	v_mov_b32_e32 v3, v0
	v_mov_b32_e32 v4, v0
	v_mov_b32_e32 v5, v0
	v_mov_b32_e32 v6, v0
	v_mov_b32_e32 v7, v0
	v_mov_b32_e32 v32, v0
	v_mov_b32_e32 v33, v0
	v_mov_b32_e32 v34, v0
	v_mov_b32_e32 v35, v0
	v_mov_b32_e32 v36, v0
	v_mov_b32_e32 v37, v0
	v_mov_b32_e32 v38, v0
	v_mov_b32_e32 v39, v0
	v_mov_b32_e32 v8, v0
	v_mov_b32_e32 v9, v0
	v_mov_b32_e32 v10, v0
	v_mov_b32_e32 v11, v0
	v_mov_b32_e32 v12, v0
	v_mov_b32_e32 v13, v0
	v_mov_b32_e32 v14, v0
	v_mov_b32_e32 v15, v0
	v_mov_b32_e32 v48, v0
	v_mov_b32_e32 v49, v0
	v_mov_b32_e32 v50, v0
	v_mov_b32_e32 v51, v0
	v_mov_b32_e32 v52, v0
	v_mov_b32_e32 v53, v0
	v_mov_b32_e32 v54, v0
	v_mov_b32_e32 v55, v0
	v_mov_b32_e32 v16, v0
	v_mov_b32_e32 v17, v0
	v_mov_b32_e32 v18, v0
	v_mov_b32_e32 v19, v0
	v_mov_b32_e32 v20, v0
	v_mov_b32_e32 v21, v0
	v_mov_b32_e32 v22, v0
	v_mov_b32_e32 v23, v0
	v_mov_b32_e32 v64, v0
	v_mov_b32_e32 v65, v0
	v_mov_b32_e32 v66, v0
	v_mov_b32_e32 v67, v0
	v_mov_b32_e32 v72, v0
	v_mov_b32_e32 v73, v0
	v_mov_b32_e32 v74, v0
	v_mov_b32_e32 v75, v0
	v_mov_b32_e32 v24, v0
	v_mov_b32_e32 v25, v0
	v_mov_b32_e32 v26, v0
	v_mov_b32_e32 v27, v0
	v_mov_b32_e32 v28, v0
	v_mov_b32_e32 v29, v0
	v_mov_b32_e32 v30, v0
	v_mov_b32_e32 v31, v0
	v_mov_b32_e32 v88, v0
	v_mov_b32_e32 v89, v0
	v_mov_b32_e32 v90, v0
	v_mov_b32_e32 v91, v0
	v_mov_b32_e32 v92, v0
	v_mov_b32_e32 v93, v0
	v_mov_b32_e32 v94, v0
	v_mov_b32_e32 v95, v0
	v_mov_b32_e32 v40, v0
	v_mov_b32_e32 v41, v0
	v_mov_b32_e32 v42, v0
	v_mov_b32_e32 v43, v0
	v_mov_b32_e32 v44, v0
	v_mov_b32_e32 v45, v0
	v_mov_b32_e32 v46, v0
	v_mov_b32_e32 v47, v0
	v_mov_b32_e32 v96, v0
	v_mov_b32_e32 v97, v0
	v_mov_b32_e32 v98, v0
	v_mov_b32_e32 v99, v0
	v_mov_b32_e32 v100, v0
	v_mov_b32_e32 v101, v0
	v_mov_b32_e32 v102, v0
	v_mov_b32_e32 v103, v0
	v_mov_b32_e32 v56, v0
	v_mov_b32_e32 v57, v0
	v_mov_b32_e32 v58, v0
	v_mov_b32_e32 v59, v0
	v_mov_b32_e32 v60, v0
	v_mov_b32_e32 v61, v0
; __device__ __forceinline__ void gb_step(const u16* ga, const u16* gw, size_t a64, size_t w64, int ko, bool issue, ...
;   if (issue) {
; #pragma unroll
;     for (int i = 0; i < 4; i++)
;       __builtin_amdgcn_global_load_lds((const unsigned*)(ga + i * a64 + ko), (lds_u32*)(wr + (i * 4 + wave) * 512), 16, 0, 0);
; #pragma unroll
;     for (int i = 0; i < 2; i++)
;       __builtin_amdgcn_global_load_lds((const unsigned*)(gw + i * w64 + ko), (lds_u32*)(wr + 256 * GST + (i * 4 + wave) * 512), 16, 0, 0);
;   }
;   const unsigned rdb = (unsigned)(size_t)(__attribute__((address_space(3))) const char*)rd;
;   const unsigned ab = rdb + (unsigned)(((wm * 128 + (lane & 15)) * GST + rsw) * 2);
;   const int wr0 = wn * 64 + (((lane & 15) >> 2) << 3) + (lane & 3);
;   const unsigned bb0 = rdb + (unsigned)((256 * GST + wr0 * GST + GSW(wr0, lane >> 4)) * 2);
;   const unsigned bb1 = rdb + (unsigned)((256 * GST + (wr0 + 4) * GST + GSW(wr0 + 4, lane >> 4)) * 2);
;   bf16x8 wf0, wf1, wf2, wf3, xf0, xf1, xf2, xf3, xf4, xf5, xf6, xf7;
;     ...
;   DSR(wf0, bb0, 0); DSR(wf1, bb1, 0); DSR(wf2, bb0, 2048); DSR(wf3, bb1, 2048);
;   DSR(xf0, ab, 0); DSR(xf1, ab, 1024); DSR(xf2, ab, 2048); DSR(xf3, ab, 3072);
;   DSR(xf4, ab, 4096); DSR(xf5, ab, 5120); DSR(xf6, ab, 6144); DSR(xf7, ab, 7168);
;     ...
;   asm volatile("s_waitcnt lgkmcnt(7)" : "+v"(wf0), "+v"(wf1), "+v"(wf2), "+v"(wf3), "+v"(xf0) : : "memory");
;   MM(0, xf0)
;   asm volatile("s_waitcnt lgkmcnt(6)" : "+v"(xf1) : : "memory");
;   MM(1, xf1)
;   asm volatile("s_waitcnt lgkmcnt(5)" : "+v"(xf2) : : "memory");
;   MM(2, xf2)
; template <class F>
; __device__ __forceinline__ void gemm_big(const ALbf& al, const u16* __restrict__ Wt, int K, int m0, int n0, const F& f, u16* sm) {
;     ...
; #pragma unroll
;   for (int i = 0; i < 4; i++)
; #pragma unroll
;     for (int j = 0; j < 8; j++) acc[i][j] = (f32x4){0.f, 0.f, 0.f, 0.f};
;   const int srow = lane >> 2;
;   const int scol = ((lane & 3) ^ ((0 - (srow >> 2)) & 3)) * 8;
;   const u16* ga = al.A + (size_t)(m0 + wave * 16 + srow) * al.lda + scol;
;   const u16* gw = Wt + (size_t)(n0 + wave * 16 + srow) * K + scol;
;   const size_t a64 = (size_t)64 * al.lda, w64 = (size_t)64 * K;
;   const int nk = K >> 5;
;   WAIT_V(0);
;   gb_issue(ga, gw, a64, w64, 0, sm, wave);
;   gb_issue(ga, gw, a64, w64, 32, sm + GB_STAGE_EL, wave);
;   WAIT_V(6);
;   RAW_BARRIER();
	v_mov_b32_e32 v62, v0
	v_mov_b32_e32 v63, v0
	v_mov_b32_e32 v104, v0
	v_mov_b32_e32 v105, v0
	v_mov_b32_e32 v106, v0
	v_mov_b32_e32 v107, v0
	v_mov_b32_e32 v108, v0
	v_mov_b32_e32 v109, v0
	v_mov_b32_e32 v110, v0
	v_mov_b32_e32 v111, v0
	v_mov_b32_e32 v68, v0
	v_mov_b32_e32 v69, v0
	v_mov_b32_e32 v70, v0
	v_mov_b32_e32 v71, v0
	v_mov_b32_e32 v76, v0
	v_mov_b32_e32 v77, v0
	v_mov_b32_e32 v78, v0
	v_mov_b32_e32 v79, v0
	v_mov_b32_e32 v112, v0
	v_mov_b32_e32 v113, v0
	v_mov_b32_e32 v114, v0
	v_mov_b32_e32 v115, v0
	v_mov_b32_e32 v116, v0
	v_mov_b32_e32 v117, v0
	v_mov_b32_e32 v118, v0
	v_mov_b32_e32 v119, v0
	v_mov_b32_e32 v80, v0
	v_mov_b32_e32 v81, v0
	v_mov_b32_e32 v82, v0
	v_mov_b32_e32 v83, v0
	v_mov_b32_e32 v84, v0
	v_mov_b32_e32 v85, v0
	v_mov_b32_e32 v86, v0
	v_mov_b32_e32 v87, v0
	v_mov_b32_e32 v120, v0
	v_mov_b32_e32 v121, v0
	v_mov_b32_e32 v122, v0
	v_mov_b32_e32 v123, v0
	v_mov_b32_e32 v124, v0
	v_mov_b32_e32 v125, v0
	v_mov_b32_e32 v126, v0
	v_mov_b32_e32 v127, v0
	v_readfirstlane_b32 s10, v130
	v_readfirstlane_b32 s11, v131
	v_readfirstlane_b32 s12, v128
	v_readfirstlane_b32 s13, v129
	v_readfirstlane_b32 s95, v134
	v_and_b32_e32 v176, 63, v132
	v_lshrrev_b32_e32 v177, 6, v132
	v_lshrrev_b32_e32 v178, 3, v176
	v_and_b32_e32 v179, 7, v176
	v_lshrrev_b32_e32 v180, 4, v176
	v_and_b32_e32 v181, 1, v177
	v_lshrrev_b32_e32 v182, 1, v177
	v_lshl_add_u32 v183, v181, 2, v180
	v_xor_b32_e32 v183, v179, v183
	v_lshl_add_u32 v184, v177, 3, v178
	v_lshlrev_b32_e32 v188, 13, v184
	v_lshl_add_u32 v128, v183, 4, v188
	v_add_u32_e32 v129, 0x40000, v128
	v_add_u32_e32 v130, 0x100000, v128
	v_add_u32_e32 v131, 0x140000, v128
	v_bfe_u32 v185, v178, 1, 1
	v_lshl_or_b32 v185, v181, 1, v185
	v_lshl_or_b32 v185, v182, 2, v185
	v_xor_b32_e32 v185, v179, v185
	v_lshl_add_u32 v134, v185, 4, v188
	v_add_u32_e32 v143, 0x40000, v134
	v_add_u32_e32 v196, 0x80000, v134
	v_add_u32_e32 v197, 0xc0000, v134
	v_and_b32_e32 v186, 15, v176
	v_bfe_u32 v187, v176, 1, 3
	v_xor_b32_e32 v187, v180, v187
	v_lshlrev_b32_e32 v187, 4, v187
	v_lshl_add_u32 v188, v182, 6, v186
	v_lshl_add_u32 v219, v188, 7, v187
	v_xor_b32_e32 v228, 64, v219
	v_lshrrev_b32_e32 v189, 2, v186
	v_lshlrev_b32_e32 v189, 3, v189
	v_and_b32_e32 v188, 3, v186
	v_add_u32_e32 v189, v189, v188
	v_lshl_add_u32 v189, v181, 6, v189
	v_lshl_add_u32 v231, v189, 7, v187
	v_xor_b32_e32 v216, 64, v231
	s_lshl_b32 s15, s95, 7
	s_sub_u32 s10, s10, s15
	s_subb_u32 s11, s11, 0
	s_sub_u32 s12, s12, s15
	s_subb_u32 s13, s13, 0
	s_add_u32 m0, s95, 0x8000
	s_nop 0
	global_load_lds_dwordx4 v128, s[10:11]
	s_add_u32 m0, s95, 0x9000
	s_nop 0
	global_load_lds_dwordx4 v129, s[10:11]
	s_add_u32 m0, s95, 0xa000
	s_nop 0
	global_load_lds_dwordx4 v130, s[10:11]
	s_add_u32 m0, s95, 0xb000
	s_nop 0
	global_load_lds_dwordx4 v131, s[10:11]
	s_add_u32 s10, s10, 0x80000
	s_addc_u32 s11, s11, 0
	s_add_u32 m0, s95, 0xc000
	s_nop 0
	global_load_lds_dwordx4 v128, s[10:11]
	s_add_u32 m0, s95, 0xd000
	s_nop 0
	global_load_lds_dwordx4 v129, s[10:11]
	s_add_u32 m0, s95, 0xe000
	s_nop 0
	global_load_lds_dwordx4 v130, s[10:11]
	s_add_u32 m0, s95, 0xf000
	s_nop 0
	global_load_lds_dwordx4 v131, s[10:11]
	s_add_u32 s10, s10, 0xfff80080
	s_addc_u32 s11, s11, -1
	s_add_u32 m0, s95, 0x0
	s_nop 0
	global_load_lds_dwordx4 v134, s[12:13]
	s_add_u32 m0, s95, 0x1000
	s_nop 0
	global_load_lds_dwordx4 v143, s[12:13]
	s_add_u32 m0, s95, 0x2000
	s_nop 0
	global_load_lds_dwordx4 v196, s[12:13]
	s_add_u32 m0, s95, 0x3000
	s_nop 0
	global_load_lds_dwordx4 v197, s[12:13]
	s_add_u32 s12, s12, 0x80
	s_addc_u32 s13, s13, 0
	s_add_u32 m0, s95, 0x4000
	s_nop 0
	global_load_lds_dwordx4 v134, s[12:13]
	s_add_u32 m0, s95, 0x5000
	s_nop 0
	global_load_lds_dwordx4 v143, s[12:13]
	s_add_u32 m0, s95, 0x6000
	s_nop 0
	global_load_lds_dwordx4 v196, s[12:13]
	s_add_u32 m0, s95, 0x7000
	s_nop 0
	global_load_lds_dwordx4 v197, s[12:13]
	s_add_u32 s12, s12, 0x80
	s_addc_u32 s13, s13, 0
	s_waitcnt vmcnt(0)
	s_barrier
	s_mov_b32 s14, 0
	s_mov_b32 s94, 0
	ds_read_b128 v[144:147], v219 offset:32768
	ds_read_b128 v[148:151], v219 offset:34816
	ds_read_b128 v[152:155], v219 offset:36864
	ds_read_b128 v[156:159], v219 offset:38912
	ds_read_b128 v[160:163], v228 offset:32768
	ds_read_b128 v[164:167], v228 offset:34816
	ds_read_b128 v[168:171], v228 offset:36864
	ds_read_b128 v[172:175], v228 offset:38912
	v_add_u32_e32 v248, s14, v231
	ds_read_b128 v[236:239], v248 offset:0
	ds_read_b128 v[240:243], v248 offset:512
	ds_read_b128 v[244:247], v248 offset:4096
	ds_read_b128 v[248:251], v248 offset:4608
	s_waitcnt lgkmcnt(0)
	s_barrier
.Lgz2_loop:
	s_cmp_lt_u32 s94, 63
	s_cselect_b64 vcc, -1, 0
	v_add_u32_e32 v212, s14, v216
	ds_read_b128 v[252:255], v212 offset:0
	ds_read_b128 v[204:207], v212 offset:512
	ds_read_b128 v[208:211], v212 offset:4096
	ds_read_b128 v[212:215], v212 offset:4608
	v_mfma_f32_16x16x32_bf16 v[124:127], v[236:239], v[144:147], v[124:127]
	ds_read_b128 v[176:179], v219 offset:49152
	v_mfma_f32_16x16x32_bf16 v[120:123], v[240:243], v[144:147], v[120:123]
	ds_read_b128 v[180:183], v219 offset:51200
	v_mfma_f32_16x16x32_bf16 v[84:87], v[244:247], v[144:147], v[84:87]
	ds_read_b128 v[184:187], v219 offset:53248
	v_mfma_f32_16x16x32_bf16 v[80:83], v[248:251], v[144:147], v[80:83]
	ds_read_b128 v[188:191], v219 offset:55296
	v_mfma_f32_16x16x32_bf16 v[116:119], v[236:239], v[148:151], v[116:119]
	ds_read_b128 v[192:195], v228 offset:49152
	v_mfma_f32_16x16x32_bf16 v[112:115], v[240:243], v[148:151], v[112:115]
	ds_read_b128 v[220:223], v228 offset:51200
	v_mfma_f32_16x16x32_bf16 v[76:79], v[244:247], v[148:151], v[76:79]
	ds_read_b128 v[224:227], v228 offset:53248
	v_mfma_f32_16x16x32_bf16 v[68:71], v[248:251], v[148:151], v[68:71]
	ds_read_b128 v[232:235], v228 offset:55296
	s_add_u32 m0, s95, 0x8000
	v_mfma_f32_16x16x32_bf16 v[108:111], v[236:239], v[152:155], v[108:111]
	s_cbranch_vccz .Lgz2_a0
	global_load_lds_dwordx4 v128, s[10:11]
; #define DSR(dst, addr, off) asm volatile("ds_read_b128 %0, %1 offset:%2" : "=v"(dst) : "v"(addr), "n"(off) : "memory")
; #define MM(j, xf)                                                                     \
;   acc[0][j] = MFMA16(wf0, xf, acc[0][j]); acc[1][j] = MFMA16(wf1, xf, acc[1][j]);      \
;   acc[2][j] = MFMA16(wf2, xf, acc[2][j]); acc[3][j] = MFMA16(wf3, xf, acc[3][j]);
; __device__ __forceinline__ void gb_step(const u16* ga, const u16* gw, size_t a64, size_t w64, int ko, bool issue, ...
;   if (issue) {
; #pragma unroll
;     for (int i = 0; i < 4; i++)
;       __builtin_amdgcn_global_load_lds((const unsigned*)(ga + i * a64 + ko), (lds_u32*)(wr + (i * 4 + wave) * 512), 16, 0, 0);
; #pragma unroll
;     for (int i = 0; i < 2; i++)
;       __builtin_amdgcn_global_load_lds((const unsigned*)(gw + i * w64 + ko), (lds_u32*)(wr + 256 * GST + (i * 4 + wave) * 512), 16, 0, 0);
;   }
;   const unsigned rdb = (unsigned)(size_t)(__attribute__((address_space(3))) const char*)rd;
;   const unsigned ab = rdb + (unsigned)(((wm * 128 + (lane & 15)) * GST + rsw) * 2);
;   const int wr0 = wn * 64 + (((lane & 15) >> 2) << 3) + (lane & 3);
;   const unsigned bb0 = rdb + (unsigned)((256 * GST + wr0 * GST + GSW(wr0, lane >> 4)) * 2);
;   const unsigned bb1 = rdb + (unsigned)((256 * GST + (wr0 + 4) * GST + GSW(wr0 + 4, lane >> 4)) * 2);
;   bf16x8 wf0, wf1, wf2, wf3, xf0, xf1, xf2, xf3, xf4, xf5, xf6, xf7;
;     ...
;   DSR(wf0, bb0, 0); DSR(wf1, bb1, 0); DSR(wf2, bb0, 2048); DSR(wf3, bb1, 2048);
;   DSR(xf0, ab, 0); DSR(xf1, ab, 1024); DSR(xf2, ab, 2048); DSR(xf3, ab, 3072);
;   DSR(xf4, ab, 4096); DSR(xf5, ab, 5120); DSR(xf6, ab, 6144); DSR(xf7, ab, 7168);
;     ...
;   asm volatile("s_waitcnt lgkmcnt(7)" : "+v"(wf0), "+v"(wf1), "+v"(wf2), "+v"(wf3), "+v"(xf0) : : "memory");
;   MM(0, xf0)
;   asm volatile("s_waitcnt lgkmcnt(6)" : "+v"(xf1) : : "memory");
;   MM(1, xf1)
;   asm volatile("s_waitcnt lgkmcnt(5)" : "+v"(xf2) : : "memory");
;   MM(2, xf2)
;   asm volatile("s_waitcnt lgkmcnt(4)" : "+v"(xf3) : : "memory");
;   MM(3, xf3)
;   asm volatile("s_waitcnt lgkmcnt(3)" : "+v"(xf4) : : "memory");
;   MM(4, xf4)
;   asm volatile("s_waitcnt lgkmcnt(2)" : "+v"(xf5) : : "memory");
;   MM(5, xf5)
;   asm volatile("s_waitcnt lgkmcnt(1)" : "+v"(xf6) : : "memory");
;   MM(6, xf6)
;   asm volatile("s_waitcnt lgkmcnt(0)" : "+v"(xf7) : : "memory");
;   MM(7, xf7)
.Lgz2_a0:
	v_mfma_f32_16x16x32_bf16 v[104:107], v[240:243], v[152:155], v[104:107]
	s_add_u32 m0, s95, 0x9000
	v_mfma_f32_16x16x32_bf16 v[60:63], v[244:247], v[152:155], v[60:63]
	s_cbranch_vccz .Lgz2_a1
	global_load_lds_dwordx4 v129, s[10:11]
.Lgz2_a1:
	v_mfma_f32_16x16x32_bf16 v[56:59], v[248:251], v[152:155], v[56:59]
	s_add_u32 m0, s95, 0xa000
	v_mfma_f32_16x16x32_bf16 v[100:103], v[236:239], v[156:159], v[100:103]
	s_cbranch_vccz .Lgz2_a2
	global_load_lds_dwordx4 v130, s[10:11]
.Lgz2_a2:
	v_mfma_f32_16x16x32_bf16 v[96:99], v[240:243], v[156:159], v[96:99]
	s_add_u32 m0, s95, 0xb000
	v_mfma_f32_16x16x32_bf16 v[44:47], v[244:247], v[156:159], v[44:47]
	s_cbranch_vccz .Lgz2_a3
	global_load_lds_dwordx4 v131, s[10:11]
.Lgz2_a3:
	v_mfma_f32_16x16x32_bf16 v[40:43], v[248:251], v[156:159], v[40:43]
	s_waitcnt lgkmcnt(8)
	v_mfma_f32_16x16x32_bf16 v[124:127], v[252:255], v[160:163], v[124:127]
	v_mfma_f32_16x16x32_bf16 v[120:123], v[204:207], v[160:163], v[120:123]
	v_mfma_f32_16x16x32_bf16 v[84:87], v[208:211], v[160:163], v[84:87]
	v_mfma_f32_16x16x32_bf16 v[80:83], v[212:215], v[160:163], v[80:83]
	v_mfma_f32_16x16x32_bf16 v[116:119], v[252:255], v[164:167], v[116:119]
	v_mfma_f32_16x16x32_bf16 v[112:115], v[204:207], v[164:167], v[112:115]
	v_mfma_f32_16x16x32_bf16 v[76:79], v[208:211], v[164:167], v[76:79]
	v_mfma_f32_16x16x32_bf16 v[68:71], v[212:215], v[164:167], v[68:71]
	v_mfma_f32_16x16x32_bf16 v[108:111], v[252:255], v[168:171], v[108:111]
	v_mfma_f32_16x16x32_bf16 v[104:107], v[204:207], v[168:171], v[104:107]
	v_mfma_f32_16x16x32_bf16 v[60:63], v[208:211], v[168:171], v[60:63]
	v_mfma_f32_16x16x32_bf16 v[56:59], v[212:215], v[168:171], v[56:59]
	v_mfma_f32_16x16x32_bf16 v[100:103], v[252:255], v[172:175], v[100:103]
	v_mfma_f32_16x16x32_bf16 v[96:99], v[204:207], v[172:175], v[96:99]
	v_mfma_f32_16x16x32_bf16 v[44:47], v[208:211], v[172:175], v[44:47]
	v_mfma_f32_16x16x32_bf16 v[40:43], v[212:215], v[172:175], v[40:43]
	s_waitcnt vmcnt(0)
	s_waitcnt lgkmcnt(0)
	s_add_u32 s10, s10, 0x80000
	s_addc_u32 s11, s11, 0
	s_xor_b32 s15, s14, 0x4000
	s_barrier
	v_mfma_f32_16x16x32_bf16 v[92:95], v[236:239], v[176:179], v[92:95]
	ds_read_b128 v[144:147], v219 offset:32768
	v_mfma_f32_16x16x32_bf16 v[88:91], v[240:243], v[176:179], v[88:91]
	ds_read_b128 v[148:151], v219 offset:34816
	v_mfma_f32_16x16x32_bf16 v[28:31], v[244:247], v[176:179], v[28:31]
	ds_read_b128 v[152:155], v219 offset:36864
	v_mfma_f32_16x16x32_bf16 v[24:27], v[248:251], v[176:179], v[24:27]
	ds_read_b128 v[156:159], v219 offset:38912
	v_mfma_f32_16x16x32_bf16 v[72:75], v[236:239], v[180:183], v[72:75]
	ds_read_b128 v[160:163], v228 offset:32768
	v_mfma_f32_16x16x32_bf16 v[64:67], v[240:243], v[180:183], v[64:67]
	ds_read_b128 v[164:167], v228 offset:34816
	v_mfma_f32_16x16x32_bf16 v[20:23], v[244:247], v[180:183], v[20:23]
	ds_read_b128 v[168:171], v228 offset:36864
	v_mfma_f32_16x16x32_bf16 v[16:19], v[248:251], v[180:183], v[16:19]
	ds_read_b128 v[172:175], v228 offset:38912
	s_add_u32 m0, s95, 0xc000
	v_mfma_f32_16x16x32_bf16 v[52:55], v[236:239], v[184:187], v[52:55]
	s_cbranch_vccz .Lgz2_b0
	global_load_lds_dwordx4 v128, s[10:11]
.Lgz2_b0:
	v_mfma_f32_16x16x32_bf16 v[48:51], v[240:243], v[184:187], v[48:51]
	s_add_u32 m0, s95, 0xd000
	v_mfma_f32_16x16x32_bf16 v[12:15], v[244:247], v[184:187], v[12:15]
	s_cbranch_vccz .Lgz2_b1
	global_load_lds_dwordx4 v129, s[10:11]
.Lgz2_b1:
	v_mfma_f32_16x16x32_bf16 v[8:11], v[248:251], v[184:187], v[8:11]
	s_add_u32 m0, s95, 0xe000
	v_mfma_f32_16x16x32_bf16 v[36:39], v[236:239], v[188:191], v[36:39]
	s_cbranch_vccz .Lgz2_b2
	global_load_lds_dwordx4 v130, s[10:11]
.Lgz2_b2:
	v_mfma_f32_16x16x32_bf16 v[32:35], v[240:243], v[188:191], v[32:35]
	s_add_u32 m0, s95, 0xf000
	v_mfma_f32_16x16x32_bf16 v[4:7], v[244:247], v[188:191], v[4:7]
	s_cbranch_vccz .Lgz2_b3
	global_load_lds_dwordx4 v131, s[10:11]
.Lgz2_b3:
	v_mfma_f32_16x16x32_bf16 v[0:3], v[248:251], v[188:191], v[0:3]
	v_add_u32_e32 v248, s15, v231
	v_mfma_f32_16x16x32_bf16 v[92:95], v[252:255], v[192:195], v[92:95]
	ds_read_b128 v[236:239], v248 offset:0
	v_mfma_f32_16x16x32_bf16 v[88:91], v[204:207], v[192:195], v[88:91]
	ds_read_b128 v[240:243], v248 offset:512
	v_mfma_f32_16x16x32_bf16 v[28:31], v[208:211], v[192:195], v[28:31]
	ds_read_b128 v[244:247], v248 offset:4096
	v_mfma_f32_16x16x32_bf16 v[24:27], v[212:215], v[192:195], v[24:27]
	ds_read_b128 v[248:251], v248 offset:4608
	v_mfma_f32_16x16x32_bf16 v[72:75], v[252:255], v[220:223], v[72:75]
	v_mfma_f32_16x16x32_bf16 v[64:67], v[204:207], v[220:223], v[64:67]
	s_cmp_lt_u32 s94, 62
	s_cbranch_scc0 .Lgz2_w0
	s_add_u32 m0, s95, s14
	s_add_u32 m0, m0, 0x0
	s_nop 0
	global_load_lds_dwordx4 v134, s[12:13]
.Lgz2_w0:
	v_mfma_f32_16x16x32_bf16 v[20:23], v[208:211], v[220:223], v[20:23]
	v_mfma_f32_16x16x32_bf16 v[16:19], v[212:215], v[220:223], v[16:19]
	s_cmp_lt_u32 s94, 62
	s_cbranch_scc0 .Lgz2_w1
	s_add_u32 m0, s95, s14
	s_add_u32 m0, m0, 0x1000
	s_nop 0
	global_load_lds_dwordx4 v143, s[12:13]
.Lgz2_w1:
	v_mfma_f32_16x16x32_bf16 v[52:55], v[252:255], v[224:227], v[52:55]
	v_mfma_f32_16x16x32_bf16 v[48:51], v[204:207], v[224:227], v[48:51]
	s_cmp_lt_u32 s94, 62
	s_cbranch_scc0 .Lgz2_w2
	s_add_u32 m0, s95, s14
	s_add_u32 m0, m0, 0x2000
	s_nop 0
	global_load_lds_dwordx4 v196, s[12:13]
.Lgz2_w2:
	v_mfma_f32_16x16x32_bf16 v[12:15], v[208:211], v[224:227], v[12:15]
	v_mfma_f32_16x16x32_bf16 v[8:11], v[212:215], v[224:227], v[8:11]
	s_cmp_lt_u32 s94, 62
	s_cbranch_scc0 .Lgz2_w3
	s_add_u32 m0, s95, s14
	s_add_u32 m0, m0, 0x3000
	s_nop 0
	global_load_lds_dwordx4 v197, s[12:13]
.Lgz2_w3:
	v_mfma_f32_16x16x32_bf16 v[36:39], v[252:255], v[232:235], v[36:39]
	v_mfma_f32_16x16x32_bf16 v[32:35], v[204:207], v[232:235], v[32:35]
	v_mfma_f32_16x16x32_bf16 v[4:7], v[208:211], v[232:235], v[4:7]
	v_mfma_f32_16x16x32_bf16 v[0:3], v[212:215], v[232:235], v[0:3]
	s_cmp_lt_u32 s94, 62
	s_cbranch_scc0 .Lgz2_v0
	s_waitcnt vmcnt(4)
	s_branch .Lgz2_vj

; #define WAIT_V(n) asm volatile("s_waitcnt vmcnt(%0)" ::"n"(n) : "memory")
; #define RAW_BARRIER() do { asm volatile("s_waitcnt lgkmcnt(0)" ::: "memory"); __builtin_amdgcn_s_barrier(); } while (0)
; template <class F>
; __device__ __forceinline__ void gemm_big(const ALbf& al, const u16* __restrict__ Wt, int K, int m0, int n0, const F& f, u16* sm) {
;     ...
;   for (int kt = 0; kt < nk; ++kt) {
;     const int nxt2 = (cur >= 1) ? cur - 1 : 2;
;     gb_step(ga, gw, a64, w64, (kt + 2) * 32, kt + 2 < nk, sm + cur * GB_STAGE_EL, sm + nxt2 * GB_STAGE_EL, wave, wm, wn, lane, rsw, acc);
;     if (kt + 2 < nk) WAIT_V(6); else WAIT_V(0);
;     RAW_BARRIER();
;     cur = (cur == 2) ? 0 : cur + 1;
;   }
.Lgz2_vj:
	s_waitcnt lgkmcnt(0)
	s_add_u32 s10, s10, 0xfff80080
	s_addc_u32 s11, s11, -1
	s_add_u32 s12, s12, 0x80
	s_addc_u32 s13, s13, 0
	s_mov_b32 s14, s15
	s_add_u32 s94, s94, 1
	s_cmp_lt_u32 s94, 64
	s_barrier
	s_cbranch_scc1 .Lgz2_loop
	v_mov_b32_e32 v204, 0x3ab69700
	v_mov_b32_e32 v205, 0xffffea00
	v_mov_b32_e32 v206, 0x41b17218
	v_mov_b32_e32 v207, 0xd000
	v_mov_b32_e32 v208, 0xf00
	v_mov_b32_e32 v209, 0x7f800000
	v_mov_b32_e32 v210, 0xffffffc0
	v_mov_b32_e32 v211, 0xffffffe0
	v_mov_b32_e32 v212, 0x7fc00000
	v_mov_b32_e32 v213, 0xac00
	v_mov_b32_e32 v214, 0x800
	v_mov_b32_e32 v215, 0x140
	v_mov_b32_e32 v216, 0x130
	s_nop 7
	s_branch .LBB0_241

; __device__ __forceinline__ int ltid() { int t = threadIdx.x; asm volatile("" : "+v"(t)); return t; }
; #define WAIT_V(n) asm volatile("s_waitcnt vmcnt(%0)" ::"n"(n) : "memory")
; #define RAW_BARRIER() do { asm volatile("s_waitcnt lgkmcnt(0)" ::: "memory"); __builtin_amdgcn_s_barrier(); } while (0)
; __device__ __forceinline__ void gb_issue(const u16* ga, const u16* gw, size_t a64, size_t w64, int ko, u16* __restrict__ wr, int wave) {
; #pragma unroll
;   for (int i = 0; i < 4; i++)
;     __builtin_amdgcn_global_load_lds((const unsigned*)(ga + i * a64 + ko), (lds_u32*)(wr + (i * 4 + wave) * 512), 16, 0, 0);
; #pragma unroll
;   for (int i = 0; i < 2; i++)
;     __builtin_amdgcn_global_load_lds((const unsigned*)(gw + i * w64 + ko), (lds_u32*)(wr + 256 * GST + (i * 4 + wave) * 512), 16, 0, 0);
; }
; template <class F>
; __device__ __forceinline__ void gemm_big(const ALbf& al, const u16* __restrict__ Wt, int K, int m0, int n0, const F& f, u16* sm) {
;   const int tid = ltid(), lane = tid & 63, wave = tid >> 6;
;   const int wm = wave >> 1, wn = wave & 1;
;   const int rsw = GSW(lane & 15, lane >> 4);
;   f32x4 acc[4][8];
; #pragma unroll
;   for (int i = 0; i < 4; i++)
; #pragma unroll
;     for (int j = 0; j < 8; j++) acc[i][j] = (f32x4){0.f, 0.f, 0.f, 0.f};
;   const int srow = lane >> 2;
;   const int scol = ((lane & 3) ^ ((0 - (srow >> 2)) & 3)) * 8;
;   const u16* ga = al.A + (size_t)(m0 + wave * 16 + srow) * al.lda + scol;
;   const u16* gw = Wt + (size_t)(n0 + wave * 16 + srow) * K + scol;
;   const size_t a64 = (size_t)64 * al.lda, w64 = (size_t)64 * K;
;   const int nk = K >> 5;
;   WAIT_V(0);
;   gb_issue(ga, gw, a64, w64, 0, sm, wave);
;   gb_issue(ga, gw, a64, w64, 32, sm + GB_STAGE_EL, wave);
;   WAIT_V(6);
;   RAW_BARRIER();
.LBB0_257:
	v_mov_b32_e32 v138, v132
	s_lshl_b32 s10, s15, 8
	v_lshrrev_b32_e32 v0, 2, v138
	v_bfe_u32 v140, v138, 4, 2
	v_sub_u32_e32 v0, 0, v0
	v_bitop3_b32 v0, v140, v0, 3 bitop3:0x78
	v_lshlrev_b32_e32 v6, 4, v0
	v_lshrrev_b32_e32 v0, 4, v138
	v_ashrrev_i32_e32 v4, 6, v138
	v_sub_u32_e32 v8, 0, v0
	s_and_b32 s17, s10, 0x3f00
	s_lshl_b32 s10, s15, 1
	v_bfe_u32 v7, v138, 2, 4
	v_xor_b32_e32 v2, v138, v8
	v_lshlrev_b32_e32 v9, 4, v4
	s_load_dwordx16 s[64:79], s[0:1], 0x160
	s_and_b32 s16, s10, 0xffffff80
	v_or_b32_e32 v3, v7, v9
	v_lshlrev_b32_e32 v2, 4, v2
	v_add_u32_e32 v0, s17, v3
	v_and_b32_e32 v134, 48, v2
	v_add_u32_e32 v2, s16, v3
	v_ashrrev_i32_e32 v1, 31, v0
	v_ashrrev_i32_e32 v3, 31, v2
	v_lshlrev_b64 v[0:1], 11, v[0:1]
	v_lshlrev_b64 v[2:3], 11, v[2:3]
	s_waitcnt lgkmcnt(0)
	v_lshl_add_u64 v[0:1], s[30:31], 0, v[0:1]
	v_lshl_add_u64 v[2:3], s[72:73], 0, v[2:3]
	v_lshl_add_u64 v[0:1], v[0:1], 0, v[134:135]
	v_lshl_add_u64 v[2:3], v[2:3], 0, v[134:135]
	v_lshlrev_b32_e32 v134, 10, v4
	v_add_u32_e32 v10, 0x1000, v134
	v_readfirstlane_b32 s10, v134
	s_waitcnt vmcnt(0)
	s_mov_b32 m0, s10
	v_readfirstlane_b32 s10, v10
	v_add_u32_e32 v10, 0x2000, v134
	v_lshl_add_u64 v[4:5], v[0:1], 0, s[96:97]
	s_mov_b32 m0, s10
	v_readfirstlane_b32 s10, v10
	v_lshl_add_u64 v[4:5], v[0:1], 0, s[86:87]
	s_mov_b32 m0, s10
	s_mov_b64 s[10:11], 0x60000
	v_add_u32_e32 v10, 0x3000, v134
	v_lshl_add_u64 v[4:5], v[0:1], 0, s[10:11]
	v_readfirstlane_b32 s10, v10
	s_mov_b32 m0, s10
	v_add_u32_e32 v10, 0x5000, v134
	v_add_u32_e32 v4, 0x4000, v134
	s_mov_b64 s[12:13], 0x20040
	v_readfirstlane_b32 s10, v4
	s_mov_b32 m0, s10
	v_readfirstlane_b32 s10, v10
	v_add_u32_e32 v10, 0x6000, v134
	v_lshl_add_u64 v[4:5], v[2:3], 0, s[96:97]
	s_mov_b32 m0, s10
	v_readfirstlane_b32 s10, v10
	v_add_u32_e32 v10, 0x7000, v134
	v_lshl_add_u64 v[4:5], v[0:1], 0, 64
	s_mov_b32 m0, s10
	v_readfirstlane_b32 s10, v10
	v_lshl_add_u64 v[4:5], v[0:1], 0, s[12:13]
	s_mov_b32 m0, s10
	s_mov_b64 s[10:11], 0x40040
	v_add_u32_e32 v10, 0x8000, v134
	v_lshl_add_u64 v[4:5], v[0:1], 0, s[10:11]
	v_readfirstlane_b32 s10, v10
	s_mov_b32 m0, s10
	s_mov_b64 s[10:11], 0x60040
	v_add_u32_e32 v4, 0x9000, v134
	v_lshl_add_u64 v[0:1], v[0:1], 0, s[10:11]
	v_readfirstlane_b32 s10, v4
	v_add_u32_e32 v4, 0xa000, v134
	s_mov_b32 m0, s10
	v_readfirstlane_b32 s10, v4
	v_lshl_add_u64 v[0:1], v[2:3], 0, 64
	s_mov_b32 m0, s10
	s_and_b32 s6, s4, 0xffffff80
	v_lshl_add_u64 v[0:1], v[2:3], 0, s[12:13]
	v_add_u32_e32 v2, 0xb000, v134
	s_and_b32 s7, s14, 0x3f00
	v_readfirstlane_b32 s10, v2
	s_mov_b32 m0, s10
	v_bitop3_b32 v2, v138, 3, v8 bitop3:0x48
	v_lshlrev_b32_e32 v0, 6, v138
	v_and_or_b32 v143, v0, s80, v6
	v_lshlrev_b32_e32 v0, 1, v138
	v_and_b32_e32 v1, 0x43, v138
	v_and_or_b32 v0, v0, 24, v1
	v_lshrrev_b32_e32 v1, 1, v138
	v_and_b32_e32 v1, 2, v1
	v_sub_u32_e32 v1, 0, v1
	v_bitop3_b32 v1, v1, v140, 2 bitop3:0x6c
	v_lshlrev_b32_e32 v1, 4, v1
	v_lshl_or_b32 v144, v0, 6, v1
	v_or_b32_e32 v0, 4, v0
	v_lshlrev_b32_e32 v1, 6, v0
	v_lshrrev_b32_e32 v0, 2, v0
	v_sub_u32_e32 v0, 0, v0
	v_bitop3_b32 v0, v0, v140, 3 bitop3:0x6c
	v_lshl_or_b32 v145, v0, 4, v1
	v_or_b32_e32 v0, s6, v7
	v_add_u32_e32 v0, v0, v9
	v_ashrrev_i32_e32 v1, 31, v0
	v_lshlrev_b64 v[0:1], 11, v[0:1]
	v_lshlrev_b32_e32 v2, 4, v2
	v_or_b32_e32 v0, v0, v2
	v_lshl_add_u64 v[128:129], s[72:73], 0, v[0:1]
	v_or_b32_e32 v0, s7, v7
	v_add_u32_e32 v0, v0, v9
	v_ashrrev_i32_e32 v1, 31, v0
	s_waitcnt vmcnt(6)
	v_lshlrev_b64 v[0:1], 11, v[0:1]
	s_waitcnt lgkmcnt(0)
	v_or_b32_e32 v0, v0, v2
	v_lshl_add_u64 v[130:131], s[30:31], 0, v[0:1]
	v_mov_b32_e32 v0, 0
	s_mov_b32 s60, 0
	s_mov_b64 s[6:7], 0
	s_mov_b32 s61, 0
	v_mov_b32_e32 v1, v0
	v_mov_b32_e32 v2, v0
	v_mov_b32_e32 v3, v0
	v_mov_b32_e32 v4, v0
	v_mov_b32_e32 v5, v0
	v_mov_b32_e32 v6, v0
	v_mov_b32_e32 v7, v0
	v_mov_b32_e32 v32, v0
	v_mov_b32_e32 v33, v0
	v_mov_b32_e32 v34, v0
	v_mov_b32_e32 v35, v0
	v_mov_b32_e32 v36, v0
	v_mov_b32_e32 v37, v0
	v_mov_b32_e32 v38, v0
	v_mov_b32_e32 v39, v0
	v_mov_b32_e32 v8, v0
	v_mov_b32_e32 v9, v0
	v_mov_b32_e32 v10, v0
	v_mov_b32_e32 v11, v0
	v_mov_b32_e32 v12, v0
	v_mov_b32_e32 v13, v0
	v_mov_b32_e32 v14, v0
	v_mov_b32_e32 v15, v0
	v_mov_b32_e32 v48, v0
	v_mov_b32_e32 v49, v0
	v_mov_b32_e32 v50, v0
	v_mov_b32_e32 v51, v0
	v_mov_b32_e32 v52, v0
	v_mov_b32_e32 v53, v0
	v_mov_b32_e32 v54, v0
	v_mov_b32_e32 v55, v0
	v_mov_b32_e32 v16, v0
	v_mov_b32_e32 v17, v0
	v_mov_b32_e32 v18, v0
	v_mov_b32_e32 v19, v0
	v_mov_b32_e32 v20, v0
	v_mov_b32_e32 v21, v0
	v_mov_b32_e32 v22, v0
	v_mov_b32_e32 v23, v0
	v_mov_b32_e32 v64, v0
	v_mov_b32_e32 v65, v0
	v_mov_b32_e32 v66, v0
	v_mov_b32_e32 v67, v0
	v_mov_b32_e32 v72, v0
	v_mov_b32_e32 v73, v0
	v_mov_b32_e32 v74, v0
	v_mov_b32_e32 v75, v0
	v_mov_b32_e32 v24, v0
	v_mov_b32_e32 v25, v0
	v_mov_b32_e32 v26, v0
	v_mov_b32_e32 v27, v0
	v_mov_b32_e32 v28, v0
	v_mov_b32_e32 v29, v0
	v_mov_b32_e32 v30, v0
	v_mov_b32_e32 v31, v0
	v_mov_b32_e32 v88, v0
	v_mov_b32_e32 v89, v0
	v_mov_b32_e32 v90, v0
	v_mov_b32_e32 v91, v0
	v_mov_b32_e32 v92, v0
	v_mov_b32_e32 v93, v0
	v_mov_b32_e32 v94, v0
	v_mov_b32_e32 v95, v0
	v_mov_b32_e32 v40, v0
	v_mov_b32_e32 v41, v0
	v_mov_b32_e32 v42, v0
	v_mov_b32_e32 v43, v0
	v_mov_b32_e32 v44, v0
	v_mov_b32_e32 v45, v0
	v_mov_b32_e32 v46, v0
	v_mov_b32_e32 v47, v0
	v_mov_b32_e32 v96, v0
	v_mov_b32_e32 v97, v0
	v_mov_b32_e32 v98, v0
	v_mov_b32_e32 v99, v0
	v_mov_b32_e32 v100, v0
	v_mov_b32_e32 v101, v0
	v_mov_b32_e32 v102, v0
	v_mov_b32_e32 v103, v0
	v_mov_b32_e32 v56, v0
	v_mov_b32_e32 v57, v0
	v_mov_b32_e32 v58, v0
	v_mov_b32_e32 v59, v0
	v_mov_b32_e32 v60, v0
	v_mov_b32_e32 v61, v0
	v_mov_b32_e32 v62, v0
; __device__ __forceinline__ void gb_step(const u16* ga, const u16* gw, size_t a64, size_t w64, int ko, bool issue, ...
;   if (issue) {
; #pragma unroll
;     for (int i = 0; i < 4; i++)
;       __builtin_amdgcn_global_load_lds((const unsigned*)(ga + i * a64 + ko), (lds_u32*)(wr + (i * 4 + wave) * 512), 16, 0, 0);
; #pragma unroll
;     for (int i = 0; i < 2; i++)
;       __builtin_amdgcn_global_load_lds((const unsigned*)(gw + i * w64 + ko), (lds_u32*)(wr + 256 * GST + (i * 4 + wave) * 512), 16, 0, 0);
;   }
;   const unsigned rdb = (unsigned)(size_t)(__attribute__((address_space(3))) const char*)rd;
;   const unsigned ab = rdb + (unsigned)(((wm * 128 + (lane & 15)) * GST + rsw) * 2);
;   const int wr0 = wn * 64 + (((lane & 15) >> 2) << 3) + (lane & 3);
;   const unsigned bb0 = rdb + (unsigned)((256 * GST + wr0 * GST + GSW(wr0, lane >> 4)) * 2);
;   const unsigned bb1 = rdb + (unsigned)((256 * GST + (wr0 + 4) * GST + GSW(wr0 + 4, lane >> 4)) * 2);
;   bf16x8 wf0, wf1, wf2, wf3, xf0, xf1, xf2, xf3, xf4, xf5, xf6, xf7;
;     ...
;   DSR(wf0, bb0, 0); DSR(wf1, bb1, 0); DSR(wf2, bb0, 2048); DSR(wf3, bb1, 2048);
;   DSR(xf0, ab, 0); DSR(xf1, ab, 1024); DSR(xf2, ab, 2048); DSR(xf3, ab, 3072);
;   DSR(xf4, ab, 4096); DSR(xf5, ab, 5120); DSR(xf6, ab, 6144); DSR(xf7, ab, 7168);
;     ...
;   asm volatile("s_waitcnt lgkmcnt(7)" : "+v"(wf0), "+v"(wf1), "+v"(wf2), "+v"(wf3), "+v"(xf0) : : "memory");
;   MM(0, xf0)
;   asm volatile("s_waitcnt lgkmcnt(6)" : "+v"(xf1) : : "memory");
;   MM(1, xf1)
;   asm volatile("s_waitcnt lgkmcnt(5)" : "+v"(xf2) : : "memory");
;   MM(2, xf2)
; template <class F>
; __device__ __forceinline__ void gemm_big(const ALbf& al, const u16* __restrict__ Wt, int K, int m0, int n0, const F& f, u16* sm) {
;     ...
; #pragma unroll
;   for (int i = 0; i < 4; i++)
; #pragma unroll
;     for (int j = 0; j < 8; j++) acc[i][j] = (f32x4){0.f, 0.f, 0.f, 0.f};
;   const int srow = lane >> 2;
;   const int scol = ((lane & 3) ^ ((0 - (srow >> 2)) & 3)) * 8;
;   const u16* ga = al.A + (size_t)(m0 + wave * 16 + srow) * al.lda + scol;
;   const u16* gw = Wt + (size_t)(n0 + wave * 16 + srow) * K + scol;
;   const size_t a64 = (size_t)64 * al.lda, w64 = (size_t)64 * K;
;   const int nk = K >> 5;
;   WAIT_V(0);
;   gb_issue(ga, gw, a64, w64, 0, sm, wave);
;   gb_issue(ga, gw, a64, w64, 32, sm + GB_STAGE_EL, wave);
;   WAIT_V(6);
;   RAW_BARRIER();
	v_mov_b32_e32 v63, v0
	v_mov_b32_e32 v104, v0
	v_mov_b32_e32 v105, v0
	v_mov_b32_e32 v106, v0
	v_mov_b32_e32 v107, v0
	v_mov_b32_e32 v108, v0
	v_mov_b32_e32 v109, v0
	v_mov_b32_e32 v110, v0
	v_mov_b32_e32 v111, v0
	v_mov_b32_e32 v68, v0
	v_mov_b32_e32 v69, v0
	v_mov_b32_e32 v70, v0
	v_mov_b32_e32 v71, v0
	v_mov_b32_e32 v76, v0
	v_mov_b32_e32 v77, v0
	v_mov_b32_e32 v78, v0
	v_mov_b32_e32 v79, v0
	v_mov_b32_e32 v112, v0
	v_mov_b32_e32 v113, v0
	v_mov_b32_e32 v114, v0
	v_mov_b32_e32 v115, v0
	v_mov_b32_e32 v116, v0
	v_mov_b32_e32 v117, v0
	v_mov_b32_e32 v118, v0
	v_mov_b32_e32 v119, v0
	v_mov_b32_e32 v80, v0
	v_mov_b32_e32 v81, v0
	v_mov_b32_e32 v82, v0
	v_mov_b32_e32 v83, v0
	v_mov_b32_e32 v84, v0
	v_mov_b32_e32 v85, v0
	v_mov_b32_e32 v86, v0
	v_mov_b32_e32 v87, v0
	v_mov_b32_e32 v120, v0
	v_mov_b32_e32 v121, v0
	v_mov_b32_e32 v122, v0
	v_mov_b32_e32 v123, v0
	v_mov_b32_e32 v124, v0
	v_mov_b32_e32 v125, v0
	v_mov_b32_e32 v126, v0
	v_mov_b32_e32 v127, v0
	v_readfirstlane_b32 s6, v130
	v_readfirstlane_b32 s7, v131
	v_readfirstlane_b32 s10, v128
	v_readfirstlane_b32 s11, v129
	v_readfirstlane_b32 s61, v134
	v_and_b32_e32 v176, 63, v132
	v_lshrrev_b32_e32 v177, 6, v132
	v_lshrrev_b32_e32 v178, 3, v176
	v_and_b32_e32 v179, 7, v176
	v_lshrrev_b32_e32 v180, 4, v176
	v_and_b32_e32 v181, 1, v177
	v_lshrrev_b32_e32 v182, 1, v177
	v_lshl_add_u32 v183, v181, 2, v180
	v_xor_b32_e32 v183, v179, v183
	v_lshl_add_u32 v184, v177, 3, v178
	v_lshlrev_b32_e32 v188, 11, v184
	v_lshl_add_u32 v128, v183, 4, v188
	v_add_u32_e32 v129, 0x10000, v128
	v_add_u32_e32 v130, 0x40000, v128
	v_add_u32_e32 v131, 0x50000, v128
	v_bfe_u32 v185, v178, 1, 1
	v_lshl_or_b32 v185, v181, 1, v185
	v_lshl_or_b32 v185, v182, 2, v185
	v_xor_b32_e32 v185, v179, v185
	v_lshl_add_u32 v134, v185, 4, v188
	v_add_u32_e32 v143, 0x10000, v134
	v_add_u32_e32 v196, 0x20000, v134
	v_add_u32_e32 v197, 0x30000, v134
	v_and_b32_e32 v186, 15, v176
	v_bfe_u32 v187, v176, 1, 3
	v_xor_b32_e32 v187, v180, v187
	v_lshlrev_b32_e32 v187, 4, v187
	v_lshl_add_u32 v188, v182, 6, v186
	v_lshl_add_u32 v219, v188, 7, v187
	v_xor_b32_e32 v228, 64, v219
	v_lshrrev_b32_e32 v189, 2, v186
	v_lshlrev_b32_e32 v189, 3, v189
	v_and_b32_e32 v188, 3, v186
	v_add_u32_e32 v189, v189, v188
	v_lshl_add_u32 v189, v181, 6, v189
	v_lshl_add_u32 v231, v189, 7, v187
	v_xor_b32_e32 v216, 64, v231
	s_lshl_b32 s13, s61, 5
	s_sub_u32 s6, s6, s13
	s_subb_u32 s7, s7, 0
	s_sub_u32 s10, s10, s13
	s_subb_u32 s11, s11, 0
	s_add_u32 m0, s61, 0x8000
	s_nop 0
	global_load_lds_dwordx4 v128, s[6:7]
	s_add_u32 m0, s61, 0x9000
	s_nop 0
	global_load_lds_dwordx4 v129, s[6:7]
	s_add_u32 m0, s61, 0xa000
	s_nop 0
	global_load_lds_dwordx4 v130, s[6:7]
	s_add_u32 m0, s61, 0xb000
	s_nop 0
	global_load_lds_dwordx4 v131, s[6:7]
	s_add_u32 s6, s6, 0x20000
	s_addc_u32 s7, s7, 0
	s_add_u32 m0, s61, 0xc000
	s_nop 0
	global_load_lds_dwordx4 v128, s[6:7]
	s_add_u32 m0, s61, 0xd000
	s_nop 0
	global_load_lds_dwordx4 v129, s[6:7]
	s_add_u32 m0, s61, 0xe000
	s_nop 0
	global_load_lds_dwordx4 v130, s[6:7]
	s_add_u32 m0, s61, 0xf000
	s_nop 0
	global_load_lds_dwordx4 v131, s[6:7]
	s_add_u32 s6, s6, 0xfffe0080
	s_addc_u32 s7, s7, -1
	s_add_u32 m0, s61, 0x0
	s_nop 0
	global_load_lds_dwordx4 v134, s[10:11]
	s_add_u32 m0, s61, 0x1000
	s_nop 0
	global_load_lds_dwordx4 v143, s[10:11]
	s_add_u32 m0, s61, 0x2000
	s_nop 0
	global_load_lds_dwordx4 v196, s[10:11]
	s_add_u32 m0, s61, 0x3000
	s_nop 0
	global_load_lds_dwordx4 v197, s[10:11]
	s_add_u32 s10, s10, 0x80
	s_addc_u32 s11, s11, 0
	s_add_u32 m0, s61, 0x4000
	s_nop 0
	global_load_lds_dwordx4 v134, s[10:11]
	s_add_u32 m0, s61, 0x5000
	s_nop 0
	global_load_lds_dwordx4 v143, s[10:11]
	s_add_u32 m0, s61, 0x6000
	s_nop 0
	global_load_lds_dwordx4 v196, s[10:11]
	s_add_u32 m0, s61, 0x7000
	s_nop 0
	global_load_lds_dwordx4 v197, s[10:11]
	s_add_u32 s10, s10, 0x80
	s_addc_u32 s11, s11, 0
	s_waitcnt vmcnt(0)
	s_barrier
	s_mov_b32 s12, 0
	s_mov_b32 s60, 0
	ds_read_b128 v[144:147], v219 offset:32768
	ds_read_b128 v[148:151], v219 offset:34816
	ds_read_b128 v[152:155], v219 offset:36864
	ds_read_b128 v[156:159], v219 offset:38912
	ds_read_b128 v[160:163], v228 offset:32768
	ds_read_b128 v[164:167], v228 offset:34816
	ds_read_b128 v[168:171], v228 offset:36864
	ds_read_b128 v[172:175], v228 offset:38912
	v_add_u32_e32 v248, s12, v231
	ds_read_b128 v[236:239], v248 offset:0
	ds_read_b128 v[240:243], v248 offset:512
	ds_read_b128 v[244:247], v248 offset:4096
	ds_read_b128 v[248:251], v248 offset:4608
	s_waitcnt lgkmcnt(0)
	s_barrier
.Lgz3_loop:
	s_cmp_lt_u32 s60, 15
	s_cselect_b64 vcc, -1, 0
	v_add_u32_e32 v212, s12, v216
	ds_read_b128 v[252:255], v212 offset:0
	ds_read_b128 v[204:207], v212 offset:512
	ds_read_b128 v[208:211], v212 offset:4096
	ds_read_b128 v[212:215], v212 offset:4608
	v_mfma_f32_16x16x32_bf16 v[124:127], v[236:239], v[144:147], v[124:127]
	ds_read_b128 v[176:179], v219 offset:49152
	v_mfma_f32_16x16x32_bf16 v[120:123], v[240:243], v[144:147], v[120:123]
	ds_read_b128 v[180:183], v219 offset:51200
	v_mfma_f32_16x16x32_bf16 v[84:87], v[244:247], v[144:147], v[84:87]
	ds_read_b128 v[184:187], v219 offset:53248
	v_mfma_f32_16x16x32_bf16 v[80:83], v[248:251], v[144:147], v[80:83]
	ds_read_b128 v[188:191], v219 offset:55296
	v_mfma_f32_16x16x32_bf16 v[116:119], v[236:239], v[148:151], v[116:119]
	ds_read_b128 v[192:195], v228 offset:49152
	v_mfma_f32_16x16x32_bf16 v[112:115], v[240:243], v[148:151], v[112:115]
	ds_read_b128 v[220:223], v228 offset:51200
	v_mfma_f32_16x16x32_bf16 v[76:79], v[244:247], v[148:151], v[76:79]
	ds_read_b128 v[224:227], v228 offset:53248
	v_mfma_f32_16x16x32_bf16 v[68:71], v[248:251], v[148:151], v[68:71]
	ds_read_b128 v[232:235], v228 offset:55296
	s_add_u32 m0, s61, 0x8000
	v_mfma_f32_16x16x32_bf16 v[108:111], v[236:239], v[152:155], v[108:111]
	s_cbranch_vccz .Lgz3_a0
	global_load_lds_dwordx4 v128, s[6:7]
; #define DSR(dst, addr, off) asm volatile("ds_read_b128 %0, %1 offset:%2" : "=v"(dst) : "v"(addr), "n"(off) : "memory")
; #define MM(j, xf)                                                                     \
;   acc[0][j] = MFMA16(wf0, xf, acc[0][j]); acc[1][j] = MFMA16(wf1, xf, acc[1][j]);      \
;   acc[2][j] = MFMA16(wf2, xf, acc[2][j]); acc[3][j] = MFMA16(wf3, xf, acc[3][j]);
; __device__ __forceinline__ void gb_step(const u16* ga, const u16* gw, size_t a64, size_t w64, int ko, bool issue, ...
;   if (issue) {
; #pragma unroll
;     for (int i = 0; i < 4; i++)
;       __builtin_amdgcn_global_load_lds((const unsigned*)(ga + i * a64 + ko), (lds_u32*)(wr + (i * 4 + wave) * 512), 16, 0, 0);
; #pragma unroll
;     for (int i = 0; i < 2; i++)
;       __builtin_amdgcn_global_load_lds((const unsigned*)(gw + i * w64 + ko), (lds_u32*)(wr + 256 * GST + (i * 4 + wave) * 512), 16, 0, 0);
;   }
;   const unsigned rdb = (unsigned)(size_t)(__attribute__((address_space(3))) const char*)rd;
;   const unsigned ab = rdb + (unsigned)(((wm * 128 + (lane & 15)) * GST + rsw) * 2);
;   const int wr0 = wn * 64 + (((lane & 15) >> 2) << 3) + (lane & 3);
;   const unsigned bb0 = rdb + (unsigned)((256 * GST + wr0 * GST + GSW(wr0, lane >> 4)) * 2);
;   const unsigned bb1 = rdb + (unsigned)((256 * GST + (wr0 + 4) * GST + GSW(wr0 + 4, lane >> 4)) * 2);
;   bf16x8 wf0, wf1, wf2, wf3, xf0, xf1, xf2, xf3, xf4, xf5, xf6, xf7;
;     ...
;   DSR(wf0, bb0, 0); DSR(wf1, bb1, 0); DSR(wf2, bb0, 2048); DSR(wf3, bb1, 2048);
;   DSR(xf0, ab, 0); DSR(xf1, ab, 1024); DSR(xf2, ab, 2048); DSR(xf3, ab, 3072);
;   DSR(xf4, ab, 4096); DSR(xf5, ab, 5120); DSR(xf6, ab, 6144); DSR(xf7, ab, 7168);
;     ...
;   asm volatile("s_waitcnt lgkmcnt(7)" : "+v"(wf0), "+v"(wf1), "+v"(wf2), "+v"(wf3), "+v"(xf0) : : "memory");
;   MM(0, xf0)
;   asm volatile("s_waitcnt lgkmcnt(6)" : "+v"(xf1) : : "memory");
;   MM(1, xf1)
;   asm volatile("s_waitcnt lgkmcnt(5)" : "+v"(xf2) : : "memory");
;   MM(2, xf2)
;   asm volatile("s_waitcnt lgkmcnt(4)" : "+v"(xf3) : : "memory");
;   MM(3, xf3)
;   asm volatile("s_waitcnt lgkmcnt(3)" : "+v"(xf4) : : "memory");
;   MM(4, xf4)
;   asm volatile("s_waitcnt lgkmcnt(2)" : "+v"(xf5) : : "memory");
;   MM(5, xf5)
;   asm volatile("s_waitcnt lgkmcnt(1)" : "+v"(xf6) : : "memory");
;   MM(6, xf6)
;   asm volatile("s_waitcnt lgkmcnt(0)" : "+v"(xf7) : : "memory");
;   MM(7, xf7)
.Lgz3_a0:
	v_mfma_f32_16x16x32_bf16 v[104:107], v[240:243], v[152:155], v[104:107]
	s_add_u32 m0, s61, 0x9000
	v_mfma_f32_16x16x32_bf16 v[60:63], v[244:247], v[152:155], v[60:63]
	s_cbranch_vccz .Lgz3_a1
	global_load_lds_dwordx4 v129, s[6:7]
.Lgz3_a1:
	v_mfma_f32_16x16x32_bf16 v[56:59], v[248:251], v[152:155], v[56:59]
	s_add_u32 m0, s61, 0xa000
	v_mfma_f32_16x16x32_bf16 v[100:103], v[236:239], v[156:159], v[100:103]
	s_cbranch_vccz .Lgz3_a2
	global_load_lds_dwordx4 v130, s[6:7]
.Lgz3_a2:
	v_mfma_f32_16x16x32_bf16 v[96:99], v[240:243], v[156:159], v[96:99]
	s_add_u32 m0, s61, 0xb000
	v_mfma_f32_16x16x32_bf16 v[44:47], v[244:247], v[156:159], v[44:47]
	s_cbranch_vccz .Lgz3_a3
	global_load_lds_dwordx4 v131, s[6:7]
.Lgz3_a3:
	v_mfma_f32_16x16x32_bf16 v[40:43], v[248:251], v[156:159], v[40:43]
	s_waitcnt lgkmcnt(8)
	v_mfma_f32_16x16x32_bf16 v[124:127], v[252:255], v[160:163], v[124:127]
	v_mfma_f32_16x16x32_bf16 v[120:123], v[204:207], v[160:163], v[120:123]
	v_mfma_f32_16x16x32_bf16 v[84:87], v[208:211], v[160:163], v[84:87]
	v_mfma_f32_16x16x32_bf16 v[80:83], v[212:215], v[160:163], v[80:83]
	v_mfma_f32_16x16x32_bf16 v[116:119], v[252:255], v[164:167], v[116:119]
	v_mfma_f32_16x16x32_bf16 v[112:115], v[204:207], v[164:167], v[112:115]
	v_mfma_f32_16x16x32_bf16 v[76:79], v[208:211], v[164:167], v[76:79]
	v_mfma_f32_16x16x32_bf16 v[68:71], v[212:215], v[164:167], v[68:71]
	v_mfma_f32_16x16x32_bf16 v[108:111], v[252:255], v[168:171], v[108:111]
	v_mfma_f32_16x16x32_bf16 v[104:107], v[204:207], v[168:171], v[104:107]
	v_mfma_f32_16x16x32_bf16 v[60:63], v[208:211], v[168:171], v[60:63]
	v_mfma_f32_16x16x32_bf16 v[56:59], v[212:215], v[168:171], v[56:59]
	v_mfma_f32_16x16x32_bf16 v[100:103], v[252:255], v[172:175], v[100:103]
	v_mfma_f32_16x16x32_bf16 v[96:99], v[204:207], v[172:175], v[96:99]
	v_mfma_f32_16x16x32_bf16 v[44:47], v[208:211], v[172:175], v[44:47]
	v_mfma_f32_16x16x32_bf16 v[40:43], v[212:215], v[172:175], v[40:43]
	s_waitcnt vmcnt(0)
	s_waitcnt lgkmcnt(0)
	s_add_u32 s6, s6, 0x20000
	s_addc_u32 s7, s7, 0
	s_xor_b32 s13, s12, 0x4000
	s_barrier
	v_mfma_f32_16x16x32_bf16 v[92:95], v[236:239], v[176:179], v[92:95]
	ds_read_b128 v[144:147], v219 offset:32768
	v_mfma_f32_16x16x32_bf16 v[88:91], v[240:243], v[176:179], v[88:91]
	ds_read_b128 v[148:151], v219 offset:34816
	v_mfma_f32_16x16x32_bf16 v[28:31], v[244:247], v[176:179], v[28:31]
	ds_read_b128 v[152:155], v219 offset:36864
	v_mfma_f32_16x16x32_bf16 v[24:27], v[248:251], v[176:179], v[24:27]
	ds_read_b128 v[156:159], v219 offset:38912
	v_mfma_f32_16x16x32_bf16 v[72:75], v[236:239], v[180:183], v[72:75]
	ds_read_b128 v[160:163], v228 offset:32768
	v_mfma_f32_16x16x32_bf16 v[64:67], v[240:243], v[180:183], v[64:67]
	ds_read_b128 v[164:167], v228 offset:34816
	v_mfma_f32_16x16x32_bf16 v[20:23], v[244:247], v[180:183], v[20:23]
	ds_read_b128 v[168:171], v228 offset:36864
	v_mfma_f32_16x16x32_bf16 v[16:19], v[248:251], v[180:183], v[16:19]
	ds_read_b128 v[172:175], v228 offset:38912
	s_add_u32 m0, s61, 0xc000
	v_mfma_f32_16x16x32_bf16 v[52:55], v[236:239], v[184:187], v[52:55]
	s_cbranch_vccz .Lgz3_b0
	global_load_lds_dwordx4 v128, s[6:7]
.Lgz3_b0:
	v_mfma_f32_16x16x32_bf16 v[48:51], v[240:243], v[184:187], v[48:51]
	s_add_u32 m0, s61, 0xd000
	v_mfma_f32_16x16x32_bf16 v[12:15], v[244:247], v[184:187], v[12:15]
	s_cbranch_vccz .Lgz3_b1
	global_load_lds_dwordx4 v129, s[6:7]
.Lgz3_b1:
	v_mfma_f32_16x16x32_bf16 v[8:11], v[248:251], v[184:187], v[8:11]
	s_add_u32 m0, s61, 0xe000
	v_mfma_f32_16x16x32_bf16 v[36:39], v[236:239], v[188:191], v[36:39]
	s_cbranch_vccz .Lgz3_b2
	global_load_lds_dwordx4 v130, s[6:7]
.Lgz3_b2:
	v_mfma_f32_16x16x32_bf16 v[32:35], v[240:243], v[188:191], v[32:35]
	s_add_u32 m0, s61, 0xf000
	v_mfma_f32_16x16x32_bf16 v[4:7], v[244:247], v[188:191], v[4:7]
	s_cbranch_vccz .Lgz3_b3
	global_load_lds_dwordx4 v131, s[6:7]
.Lgz3_b3:
	v_mfma_f32_16x16x32_bf16 v[0:3], v[248:251], v[188:191], v[0:3]
	v_add_u32_e32 v248, s13, v231
	v_mfma_f32_16x16x32_bf16 v[92:95], v[252:255], v[192:195], v[92:95]
	ds_read_b128 v[236:239], v248 offset:0
	v_mfma_f32_16x16x32_bf16 v[88:91], v[204:207], v[192:195], v[88:91]
	ds_read_b128 v[240:243], v248 offset:512
	v_mfma_f32_16x16x32_bf16 v[28:31], v[208:211], v[192:195], v[28:31]
	ds_read_b128 v[244:247], v248 offset:4096
	v_mfma_f32_16x16x32_bf16 v[24:27], v[212:215], v[192:195], v[24:27]
	ds_read_b128 v[248:251], v248 offset:4608
	v_mfma_f32_16x16x32_bf16 v[72:75], v[252:255], v[220:223], v[72:75]
	v_mfma_f32_16x16x32_bf16 v[64:67], v[204:207], v[220:223], v[64:67]
	s_cmp_lt_u32 s60, 14
	s_cbranch_scc0 .Lgz3_w0
	s_add_u32 m0, s61, s12
	s_add_u32 m0, m0, 0x0
	s_nop 0
	global_load_lds_dwordx4 v134, s[10:11]
.Lgz3_w0:
	v_mfma_f32_16x16x32_bf16 v[20:23], v[208:211], v[220:223], v[20:23]
	v_mfma_f32_16x16x32_bf16 v[16:19], v[212:215], v[220:223], v[16:19]
	s_cmp_lt_u32 s60, 14
	s_cbranch_scc0 .Lgz3_w1
	s_add_u32 m0, s61, s12
	s_add_u32 m0, m0, 0x1000
	s_nop 0
	global_load_lds_dwordx4 v143, s[10:11]
.Lgz3_w1:
	v_mfma_f32_16x16x32_bf16 v[52:55], v[252:255], v[224:227], v[52:55]
	v_mfma_f32_16x16x32_bf16 v[48:51], v[204:207], v[224:227], v[48:51]
	s_cmp_lt_u32 s60, 14
	s_cbranch_scc0 .Lgz3_w2
	s_add_u32 m0, s61, s12
	s_add_u32 m0, m0, 0x2000
	s_nop 0
	global_load_lds_dwordx4 v196, s[10:11]
.Lgz3_w2:
	v_mfma_f32_16x16x32_bf16 v[12:15], v[208:211], v[224:227], v[12:15]
	v_mfma_f32_16x16x32_bf16 v[8:11], v[212:215], v[224:227], v[8:11]
	s_cmp_lt_u32 s60, 14
	s_cbranch_scc0 .Lgz3_w3
	s_add_u32 m0, s61, s12
	s_add_u32 m0, m0, 0x3000
	s_nop 0
	global_load_lds_dwordx4 v197, s[10:11]
.Lgz3_w3:
	v_mfma_f32_16x16x32_bf16 v[36:39], v[252:255], v[232:235], v[36:39]
	v_mfma_f32_16x16x32_bf16 v[32:35], v[204:207], v[232:235], v[32:35]
	v_mfma_f32_16x16x32_bf16 v[4:7], v[208:211], v[232:235], v[4:7]
	v_mfma_f32_16x16x32_bf16 v[0:3], v[212:215], v[232:235], v[0:3]
	s_cmp_lt_u32 s60, 14
	s_cbranch_scc0 .Lgz3_v0
	s_waitcnt vmcnt(4)
	s_branch .Lgz3_vj

; #define WAIT_V(n) asm volatile("s_waitcnt vmcnt(%0)" ::"n"(n) : "memory")
; #define RAW_BARRIER() do { asm volatile("s_waitcnt lgkmcnt(0)" ::: "memory"); __builtin_amdgcn_s_barrier(); } while (0)
; template <class F>
; __device__ __forceinline__ void gemm_big(const ALbf& al, const u16* __restrict__ Wt, int K, int m0, int n0, const F& f, u16* sm) {
;     ...
;   for (int kt = 0; kt < nk; ++kt) {
;     const int nxt2 = (cur >= 1) ? cur - 1 : 2;
;     gb_step(ga, gw, a64, w64, (kt + 2) * 32, kt + 2 < nk, sm + cur * GB_STAGE_EL, sm + nxt2 * GB_STAGE_EL, wave, wm, wn, lane, rsw, acc);
;     if (kt + 2 < nk) WAIT_V(6); else WAIT_V(0);
;     RAW_BARRIER();
;     cur = (cur == 2) ? 0 : cur + 1;
;   }
.Lgz3_vj:
	s_waitcnt lgkmcnt(0)
	s_add_u32 s6, s6, 0xfffe0080
	s_addc_u32 s7, s7, -1
	s_add_u32 s10, s10, 0x80
	s_addc_u32 s11, s11, 0
	s_mov_b32 s12, s13
	s_add_u32 s60, s60, 1
	s_cmp_lt_u32 s60, 16
	s_barrier
	s_cbranch_scc1 .Lgz3_loop
	v_mov_b32_e32 v204, 0x3ab69700
	v_mov_b32_e32 v205, 0xffffea00
	v_mov_b32_e32 v206, 0x41b17218
	v_mov_b32_e32 v207, 0xd000
	v_mov_b32_e32 v208, 0xf00
	v_mov_b32_e32 v209, 0x7f800000
	v_mov_b32_e32 v210, 0xffffffc0
	v_mov_b32_e32 v211, 0xffffffe0
	v_mov_b32_e32 v212, 0x7fc00000
	v_mov_b32_e32 v213, 0xac00
	v_mov_b32_e32 v214, 0x800
	v_mov_b32_e32 v215, 0x140
	v_mov_b32_e32 v216, 0x130
	s_nop 7
	s_branch .LBB0_256

; __device__ __forceinline__ int ltid() { int t = threadIdx.x; asm volatile("" : "+v"(t)); return t; }
; #define WAIT_V(n) asm volatile("s_waitcnt vmcnt(%0)" ::"n"(n) : "memory")
; #define RAW_BARRIER() do { asm volatile("s_waitcnt lgkmcnt(0)" ::: "memory"); __builtin_amdgcn_s_barrier(); } while (0)
; __device__ __forceinline__ void gb_issue(const u16* ga, const u16* gw, size_t a64, size_t w64, int ko, u16* __restrict__ wr, int wave) {
; #pragma unroll
;   for (int i = 0; i < 4; i++)
;     __builtin_amdgcn_global_load_lds((const unsigned*)(ga + i * a64 + ko), (lds_u32*)(wr + (i * 4 + wave) * 512), 16, 0, 0);
; #pragma unroll
;   for (int i = 0; i < 2; i++)
;     __builtin_amdgcn_global_load_lds((const unsigned*)(gw + i * w64 + ko), (lds_u32*)(wr + 256 * GST + (i * 4 + wave) * 512), 16, 0, 0);
; }
; template <class F>
; __device__ __forceinline__ void gemm_big(const ALbf& al, const u16* __restrict__ Wt, int K, int m0, int n0, const F& f, u16* sm) {
;   const int tid = ltid(), lane = tid & 63, wave = tid >> 6;
;   const int wm = wave >> 1, wn = wave & 1;
;   const int rsw = GSW(lane & 15, lane >> 4);
;   f32x4 acc[4][8];
; #pragma unroll
;   for (int i = 0; i < 4; i++)
; #pragma unroll
;     for (int j = 0; j < 8; j++) acc[i][j] = (f32x4){0.f, 0.f, 0.f, 0.f};
;   const int srow = lane >> 2;
;   const int scol = ((lane & 3) ^ ((0 - (srow >> 2)) & 3)) * 8;
;   const u16* ga = al.A + (size_t)(m0 + wave * 16 + srow) * al.lda + scol;
;   const u16* gw = Wt + (size_t)(n0 + wave * 16 + srow) * K + scol;
;   const size_t a64 = (size_t)64 * al.lda, w64 = (size_t)64 * K;
;   const int nk = K >> 5;
;   WAIT_V(0);
;   gb_issue(ga, gw, a64, w64, 0, sm, wave);
;   gb_issue(ga, gw, a64, w64, 32, sm + GB_STAGE_EL, wave);
;   WAIT_V(6);
;   RAW_BARRIER();
.LBB0_279:
	v_mov_b32_e32 v138, v132
	s_lshl_b32 s8, s13, 8
	v_lshrrev_b32_e32 v0, 2, v138
	v_bfe_u32 v140, v138, 4, 2
	v_sub_u32_e32 v0, 0, v0
	v_bitop3_b32 v0, v140, v0, 3 bitop3:0x78
	v_lshlrev_b32_e32 v6, 4, v0
	v_lshrrev_b32_e32 v0, 4, v138
	v_ashrrev_i32_e32 v4, 6, v138
	v_sub_u32_e32 v8, 0, v0
	s_and_b32 s15, s8, 0x3f00
	s_lshl_b32 s8, s13, 1
	v_bfe_u32 v7, v138, 2, 4
	v_xor_b32_e32 v2, v138, v8
	v_lshlrev_b32_e32 v9, 4, v4
	s_load_dwordx16 s[60:75], s[0:1], 0x160
	s_and_b32 s14, s8, 0xffffff80
	v_or_b32_e32 v3, v7, v9
	v_lshlrev_b32_e32 v2, 4, v2
	v_add_u32_e32 v0, s15, v3
	v_and_b32_e32 v134, 48, v2
	v_add_u32_e32 v2, s14, v3
	v_ashrrev_i32_e32 v1, 31, v0
	v_ashrrev_i32_e32 v3, 31, v2
	v_lshlrev_b64 v[0:1], 11, v[0:1]
	v_lshlrev_b64 v[2:3], 11, v[2:3]
	s_waitcnt lgkmcnt(0)
	v_lshl_add_u64 v[0:1], s[30:31], 0, v[0:1]
	v_lshl_add_u64 v[2:3], s[62:63], 0, v[2:3]
	v_lshl_add_u64 v[0:1], v[0:1], 0, v[134:135]
	v_lshl_add_u64 v[2:3], v[2:3], 0, v[134:135]
	v_lshlrev_b32_e32 v134, 10, v4
	v_add_u32_e32 v10, 0x1000, v134
	v_readfirstlane_b32 s8, v134
	s_waitcnt vmcnt(0)
	s_mov_b32 m0, s8
	v_readfirstlane_b32 s8, v10
	v_add_u32_e32 v10, 0x2000, v134
	v_lshl_add_u64 v[4:5], v[0:1], 0, s[96:97]
	s_mov_b32 m0, s8
	v_readfirstlane_b32 s8, v10
	v_lshl_add_u64 v[4:5], v[0:1], 0, s[86:87]
	s_mov_b32 m0, s8
	s_mov_b64 s[8:9], 0x60000
	v_add_u32_e32 v10, 0x3000, v134
	v_lshl_add_u64 v[4:5], v[0:1], 0, s[8:9]
	v_readfirstlane_b32 s8, v10
	s_mov_b32 m0, s8
	v_add_u32_e32 v10, 0x5000, v134
	v_add_u32_e32 v4, 0x4000, v134
	s_mov_b64 s[10:11], 0x20040
	v_readfirstlane_b32 s8, v4
	s_mov_b32 m0, s8
	v_readfirstlane_b32 s8, v10
	v_add_u32_e32 v10, 0x6000, v134
	v_lshl_add_u64 v[4:5], v[2:3], 0, s[96:97]
	s_mov_b32 m0, s8
	v_readfirstlane_b32 s8, v10
	v_add_u32_e32 v10, 0x7000, v134
	v_lshl_add_u64 v[4:5], v[0:1], 0, 64
	s_mov_b32 m0, s8
	v_readfirstlane_b32 s8, v10
	v_lshl_add_u64 v[4:5], v[0:1], 0, s[10:11]
	s_mov_b32 m0, s8
	s_mov_b64 s[8:9], 0x40040
	v_add_u32_e32 v10, 0x8000, v134
	v_lshl_add_u64 v[4:5], v[0:1], 0, s[8:9]
	v_readfirstlane_b32 s8, v10
	s_mov_b32 m0, s8
	s_mov_b64 s[8:9], 0x60040
	v_add_u32_e32 v4, 0x9000, v134
	v_lshl_add_u64 v[0:1], v[0:1], 0, s[8:9]
	v_readfirstlane_b32 s8, v4
	v_add_u32_e32 v4, 0xa000, v134
	s_mov_b32 m0, s8
	v_readfirstlane_b32 s8, v4
	v_lshl_add_u64 v[0:1], v[2:3], 0, 64
	s_mov_b32 m0, s8
	s_and_b32 s6, s4, 0xffffff80
	v_lshl_add_u64 v[0:1], v[2:3], 0, s[10:11]
	v_add_u32_e32 v2, 0xb000, v134
	s_and_b32 s7, s12, 0x3f00
	v_readfirstlane_b32 s8, v2
	s_mov_b32 m0, s8
	v_bitop3_b32 v2, v138, 3, v8 bitop3:0x48
	v_lshlrev_b32_e32 v0, 6, v138
	v_and_or_b32 v143, v0, s80, v6
	v_lshlrev_b32_e32 v0, 1, v138
	v_and_b32_e32 v1, 0x43, v138
	v_and_or_b32 v0, v0, 24, v1
	v_lshrrev_b32_e32 v1, 1, v138
	v_and_b32_e32 v1, 2, v1
	v_sub_u32_e32 v1, 0, v1
	v_bitop3_b32 v1, v1, v140, 2 bitop3:0x6c
	v_lshlrev_b32_e32 v1, 4, v1
	v_lshl_or_b32 v144, v0, 6, v1
	v_or_b32_e32 v0, 4, v0
	v_lshlrev_b32_e32 v1, 6, v0
	v_lshrrev_b32_e32 v0, 2, v0
	v_sub_u32_e32 v0, 0, v0
	v_bitop3_b32 v0, v0, v140, 3 bitop3:0x6c
	v_lshl_or_b32 v145, v0, 4, v1
	v_or_b32_e32 v0, s6, v7
	v_add_u32_e32 v0, v0, v9
	v_ashrrev_i32_e32 v1, 31, v0
	v_lshlrev_b64 v[0:1], 11, v[0:1]
	v_lshlrev_b32_e32 v2, 4, v2
	v_or_b32_e32 v0, v0, v2
	v_lshl_add_u64 v[128:129], s[62:63], 0, v[0:1]
	v_or_b32_e32 v0, s7, v7
	v_add_u32_e32 v0, v0, v9
	v_ashrrev_i32_e32 v1, 31, v0
	s_waitcnt vmcnt(6)
	v_lshlrev_b64 v[0:1], 11, v[0:1]
	s_waitcnt lgkmcnt(0)
	v_or_b32_e32 v0, v0, v2
	v_lshl_add_u64 v[130:131], s[30:31], 0, v[0:1]
	v_mov_b32_e32 v0, 0
	s_mov_b32 s16, 0
	s_mov_b64 s[6:7], 0
	s_mov_b32 s17, 0
	v_mov_b32_e32 v1, v0
	v_mov_b32_e32 v2, v0
	v_mov_b32_e32 v3, v0
	v_mov_b32_e32 v4, v0
	v_mov_b32_e32 v5, v0
	v_mov_b32_e32 v6, v0
	v_mov_b32_e32 v7, v0
	v_mov_b32_e32 v32, v0
	v_mov_b32_e32 v33, v0
	v_mov_b32_e32 v34, v0
	v_mov_b32_e32 v35, v0
	v_mov_b32_e32 v36, v0
	v_mov_b32_e32 v37, v0
	v_mov_b32_e32 v38, v0
	v_mov_b32_e32 v39, v0
	v_mov_b32_e32 v8, v0
	v_mov_b32_e32 v9, v0
	v_mov_b32_e32 v10, v0
	v_mov_b32_e32 v11, v0
	v_mov_b32_e32 v12, v0
	v_mov_b32_e32 v13, v0
	v_mov_b32_e32 v14, v0
	v_mov_b32_e32 v15, v0
	v_mov_b32_e32 v48, v0
	v_mov_b32_e32 v49, v0
	v_mov_b32_e32 v50, v0
	v_mov_b32_e32 v51, v0
	v_mov_b32_e32 v52, v0
	v_mov_b32_e32 v53, v0
	v_mov_b32_e32 v54, v0
	v_mov_b32_e32 v55, v0
	v_mov_b32_e32 v16, v0
	v_mov_b32_e32 v17, v0
	v_mov_b32_e32 v18, v0
	v_mov_b32_e32 v19, v0
	v_mov_b32_e32 v20, v0
	v_mov_b32_e32 v21, v0
	v_mov_b32_e32 v22, v0
	v_mov_b32_e32 v23, v0
	v_mov_b32_e32 v64, v0
	v_mov_b32_e32 v65, v0
	v_mov_b32_e32 v66, v0
	v_mov_b32_e32 v67, v0
	v_mov_b32_e32 v72, v0
	v_mov_b32_e32 v73, v0
	v_mov_b32_e32 v74, v0
	v_mov_b32_e32 v75, v0
	v_mov_b32_e32 v24, v0
	v_mov_b32_e32 v25, v0
	v_mov_b32_e32 v26, v0
	v_mov_b32_e32 v27, v0
	v_mov_b32_e32 v28, v0
	v_mov_b32_e32 v29, v0
	v_mov_b32_e32 v30, v0
	v_mov_b32_e32 v31, v0
	v_mov_b32_e32 v88, v0
	v_mov_b32_e32 v89, v0
	v_mov_b32_e32 v90, v0
	v_mov_b32_e32 v91, v0
	v_mov_b32_e32 v92, v0
	v_mov_b32_e32 v93, v0
	v_mov_b32_e32 v94, v0
	v_mov_b32_e32 v95, v0
	v_mov_b32_e32 v40, v0
	v_mov_b32_e32 v41, v0
	v_mov_b32_e32 v42, v0
	v_mov_b32_e32 v43, v0
	v_mov_b32_e32 v44, v0
	v_mov_b32_e32 v45, v0
	v_mov_b32_e32 v46, v0
	v_mov_b32_e32 v47, v0
	v_mov_b32_e32 v96, v0
	v_mov_b32_e32 v97, v0
	v_mov_b32_e32 v98, v0
	v_mov_b32_e32 v99, v0
	v_mov_b32_e32 v100, v0
	v_mov_b32_e32 v101, v0
	v_mov_b32_e32 v102, v0
	v_mov_b32_e32 v103, v0
	v_mov_b32_e32 v56, v0
	v_mov_b32_e32 v57, v0
	v_mov_b32_e32 v58, v0
	v_mov_b32_e32 v59, v0
	v_mov_b32_e32 v60, v0
	v_mov_b32_e32 v61, v0
	v_mov_b32_e32 v62, v0
	v_mov_b32_e32 v63, v0
	v_mov_b32_e32 v104, v0
; __device__ __forceinline__ void gb_step(const u16* ga, const u16* gw, size_t a64, size_t w64, int ko, bool issue, ...
;   if (issue) {
; #pragma unroll
;     for (int i = 0; i < 4; i++)
;       __builtin_amdgcn_global_load_lds((const unsigned*)(ga + i * a64 + ko), (lds_u32*)(wr + (i * 4 + wave) * 512), 16, 0, 0);
; #pragma unroll
;     for (int i = 0; i < 2; i++)
;       __builtin_amdgcn_global_load_lds((const unsigned*)(gw + i * w64 + ko), (lds_u32*)(wr + 256 * GST + (i * 4 + wave) * 512), 16, 0, 0);
;   }
;   const unsigned rdb = (unsigned)(size_t)(__attribute__((address_space(3))) const char*)rd;
;   const unsigned ab = rdb + (unsigned)(((wm * 128 + (lane & 15)) * GST + rsw) * 2);
;   const int wr0 = wn * 64 + (((lane & 15) >> 2) << 3) + (lane & 3);
;   const unsigned bb0 = rdb + (unsigned)((256 * GST + wr0 * GST + GSW(wr0, lane >> 4)) * 2);
;   const unsigned bb1 = rdb + (unsigned)((256 * GST + (wr0 + 4) * GST + GSW(wr0 + 4, lane >> 4)) * 2);
;   bf16x8 wf0, wf1, wf2, wf3, xf0, xf1, xf2, xf3, xf4, xf5, xf6, xf7;
;     ...
;   DSR(wf0, bb0, 0); DSR(wf1, bb1, 0); DSR(wf2, bb0, 2048); DSR(wf3, bb1, 2048);
;   DSR(xf0, ab, 0); DSR(xf1, ab, 1024); DSR(xf2, ab, 2048); DSR(xf3, ab, 3072);
;   DSR(xf4, ab, 4096); DSR(xf5, ab, 5120); DSR(xf6, ab, 6144); DSR(xf7, ab, 7168);
;     ...
;   asm volatile("s_waitcnt lgkmcnt(7)" : "+v"(wf0), "+v"(wf1), "+v"(wf2), "+v"(wf3), "+v"(xf0) : : "memory");
;   MM(0, xf0)
;   asm volatile("s_waitcnt lgkmcnt(6)" : "+v"(xf1) : : "memory");
;   MM(1, xf1)
;   asm volatile("s_waitcnt lgkmcnt(5)" : "+v"(xf2) : : "memory");
;   MM(2, xf2)
; template <class F>
; __device__ __forceinline__ void gemm_big(const ALbf& al, const u16* __restrict__ Wt, int K, int m0, int n0, const F& f, u16* sm) {
;     ...
; #pragma unroll
;   for (int i = 0; i < 4; i++)
; #pragma unroll
;     for (int j = 0; j < 8; j++) acc[i][j] = (f32x4){0.f, 0.f, 0.f, 0.f};
;   const int srow = lane >> 2;
;   const int scol = ((lane & 3) ^ ((0 - (srow >> 2)) & 3)) * 8;
;   const u16* ga = al.A + (size_t)(m0 + wave * 16 + srow) * al.lda + scol;
;   const u16* gw = Wt + (size_t)(n0 + wave * 16 + srow) * K + scol;
;   const size_t a64 = (size_t)64 * al.lda, w64 = (size_t)64 * K;
;   const int nk = K >> 5;
;   WAIT_V(0);
;   gb_issue(ga, gw, a64, w64, 0, sm, wave);
;   gb_issue(ga, gw, a64, w64, 32, sm + GB_STAGE_EL, wave);
;   WAIT_V(6);
;   RAW_BARRIER();
	v_mov_b32_e32 v105, v0
	v_mov_b32_e32 v106, v0
	v_mov_b32_e32 v107, v0
	v_mov_b32_e32 v108, v0
	v_mov_b32_e32 v109, v0
	v_mov_b32_e32 v110, v0
	v_mov_b32_e32 v111, v0
	v_mov_b32_e32 v68, v0
	v_mov_b32_e32 v69, v0
	v_mov_b32_e32 v70, v0
	v_mov_b32_e32 v71, v0
	v_mov_b32_e32 v76, v0
	v_mov_b32_e32 v77, v0
	v_mov_b32_e32 v78, v0
	v_mov_b32_e32 v79, v0
	v_mov_b32_e32 v112, v0
	v_mov_b32_e32 v113, v0
	v_mov_b32_e32 v114, v0
	v_mov_b32_e32 v115, v0
	v_mov_b32_e32 v116, v0
	v_mov_b32_e32 v117, v0
	v_mov_b32_e32 v118, v0
	v_mov_b32_e32 v119, v0
	v_mov_b32_e32 v80, v0
	v_mov_b32_e32 v81, v0
	v_mov_b32_e32 v82, v0
	v_mov_b32_e32 v83, v0
	v_mov_b32_e32 v84, v0
	v_mov_b32_e32 v85, v0
	v_mov_b32_e32 v86, v0
	v_mov_b32_e32 v87, v0
	v_mov_b32_e32 v120, v0
	v_mov_b32_e32 v121, v0
	v_mov_b32_e32 v122, v0
	v_mov_b32_e32 v123, v0
	v_mov_b32_e32 v124, v0
	v_mov_b32_e32 v125, v0
	v_mov_b32_e32 v126, v0
	v_mov_b32_e32 v127, v0
	v_readfirstlane_b32 s6, v130
	v_readfirstlane_b32 s7, v131
	v_readfirstlane_b32 s8, v128
	v_readfirstlane_b32 s9, v129
	v_readfirstlane_b32 s17, v134
	v_and_b32_e32 v176, 63, v132
	v_lshrrev_b32_e32 v177, 6, v132
	v_lshrrev_b32_e32 v178, 3, v176
	v_and_b32_e32 v179, 7, v176
	v_lshrrev_b32_e32 v180, 4, v176
	v_and_b32_e32 v181, 1, v177
	v_lshrrev_b32_e32 v182, 1, v177
	v_lshl_add_u32 v183, v181, 2, v180
	v_xor_b32_e32 v183, v179, v183
	v_lshl_add_u32 v184, v177, 3, v178
	v_lshlrev_b32_e32 v188, 11, v184
	v_lshl_add_u32 v128, v183, 4, v188
	v_add_u32_e32 v129, 0x10000, v128
	v_add_u32_e32 v130, 0x40000, v128
	v_add_u32_e32 v131, 0x50000, v128
	v_bfe_u32 v185, v178, 1, 1
	v_lshl_or_b32 v185, v181, 1, v185
	v_lshl_or_b32 v185, v182, 2, v185
	v_xor_b32_e32 v185, v179, v185
	v_lshl_add_u32 v134, v185, 4, v188
	v_add_u32_e32 v143, 0x10000, v134
	v_add_u32_e32 v196, 0x20000, v134
	v_add_u32_e32 v197, 0x30000, v134
	v_and_b32_e32 v186, 15, v176
	v_bfe_u32 v187, v176, 1, 3
	v_xor_b32_e32 v187, v180, v187
	v_lshlrev_b32_e32 v187, 4, v187
	v_lshl_add_u32 v188, v182, 6, v186
	v_lshl_add_u32 v219, v188, 7, v187
	v_xor_b32_e32 v228, 64, v219
	v_lshrrev_b32_e32 v189, 2, v186
	v_lshlrev_b32_e32 v189, 3, v189
	v_and_b32_e32 v188, 3, v186
	v_add_u32_e32 v189, v189, v188
	v_lshl_add_u32 v189, v181, 6, v189
	v_lshl_add_u32 v231, v189, 7, v187
	v_xor_b32_e32 v216, 64, v231
	s_lshl_b32 s11, s17, 5
	s_sub_u32 s6, s6, s11
	s_subb_u32 s7, s7, 0
	s_sub_u32 s8, s8, s11
	s_subb_u32 s9, s9, 0
	s_add_u32 m0, s17, 0x8000
	s_nop 0
	global_load_lds_dwordx4 v128, s[6:7]
	s_add_u32 m0, s17, 0x9000
	s_nop 0
	global_load_lds_dwordx4 v129, s[6:7]
	s_add_u32 m0, s17, 0xa000
	s_nop 0
	global_load_lds_dwordx4 v130, s[6:7]
	s_add_u32 m0, s17, 0xb000
	s_nop 0
	global_load_lds_dwordx4 v131, s[6:7]
	s_add_u32 s6, s6, 0x20000
	s_addc_u32 s7, s7, 0
	s_add_u32 m0, s17, 0xc000
	s_nop 0
	global_load_lds_dwordx4 v128, s[6:7]
	s_add_u32 m0, s17, 0xd000
	s_nop 0
	global_load_lds_dwordx4 v129, s[6:7]
	s_add_u32 m0, s17, 0xe000
	s_nop 0
	global_load_lds_dwordx4 v130, s[6:7]
	s_add_u32 m0, s17, 0xf000
	s_nop 0
	global_load_lds_dwordx4 v131, s[6:7]
	s_add_u32 s6, s6, 0xfffe0080
	s_addc_u32 s7, s7, -1
	s_add_u32 m0, s17, 0x0
	s_nop 0
	global_load_lds_dwordx4 v134, s[8:9]
	s_add_u32 m0, s17, 0x1000
	s_nop 0
	global_load_lds_dwordx4 v143, s[8:9]
	s_add_u32 m0, s17, 0x2000
	s_nop 0
	global_load_lds_dwordx4 v196, s[8:9]
	s_add_u32 m0, s17, 0x3000
	s_nop 0
	global_load_lds_dwordx4 v197, s[8:9]
	s_add_u32 s8, s8, 0x80
	s_addc_u32 s9, s9, 0
	s_add_u32 m0, s17, 0x4000
	s_nop 0
	global_load_lds_dwordx4 v134, s[8:9]
	s_add_u32 m0, s17, 0x5000
	s_nop 0
	global_load_lds_dwordx4 v143, s[8:9]
	s_add_u32 m0, s17, 0x6000
	s_nop 0
	global_load_lds_dwordx4 v196, s[8:9]
	s_add_u32 m0, s17, 0x7000
	s_nop 0
	global_load_lds_dwordx4 v197, s[8:9]
	s_add_u32 s8, s8, 0x80
	s_addc_u32 s9, s9, 0
	s_waitcnt vmcnt(0)
	s_barrier
	s_mov_b32 s10, 0
	s_mov_b32 s16, 0
	ds_read_b128 v[144:147], v219 offset:32768
	ds_read_b128 v[148:151], v219 offset:34816
	ds_read_b128 v[152:155], v219 offset:36864
	ds_read_b128 v[156:159], v219 offset:38912
	ds_read_b128 v[160:163], v228 offset:32768
	ds_read_b128 v[164:167], v228 offset:34816
	ds_read_b128 v[168:171], v228 offset:36864
	ds_read_b128 v[172:175], v228 offset:38912
	v_add_u32_e32 v248, s10, v231
	ds_read_b128 v[236:239], v248 offset:0
	ds_read_b128 v[240:243], v248 offset:512
	ds_read_b128 v[244:247], v248 offset:4096
	ds_read_b128 v[248:251], v248 offset:4608
	s_waitcnt lgkmcnt(0)
	s_barrier
.Lgz4_loop:
	s_cmp_lt_u32 s16, 15
	s_cselect_b64 vcc, -1, 0
	v_add_u32_e32 v212, s10, v216
	ds_read_b128 v[252:255], v212 offset:0
	ds_read_b128 v[204:207], v212 offset:512
	ds_read_b128 v[208:211], v212 offset:4096
	ds_read_b128 v[212:215], v212 offset:4608
	v_mfma_f32_16x16x32_bf16 v[124:127], v[236:239], v[144:147], v[124:127]
	ds_read_b128 v[176:179], v219 offset:49152
	v_mfma_f32_16x16x32_bf16 v[120:123], v[240:243], v[144:147], v[120:123]
	ds_read_b128 v[180:183], v219 offset:51200
	v_mfma_f32_16x16x32_bf16 v[84:87], v[244:247], v[144:147], v[84:87]
	ds_read_b128 v[184:187], v219 offset:53248
	v_mfma_f32_16x16x32_bf16 v[80:83], v[248:251], v[144:147], v[80:83]
	ds_read_b128 v[188:191], v219 offset:55296
	v_mfma_f32_16x16x32_bf16 v[116:119], v[236:239], v[148:151], v[116:119]
	ds_read_b128 v[192:195], v228 offset:49152
	v_mfma_f32_16x16x32_bf16 v[112:115], v[240:243], v[148:151], v[112:115]
	ds_read_b128 v[220:223], v228 offset:51200
	v_mfma_f32_16x16x32_bf16 v[76:79], v[244:247], v[148:151], v[76:79]
	ds_read_b128 v[224:227], v228 offset:53248
	v_mfma_f32_16x16x32_bf16 v[68:71], v[248:251], v[148:151], v[68:71]
	ds_read_b128 v[232:235], v228 offset:55296
	s_add_u32 m0, s17, 0x8000
	v_mfma_f32_16x16x32_bf16 v[108:111], v[236:239], v[152:155], v[108:111]
	s_cbranch_vccz .Lgz4_a0
	global_load_lds_dwordx4 v128, s[6:7]

; #define MM(j, xf)                                                                     \
;   acc[0][j] = MFMA16(wf0, xf, acc[0][j]); acc[1][j] = MFMA16(wf1, xf, acc[1][j]);      \
;   acc[2][j] = MFMA16(wf2, xf, acc[2][j]); acc[3][j] = MFMA16(wf3, xf, acc[3][j]);
; __device__ __forceinline__ void gb_step(const u16* ga, const u16* gw, size_t a64, size_t w64, int ko, bool issue, ...
;     ...
;   asm volatile("s_waitcnt lgkmcnt(7)" : "+v"(wf0), "+v"(wf1), "+v"(wf2), "+v"(wf3), "+v"(xf0) : : "memory");
;   MM(0, xf0)
;   asm volatile("s_waitcnt lgkmcnt(6)" : "+v"(xf1) : : "memory");
;   MM(1, xf1)
;   asm volatile("s_waitcnt lgkmcnt(5)" : "+v"(xf2) : : "memory");
;   MM(2, xf2)
;   asm volatile("s_waitcnt lgkmcnt(4)" : "+v"(xf3) : : "memory");
;   MM(3, xf3)
;   asm volatile("s_waitcnt lgkmcnt(3)" : "+v"(xf4) : : "memory");
;   MM(4, xf4)
;   asm volatile("s_waitcnt lgkmcnt(2)" : "+v"(xf5) : : "memory");
;   MM(5, xf5)
;   asm volatile("s_waitcnt lgkmcnt(1)" : "+v"(xf6) : : "memory");
;   MM(6, xf6)
;   asm volatile("s_waitcnt lgkmcnt(0)" : "+v"(xf7) : : "memory");
;   MM(7, xf7)
.Lgz4_a3:
	v_mfma_f32_16x16x32_bf16 v[40:43], v[248:251], v[156:159], v[40:43]
	s_waitcnt lgkmcnt(8)
	v_mfma_f32_16x16x32_bf16 v[124:127], v[252:255], v[160:163], v[124:127]
	v_mfma_f32_16x16x32_bf16 v[120:123], v[204:207], v[160:163], v[120:123]
	v_mfma_f32_16x16x32_bf16 v[84:87], v[208:211], v[160:163], v[84:87]
	v_mfma_f32_16x16x32_bf16 v[80:83], v[212:215], v[160:163], v[80:83]
	v_mfma_f32_16x16x32_bf16 v[116:119], v[252:255], v[164:167], v[116:119]
	v_mfma_f32_16x16x32_bf16 v[112:115], v[204:207], v[164:167], v[112:115]
	v_mfma_f32_16x16x32_bf16 v[76:79], v[208:211], v[164:167], v[76:79]
	v_mfma_f32_16x16x32_bf16 v[68:71], v[212:215], v[164:167], v[68:71]
	v_mfma_f32_16x16x32_bf16 v[108:111], v[252:255], v[168:171], v[108:111]
	v_mfma_f32_16x16x32_bf16 v[104:107], v[204:207], v[168:171], v[104:107]
	v_mfma_f32_16x16x32_bf16 v[60:63], v[208:211], v[168:171], v[60:63]
	v_mfma_f32_16x16x32_bf16 v[56:59], v[212:215], v[168:171], v[56:59]
	v_mfma_f32_16x16x32_bf16 v[100:103], v[252:255], v[172:175], v[100:103]
	v_mfma_f32_16x16x32_bf16 v[96:99], v[204:207], v[172:175], v[96:99]
	v_mfma_f32_16x16x32_bf16 v[44:47], v[208:211], v[172:175], v[44:47]
	v_mfma_f32_16x16x32_bf16 v[40:43], v[212:215], v[172:175], v[40:43]
	s_waitcnt vmcnt(0)
	s_waitcnt lgkmcnt(0)
	s_add_u32 s6, s6, 0x20000
	s_addc_u32 s7, s7, 0
	s_xor_b32 s11, s10, 0x4000
	s_barrier
	v_mfma_f32_16x16x32_bf16 v[92:95], v[236:239], v[176:179], v[92:95]
	ds_read_b128 v[144:147], v219 offset:32768
	v_mfma_f32_16x16x32_bf16 v[88:91], v[240:243], v[176:179], v[88:91]
	ds_read_b128 v[148:151], v219 offset:34816
	v_mfma_f32_16x16x32_bf16 v[28:31], v[244:247], v[176:179], v[28:31]
	ds_read_b128 v[152:155], v219 offset:36864
	v_mfma_f32_16x16x32_bf16 v[24:27], v[248:251], v[176:179], v[24:27]
	ds_read_b128 v[156:159], v219 offset:38912
	v_mfma_f32_16x16x32_bf16 v[72:75], v[236:239], v[180:183], v[72:75]
	ds_read_b128 v[160:163], v228 offset:32768
	v_mfma_f32_16x16x32_bf16 v[64:67], v[240:243], v[180:183], v[64:67]
	ds_read_b128 v[164:167], v228 offset:34816
	v_mfma_f32_16x16x32_bf16 v[20:23], v[244:247], v[180:183], v[20:23]
	ds_read_b128 v[168:171], v228 offset:36864
	v_mfma_f32_16x16x32_bf16 v[16:19], v[248:251], v[180:183], v[16:19]
	ds_read_b128 v[172:175], v228 offset:38912
	s_add_u32 m0, s17, 0xc000
	v_mfma_f32_16x16x32_bf16 v[52:55], v[236:239], v[184:187], v[52:55]
	s_cbranch_vccz .Lgz4_b0
	global_load_lds_dwordx4 v128, s[6:7]

; #define MM(j, xf)                                                                     \
;   acc[0][j] = MFMA16(wf0, xf, acc[0][j]); acc[1][j] = MFMA16(wf1, xf, acc[1][j]);      \
;   acc[2][j] = MFMA16(wf2, xf, acc[2][j]); acc[3][j] = MFMA16(wf3, xf, acc[3][j]);
; __device__ __forceinline__ void gb_step(const u16* ga, const u16* gw, size_t a64, size_t w64, int ko, bool issue, ...
;     ...
;   asm volatile("s_waitcnt lgkmcnt(7)" : "+v"(wf0), "+v"(wf1), "+v"(wf2), "+v"(wf3), "+v"(xf0) : : "memory");
;   MM(0, xf0)
;   asm volatile("s_waitcnt lgkmcnt(6)" : "+v"(xf1) : : "memory");
;   MM(1, xf1)
;   asm volatile("s_waitcnt lgkmcnt(5)" : "+v"(xf2) : : "memory");
;   MM(2, xf2)
;   asm volatile("s_waitcnt lgkmcnt(4)" : "+v"(xf3) : : "memory");
;   MM(3, xf3)
;   asm volatile("s_waitcnt lgkmcnt(3)" : "+v"(xf4) : : "memory");
;   MM(4, xf4)
;   asm volatile("s_waitcnt lgkmcnt(2)" : "+v"(xf5) : : "memory");
;   MM(5, xf5)
;   asm volatile("s_waitcnt lgkmcnt(1)" : "+v"(xf6) : : "memory");
;   MM(6, xf6)
;   asm volatile("s_waitcnt lgkmcnt(0)" : "+v"(xf7) : : "memory");
;   MM(7, xf7)
.Lgz4_b3:
	v_mfma_f32_16x16x32_bf16 v[0:3], v[248:251], v[188:191], v[0:3]
	v_add_u32_e32 v248, s11, v231
	v_mfma_f32_16x16x32_bf16 v[92:95], v[252:255], v[192:195], v[92:95]
	ds_read_b128 v[236:239], v248 offset:0
	v_mfma_f32_16x16x32_bf16 v[88:91], v[204:207], v[192:195], v[88:91]
	ds_read_b128 v[240:243], v248 offset:512
	v_mfma_f32_16x16x32_bf16 v[28:31], v[208:211], v[192:195], v[28:31]
	ds_read_b128 v[244:247], v248 offset:4096
	v_mfma_f32_16x16x32_bf16 v[24:27], v[212:215], v[192:195], v[24:27]
	ds_read_b128 v[248:251], v248 offset:4608
	v_mfma_f32_16x16x32_bf16 v[72:75], v[252:255], v[220:223], v[72:75]
	v_mfma_f32_16x16x32_bf16 v[64:67], v[204:207], v[220:223], v[64:67]
	s_cmp_lt_u32 s16, 14
	s_cbranch_scc0 .Lgz4_w0
	s_add_u32 m0, s17, s10
	s_add_u32 m0, m0, 0x0
	s_nop 0
	global_load_lds_dwordx4 v134, s[8:9]

; __device__ __forceinline__ int ltid() { int t = threadIdx.x; asm volatile("" : "+v"(t)); return t; }
; #define WAIT_V(n) asm volatile("s_waitcnt vmcnt(%0)" ::"n"(n) : "memory")
; #define RAW_BARRIER() do { asm volatile("s_waitcnt lgkmcnt(0)" ::: "memory"); __builtin_amdgcn_s_barrier(); } while (0)
; __device__ __forceinline__ void gb_issue(const u16* ga, const u16* gw, size_t a64, size_t w64, int ko, u16* __restrict__ wr, int wave) {
; #pragma unroll
;   for (int i = 0; i < 4; i++)
;     __builtin_amdgcn_global_load_lds((const unsigned*)(ga + i * a64 + ko), (lds_u32*)(wr + (i * 4 + wave) * 512), 16, 0, 0);
; #pragma unroll
;   for (int i = 0; i < 2; i++)
;     __builtin_amdgcn_global_load_lds((const unsigned*)(gw + i * w64 + ko), (lds_u32*)(wr + 256 * GST + (i * 4 + wave) * 512), 16, 0, 0);
; }
; template <class F>
; __device__ __forceinline__ void gemm_big(const ALbf& al, const u16* __restrict__ Wt, int K, int m0, int n0, const F& f, u16* sm) {
;   const int tid = ltid(), lane = tid & 63, wave = tid >> 6;
;   const int wm = wave >> 1, wn = wave & 1;
;   const int rsw = GSW(lane & 15, lane >> 4);
;   f32x4 acc[4][8];
; #pragma unroll
;   for (int i = 0; i < 4; i++)
; #pragma unroll
;     for (int j = 0; j < 8; j++) acc[i][j] = (f32x4){0.f, 0.f, 0.f, 0.f};
;   const int srow = lane >> 2;
;   const int scol = ((lane & 3) ^ ((0 - (srow >> 2)) & 3)) * 8;
;   const u16* ga = al.A + (size_t)(m0 + wave * 16 + srow) * al.lda + scol;
;   const u16* gw = Wt + (size_t)(n0 + wave * 16 + srow) * K + scol;
;   const size_t a64 = (size_t)64 * al.lda, w64 = (size_t)64 * K;
;   const int nk = K >> 5;
;   WAIT_V(0);
;   gb_issue(ga, gw, a64, w64, 0, sm, wave);
;   gb_issue(ga, gw, a64, w64, 32, sm + GB_STAGE_EL, wave);
;   WAIT_V(6);
;   RAW_BARRIER();
.LBB0_322:
	v_mov_b32_e32 v138, v132
	s_lshl_b32 s14, s59, 8
	v_lshrrev_b32_e32 v0, 2, v138
	v_bfe_u32 v140, v138, 4, 2
	v_sub_u32_e32 v0, 0, v0
	v_bitop3_b32 v0, v140, v0, 3 bitop3:0x78
	v_lshlrev_b32_e32 v6, 4, v0
	v_lshrrev_b32_e32 v0, 4, v138
	v_ashrrev_i32_e32 v4, 6, v138
	v_sub_u32_e32 v8, 0, v0
	s_and_b32 s61, s14, 0x3f00
	s_lshl_b32 s14, s59, 1
	v_bfe_u32 v7, v138, 2, 4
	v_xor_b32_e32 v2, v138, v8
	v_lshlrev_b32_e32 v9, 4, v4
	s_and_b32 s60, s14, 0xffffff80
	v_or_b32_e32 v3, v7, v9
	v_lshlrev_b32_e32 v2, 4, v2
	v_add_u32_e32 v0, s61, v3
	v_and_b32_e32 v134, 48, v2
	v_add_u32_e32 v2, s60, v3
	v_ashrrev_i32_e32 v1, 31, v0
	v_ashrrev_i32_e32 v3, 31, v2
	v_lshlrev_b64 v[0:1], 11, v[0:1]
	v_lshlrev_b64 v[2:3], 11, v[2:3]
	v_lshl_add_u64 v[0:1], s[30:31], 0, v[0:1]
	v_lshl_add_u64 v[2:3], s[8:9], 0, v[2:3]
	v_lshl_add_u64 v[0:1], v[0:1], 0, v[134:135]
	v_lshl_add_u64 v[2:3], v[2:3], 0, v[134:135]
	v_lshlrev_b32_e32 v134, 10, v4
	v_add_u32_e32 v10, 0x1000, v134
	v_readfirstlane_b32 s14, v134
	s_waitcnt vmcnt(0)
	s_mov_b32 m0, s14
	v_readfirstlane_b32 s14, v10
	v_add_u32_e32 v10, 0x2000, v134
	v_lshl_add_u64 v[4:5], v[0:1], 0, s[96:97]
	s_mov_b32 m0, s14
	v_readfirstlane_b32 s14, v10
	v_add_u32_e32 v10, 0x3000, v134
	v_lshl_add_u64 v[4:5], v[0:1], 0, s[86:87]
	s_mov_b32 m0, s14
	s_mov_b64 s[12:13], 0x60000
	v_readfirstlane_b32 s14, v10
	v_lshl_add_u64 v[4:5], v[0:1], 0, s[12:13]
	s_mov_b32 m0, s14
	v_add_u32_e32 v10, 0x5000, v134
	v_add_u32_e32 v4, 0x4000, v134
	s_mov_b64 s[12:13], 0x20040
	v_readfirstlane_b32 s14, v4
	s_mov_b32 m0, s14
	v_readfirstlane_b32 s14, v10
	v_add_u32_e32 v10, 0x6000, v134
	v_lshl_add_u64 v[4:5], v[2:3], 0, s[96:97]
	s_mov_b32 m0, s14
	v_readfirstlane_b32 s14, v10
	v_add_u32_e32 v10, 0x7000, v134
	v_lshl_add_u64 v[4:5], v[0:1], 0, 64
	s_mov_b32 m0, s14
	v_readfirstlane_b32 s14, v10
	v_lshl_add_u64 v[4:5], v[0:1], 0, s[12:13]
	s_mov_b32 m0, s14
	s_mov_b64 s[14:15], 0x40040
	v_add_u32_e32 v10, 0x8000, v134
	v_lshl_add_u64 v[4:5], v[0:1], 0, s[14:15]
	v_readfirstlane_b32 s14, v10
	s_mov_b32 m0, s14
	s_mov_b64 s[14:15], 0x60040
	v_add_u32_e32 v4, 0x9000, v134
	v_lshl_add_u64 v[0:1], v[0:1], 0, s[14:15]
	v_readfirstlane_b32 s14, v4
	v_add_u32_e32 v4, 0xa000, v134
	s_mov_b32 m0, s14
	v_readfirstlane_b32 s14, v4
	v_lshl_add_u64 v[0:1], v[2:3], 0, 64
	s_mov_b32 m0, s14
	s_and_b32 s10, s4, 0xffffff80
	v_lshl_add_u64 v[0:1], v[2:3], 0, s[12:13]
	v_add_u32_e32 v2, 0xb000, v134
	s_and_b32 s11, s35, 0x3f00
	v_readfirstlane_b32 s14, v2
	s_mov_b32 m0, s14
	v_bitop3_b32 v2, v138, 3, v8 bitop3:0x48
	v_lshlrev_b32_e32 v0, 6, v138
	v_and_or_b32 v143, v0, s80, v6
	v_lshlrev_b32_e32 v0, 1, v138
	v_and_b32_e32 v1, 0x43, v138
	v_and_or_b32 v0, v0, 24, v1
	v_lshrrev_b32_e32 v1, 1, v138
	v_and_b32_e32 v1, 2, v1
	v_sub_u32_e32 v1, 0, v1
	v_bitop3_b32 v1, v1, v140, 2 bitop3:0x6c
	v_lshlrev_b32_e32 v1, 4, v1
	v_lshl_or_b32 v144, v0, 6, v1
	v_or_b32_e32 v0, 4, v0
	v_lshlrev_b32_e32 v1, 6, v0
	v_lshrrev_b32_e32 v0, 2, v0
	v_sub_u32_e32 v0, 0, v0
	v_bitop3_b32 v0, v0, v140, 3 bitop3:0x6c
	v_lshl_or_b32 v145, v0, 4, v1
	v_or_b32_e32 v0, s10, v7
	v_add_u32_e32 v0, v0, v9
	v_ashrrev_i32_e32 v1, 31, v0
	v_lshlrev_b64 v[0:1], 11, v[0:1]
	v_lshlrev_b32_e32 v2, 4, v2
	v_or_b32_e32 v0, v0, v2
	v_lshl_add_u64 v[128:129], s[8:9], 0, v[0:1]
	v_or_b32_e32 v0, s11, v7
	v_add_u32_e32 v0, v0, v9
	v_ashrrev_i32_e32 v1, 31, v0
	s_waitcnt vmcnt(6)
	v_lshlrev_b64 v[0:1], 11, v[0:1]
	s_waitcnt lgkmcnt(0)
	v_or_b32_e32 v0, v0, v2
	v_lshl_add_u64 v[130:131], s[30:31], 0, v[0:1]
	v_mov_b32_e32 v0, 0
	s_mov_b32 s93, 0
	s_mov_b64 s[10:11], 0
	s_mov_b32 s94, 0
	v_mov_b32_e32 v1, v0
	v_mov_b32_e32 v2, v0
	v_mov_b32_e32 v3, v0
	v_mov_b32_e32 v4, v0
	v_mov_b32_e32 v5, v0
	v_mov_b32_e32 v6, v0
	v_mov_b32_e32 v7, v0
	v_mov_b32_e32 v32, v0
	v_mov_b32_e32 v33, v0
	v_mov_b32_e32 v34, v0
	v_mov_b32_e32 v35, v0
	v_mov_b32_e32 v36, v0
	v_mov_b32_e32 v37, v0
	v_mov_b32_e32 v38, v0
	v_mov_b32_e32 v39, v0
	v_mov_b32_e32 v8, v0
	v_mov_b32_e32 v9, v0
	v_mov_b32_e32 v10, v0
	v_mov_b32_e32 v11, v0
	v_mov_b32_e32 v12, v0
	v_mov_b32_e32 v13, v0
	v_mov_b32_e32 v14, v0
	v_mov_b32_e32 v15, v0
	v_mov_b32_e32 v48, v0
	v_mov_b32_e32 v49, v0
	v_mov_b32_e32 v50, v0
	v_mov_b32_e32 v51, v0
	v_mov_b32_e32 v52, v0
	v_mov_b32_e32 v53, v0
	v_mov_b32_e32 v54, v0
	v_mov_b32_e32 v55, v0
	v_mov_b32_e32 v16, v0
	v_mov_b32_e32 v17, v0
	v_mov_b32_e32 v18, v0
	v_mov_b32_e32 v19, v0
	v_mov_b32_e32 v20, v0
	v_mov_b32_e32 v21, v0
	v_mov_b32_e32 v22, v0
	v_mov_b32_e32 v23, v0
	v_mov_b32_e32 v64, v0
	v_mov_b32_e32 v65, v0
	v_mov_b32_e32 v66, v0
	v_mov_b32_e32 v67, v0
	v_mov_b32_e32 v72, v0
	v_mov_b32_e32 v73, v0
	v_mov_b32_e32 v74, v0
	v_mov_b32_e32 v75, v0
	v_mov_b32_e32 v24, v0
	v_mov_b32_e32 v25, v0
	v_mov_b32_e32 v26, v0
	v_mov_b32_e32 v27, v0
	v_mov_b32_e32 v28, v0
	v_mov_b32_e32 v29, v0
	v_mov_b32_e32 v30, v0
	v_mov_b32_e32 v31, v0
	v_mov_b32_e32 v88, v0
	v_mov_b32_e32 v89, v0
	v_mov_b32_e32 v90, v0
	v_mov_b32_e32 v91, v0
	v_mov_b32_e32 v92, v0
	v_mov_b32_e32 v93, v0
	v_mov_b32_e32 v94, v0
	v_mov_b32_e32 v95, v0
	v_mov_b32_e32 v40, v0
	v_mov_b32_e32 v41, v0
	v_mov_b32_e32 v42, v0
	v_mov_b32_e32 v43, v0
	v_mov_b32_e32 v44, v0
	v_mov_b32_e32 v45, v0
	v_mov_b32_e32 v46, v0
	v_mov_b32_e32 v47, v0
	v_mov_b32_e32 v96, v0
	v_mov_b32_e32 v97, v0
	v_mov_b32_e32 v98, v0
	v_mov_b32_e32 v99, v0
	v_mov_b32_e32 v100, v0
	v_mov_b32_e32 v101, v0
	v_mov_b32_e32 v102, v0
	v_mov_b32_e32 v103, v0
	v_mov_b32_e32 v56, v0
	v_mov_b32_e32 v57, v0
	v_mov_b32_e32 v58, v0
	v_mov_b32_e32 v59, v0
	v_mov_b32_e32 v60, v0
	v_mov_b32_e32 v61, v0
	v_mov_b32_e32 v62, v0
	v_mov_b32_e32 v63, v0
	v_mov_b32_e32 v104, v0
	v_mov_b32_e32 v105, v0
; __device__ __forceinline__ void gb_step(const u16* ga, const u16* gw, size_t a64, size_t w64, int ko, bool issue, ...
;   if (issue) {
; #pragma unroll
;     for (int i = 0; i < 4; i++)
;       __builtin_amdgcn_global_load_lds((const unsigned*)(ga + i * a64 + ko), (lds_u32*)(wr + (i * 4 + wave) * 512), 16, 0, 0);
; #pragma unroll
;     for (int i = 0; i < 2; i++)
;       __builtin_amdgcn_global_load_lds((const unsigned*)(gw + i * w64 + ko), (lds_u32*)(wr + 256 * GST + (i * 4 + wave) * 512), 16, 0, 0);
;   }
;   const unsigned rdb = (unsigned)(size_t)(__attribute__((address_space(3))) const char*)rd;
;   const unsigned ab = rdb + (unsigned)(((wm * 128 + (lane & 15)) * GST + rsw) * 2);
;   const int wr0 = wn * 64 + (((lane & 15) >> 2) << 3) + (lane & 3);
;   const unsigned bb0 = rdb + (unsigned)((256 * GST + wr0 * GST + GSW(wr0, lane >> 4)) * 2);
;   const unsigned bb1 = rdb + (unsigned)((256 * GST + (wr0 + 4) * GST + GSW(wr0 + 4, lane >> 4)) * 2);
;   bf16x8 wf0, wf1, wf2, wf3, xf0, xf1, xf2, xf3, xf4, xf5, xf6, xf7;
;     ...
;   DSR(wf0, bb0, 0); DSR(wf1, bb1, 0); DSR(wf2, bb0, 2048); DSR(wf3, bb1, 2048);
;   DSR(xf0, ab, 0); DSR(xf1, ab, 1024); DSR(xf2, ab, 2048); DSR(xf3, ab, 3072);
;   DSR(xf4, ab, 4096); DSR(xf5, ab, 5120); DSR(xf6, ab, 6144); DSR(xf7, ab, 7168);
;     ...
;   asm volatile("s_waitcnt lgkmcnt(7)" : "+v"(wf0), "+v"(wf1), "+v"(wf2), "+v"(wf3), "+v"(xf0) : : "memory");
;   MM(0, xf0)
;   asm volatile("s_waitcnt lgkmcnt(6)" : "+v"(xf1) : : "memory");
;   MM(1, xf1)
;   asm volatile("s_waitcnt lgkmcnt(5)" : "+v"(xf2) : : "memory");
;   MM(2, xf2)
; template <class F>
; __device__ __forceinline__ void gemm_big(const ALbf& al, const u16* __restrict__ Wt, int K, int m0, int n0, const F& f, u16* sm) {
;     ...
; #pragma unroll
;   for (int i = 0; i < 4; i++)
; #pragma unroll
;     for (int j = 0; j < 8; j++) acc[i][j] = (f32x4){0.f, 0.f, 0.f, 0.f};
;   const int srow = lane >> 2;
;   const int scol = ((lane & 3) ^ ((0 - (srow >> 2)) & 3)) * 8;
;   const u16* ga = al.A + (size_t)(m0 + wave * 16 + srow) * al.lda + scol;
;   const u16* gw = Wt + (size_t)(n0 + wave * 16 + srow) * K + scol;
;   const size_t a64 = (size_t)64 * al.lda, w64 = (size_t)64 * K;
;   const int nk = K >> 5;
;   WAIT_V(0);
;   gb_issue(ga, gw, a64, w64, 0, sm, wave);
;   gb_issue(ga, gw, a64, w64, 32, sm + GB_STAGE_EL, wave);
;   WAIT_V(6);
;   RAW_BARRIER();
	v_mov_b32_e32 v106, v0
	v_mov_b32_e32 v107, v0
	v_mov_b32_e32 v108, v0
	v_mov_b32_e32 v109, v0
	v_mov_b32_e32 v110, v0
	v_mov_b32_e32 v111, v0
	v_mov_b32_e32 v68, v0
	v_mov_b32_e32 v69, v0
	v_mov_b32_e32 v70, v0
	v_mov_b32_e32 v71, v0
	v_mov_b32_e32 v76, v0
	v_mov_b32_e32 v77, v0
	v_mov_b32_e32 v78, v0
	v_mov_b32_e32 v79, v0
	v_mov_b32_e32 v112, v0
	v_mov_b32_e32 v113, v0
	v_mov_b32_e32 v114, v0
	v_mov_b32_e32 v115, v0
	v_mov_b32_e32 v116, v0
	v_mov_b32_e32 v117, v0
	v_mov_b32_e32 v118, v0
	v_mov_b32_e32 v119, v0
	v_mov_b32_e32 v80, v0
	v_mov_b32_e32 v81, v0
	v_mov_b32_e32 v82, v0
	v_mov_b32_e32 v83, v0
	v_mov_b32_e32 v84, v0
	v_mov_b32_e32 v85, v0
	v_mov_b32_e32 v86, v0
	v_mov_b32_e32 v87, v0
	v_mov_b32_e32 v120, v0
	v_mov_b32_e32 v121, v0
	v_mov_b32_e32 v122, v0
	v_mov_b32_e32 v123, v0
	v_mov_b32_e32 v124, v0
	v_mov_b32_e32 v125, v0
	v_mov_b32_e32 v126, v0
	v_mov_b32_e32 v127, v0
	v_readfirstlane_b32 s10, v130
	v_readfirstlane_b32 s11, v131
	v_readfirstlane_b32 s14, v128
	v_readfirstlane_b32 s15, v129
	v_readfirstlane_b32 s94, v134
	v_and_b32_e32 v176, 63, v132
	v_lshrrev_b32_e32 v177, 6, v132
	v_lshrrev_b32_e32 v178, 3, v176
	v_and_b32_e32 v179, 7, v176
	v_lshrrev_b32_e32 v180, 4, v176
	v_and_b32_e32 v181, 1, v177
	v_lshrrev_b32_e32 v182, 1, v177
	v_lshl_add_u32 v183, v181, 2, v180
	v_xor_b32_e32 v183, v179, v183
	v_lshl_add_u32 v184, v177, 3, v178
	v_lshlrev_b32_e32 v188, 11, v184
	v_lshl_add_u32 v128, v183, 4, v188
	v_add_u32_e32 v129, 0x10000, v128
	v_add_u32_e32 v130, 0x40000, v128
	v_add_u32_e32 v131, 0x50000, v128
	v_bfe_u32 v185, v178, 1, 1
	v_lshl_or_b32 v185, v181, 1, v185
	v_lshl_or_b32 v185, v182, 2, v185
	v_xor_b32_e32 v185, v179, v185
	v_lshl_add_u32 v134, v185, 4, v188
	v_add_u32_e32 v143, 0x10000, v134
	v_add_u32_e32 v196, 0x20000, v134
	v_add_u32_e32 v197, 0x30000, v134
	v_and_b32_e32 v186, 15, v176
	v_bfe_u32 v187, v176, 1, 3
	v_xor_b32_e32 v187, v180, v187
	v_lshlrev_b32_e32 v187, 4, v187
	v_lshl_add_u32 v188, v182, 6, v186
	v_lshl_add_u32 v219, v188, 7, v187
	v_xor_b32_e32 v228, 64, v219
	v_lshrrev_b32_e32 v189, 2, v186
	v_lshlrev_b32_e32 v189, 3, v189
	v_and_b32_e32 v188, 3, v186
	v_add_u32_e32 v189, v189, v188
	v_lshl_add_u32 v189, v181, 6, v189
	v_lshl_add_u32 v231, v189, 7, v187
	v_xor_b32_e32 v216, 64, v231
	s_lshl_b32 s17, s94, 5
	s_sub_u32 s10, s10, s17
	s_subb_u32 s11, s11, 0
	s_sub_u32 s14, s14, s17
	s_subb_u32 s15, s15, 0
	s_add_u32 m0, s94, 0x8000
	s_nop 0
	global_load_lds_dwordx4 v128, s[10:11]
	s_add_u32 m0, s94, 0x9000
	s_nop 0
	global_load_lds_dwordx4 v129, s[10:11]
	s_add_u32 m0, s94, 0xa000
	s_nop 0
	global_load_lds_dwordx4 v130, s[10:11]
	s_add_u32 m0, s94, 0xb000
	s_nop 0
	global_load_lds_dwordx4 v131, s[10:11]
	s_add_u32 s10, s10, 0x20000
	s_addc_u32 s11, s11, 0
	s_add_u32 m0, s94, 0xc000
	s_nop 0
	global_load_lds_dwordx4 v128, s[10:11]
	s_add_u32 m0, s94, 0xd000
	s_nop 0
	global_load_lds_dwordx4 v129, s[10:11]
	s_add_u32 m0, s94, 0xe000
	s_nop 0
	global_load_lds_dwordx4 v130, s[10:11]
	s_add_u32 m0, s94, 0xf000
	s_nop 0
	global_load_lds_dwordx4 v131, s[10:11]
	s_add_u32 s10, s10, 0xfffe0080
	s_addc_u32 s11, s11, -1
	s_add_u32 m0, s94, 0x0
	s_nop 0
	global_load_lds_dwordx4 v134, s[14:15]
	s_add_u32 m0, s94, 0x1000
	s_nop 0
	global_load_lds_dwordx4 v143, s[14:15]
	s_add_u32 m0, s94, 0x2000
	s_nop 0
	global_load_lds_dwordx4 v196, s[14:15]
	s_add_u32 m0, s94, 0x3000
	s_nop 0
	global_load_lds_dwordx4 v197, s[14:15]
	s_add_u32 s14, s14, 0x80
	s_addc_u32 s15, s15, 0
	s_add_u32 m0, s94, 0x4000
	s_nop 0
	global_load_lds_dwordx4 v134, s[14:15]
	s_add_u32 m0, s94, 0x5000
	s_nop 0
	global_load_lds_dwordx4 v143, s[14:15]
	s_add_u32 m0, s94, 0x6000
	s_nop 0
	global_load_lds_dwordx4 v196, s[14:15]
	s_add_u32 m0, s94, 0x7000
	s_nop 0
	global_load_lds_dwordx4 v197, s[14:15]
	s_add_u32 s14, s14, 0x80
	s_addc_u32 s15, s15, 0
	s_waitcnt vmcnt(0)
	s_barrier
	s_mov_b32 s16, 0
	s_mov_b32 s93, 0
	ds_read_b128 v[144:147], v219 offset:32768
	ds_read_b128 v[148:151], v219 offset:34816
	ds_read_b128 v[152:155], v219 offset:36864
	ds_read_b128 v[156:159], v219 offset:38912
	ds_read_b128 v[160:163], v228 offset:32768
	ds_read_b128 v[164:167], v228 offset:34816
	ds_read_b128 v[168:171], v228 offset:36864
	ds_read_b128 v[172:175], v228 offset:38912
	v_add_u32_e32 v248, s16, v231
	ds_read_b128 v[236:239], v248 offset:0
	ds_read_b128 v[240:243], v248 offset:512
	ds_read_b128 v[244:247], v248 offset:4096
	ds_read_b128 v[248:251], v248 offset:4608
	s_waitcnt lgkmcnt(0)
	s_barrier
.Lgz5_loop:
	s_cmp_lt_u32 s93, 15
	s_cselect_b64 vcc, -1, 0
	v_add_u32_e32 v212, s16, v216
	ds_read_b128 v[252:255], v212 offset:0
	ds_read_b128 v[204:207], v212 offset:512
	ds_read_b128 v[208:211], v212 offset:4096
	ds_read_b128 v[212:215], v212 offset:4608
	v_mfma_f32_16x16x32_bf16 v[124:127], v[236:239], v[144:147], v[124:127]
	ds_read_b128 v[176:179], v219 offset:49152
	v_mfma_f32_16x16x32_bf16 v[120:123], v[240:243], v[144:147], v[120:123]
	ds_read_b128 v[180:183], v219 offset:51200
	v_mfma_f32_16x16x32_bf16 v[84:87], v[244:247], v[144:147], v[84:87]
	ds_read_b128 v[184:187], v219 offset:53248
	v_mfma_f32_16x16x32_bf16 v[80:83], v[248:251], v[144:147], v[80:83]
	ds_read_b128 v[188:191], v219 offset:55296
	v_mfma_f32_16x16x32_bf16 v[116:119], v[236:239], v[148:151], v[116:119]
	ds_read_b128 v[192:195], v228 offset:49152
	v_mfma_f32_16x16x32_bf16 v[112:115], v[240:243], v[148:151], v[112:115]
	ds_read_b128 v[220:223], v228 offset:51200
	v_mfma_f32_16x16x32_bf16 v[76:79], v[244:247], v[148:151], v[76:79]
	ds_read_b128 v[224:227], v228 offset:53248
	v_mfma_f32_16x16x32_bf16 v[68:71], v[248:251], v[148:151], v[68:71]
	ds_read_b128 v[232:235], v228 offset:55296
	s_add_u32 m0, s94, 0x8000
	v_mfma_f32_16x16x32_bf16 v[108:111], v[236:239], v[152:155], v[108:111]
	s_cbranch_vccz .Lgz5_a0
	global_load_lds_dwordx4 v128, s[10:11]
; #define DSR(dst, addr, off) asm volatile("ds_read_b128 %0, %1 offset:%2" : "=v"(dst) : "v"(addr), "n"(off) : "memory")
; #define MM(j, xf)                                                                     \
;   acc[0][j] = MFMA16(wf0, xf, acc[0][j]); acc[1][j] = MFMA16(wf1, xf, acc[1][j]);      \
;   acc[2][j] = MFMA16(wf2, xf, acc[2][j]); acc[3][j] = MFMA16(wf3, xf, acc[3][j]);
; __device__ __forceinline__ void gb_step(const u16* ga, const u16* gw, size_t a64, size_t w64, int ko, bool issue, ...
;   if (issue) {
; #pragma unroll
;     for (int i = 0; i < 4; i++)
;       __builtin_amdgcn_global_load_lds((const unsigned*)(ga + i * a64 + ko), (lds_u32*)(wr + (i * 4 + wave) * 512), 16, 0, 0);
; #pragma unroll
;     for (int i = 0; i < 2; i++)
;       __builtin_amdgcn_global_load_lds((const unsigned*)(gw + i * w64 + ko), (lds_u32*)(wr + 256 * GST + (i * 4 + wave) * 512), 16, 0, 0);
;   }
;   const unsigned rdb = (unsigned)(size_t)(__attribute__((address_space(3))) const char*)rd;
;   const unsigned ab = rdb + (unsigned)(((wm * 128 + (lane & 15)) * GST + rsw) * 2);
;   const int wr0 = wn * 64 + (((lane & 15) >> 2) << 3) + (lane & 3);
;   const unsigned bb0 = rdb + (unsigned)((256 * GST + wr0 * GST + GSW(wr0, lane >> 4)) * 2);
;   const unsigned bb1 = rdb + (unsigned)((256 * GST + (wr0 + 4) * GST + GSW(wr0 + 4, lane >> 4)) * 2);
;   bf16x8 wf0, wf1, wf2, wf3, xf0, xf1, xf2, xf3, xf4, xf5, xf6, xf7;
;     ...
;   DSR(wf0, bb0, 0); DSR(wf1, bb1, 0); DSR(wf2, bb0, 2048); DSR(wf3, bb1, 2048);
;   DSR(xf0, ab, 0); DSR(xf1, ab, 1024); DSR(xf2, ab, 2048); DSR(xf3, ab, 3072);
;   DSR(xf4, ab, 4096); DSR(xf5, ab, 5120); DSR(xf6, ab, 6144); DSR(xf7, ab, 7168);
;     ...
;   asm volatile("s_waitcnt lgkmcnt(7)" : "+v"(wf0), "+v"(wf1), "+v"(wf2), "+v"(wf3), "+v"(xf0) : : "memory");
;   MM(0, xf0)
;   asm volatile("s_waitcnt lgkmcnt(6)" : "+v"(xf1) : : "memory");
;   MM(1, xf1)
;   asm volatile("s_waitcnt lgkmcnt(5)" : "+v"(xf2) : : "memory");
;   MM(2, xf2)
;   asm volatile("s_waitcnt lgkmcnt(4)" : "+v"(xf3) : : "memory");
;   MM(3, xf3)
;   asm volatile("s_waitcnt lgkmcnt(3)" : "+v"(xf4) : : "memory");
;   MM(4, xf4)
;   asm volatile("s_waitcnt lgkmcnt(2)" : "+v"(xf5) : : "memory");
;   MM(5, xf5)
;   asm volatile("s_waitcnt lgkmcnt(1)" : "+v"(xf6) : : "memory");
;   MM(6, xf6)
;   asm volatile("s_waitcnt lgkmcnt(0)" : "+v"(xf7) : : "memory");
;   MM(7, xf7)
.Lgz5_a0:
	v_mfma_f32_16x16x32_bf16 v[104:107], v[240:243], v[152:155], v[104:107]
	s_add_u32 m0, s94, 0x9000
	v_mfma_f32_16x16x32_bf16 v[60:63], v[244:247], v[152:155], v[60:63]
	s_cbranch_vccz .Lgz5_a1
	global_load_lds_dwordx4 v129, s[10:11]
.Lgz5_a1:
	v_mfma_f32_16x16x32_bf16 v[56:59], v[248:251], v[152:155], v[56:59]
	s_add_u32 m0, s94, 0xa000
	v_mfma_f32_16x16x32_bf16 v[100:103], v[236:239], v[156:159], v[100:103]
	s_cbranch_vccz .Lgz5_a2
	global_load_lds_dwordx4 v130, s[10:11]
.Lgz5_a2:
	v_mfma_f32_16x16x32_bf16 v[96:99], v[240:243], v[156:159], v[96:99]
	s_add_u32 m0, s94, 0xb000
	v_mfma_f32_16x16x32_bf16 v[44:47], v[244:247], v[156:159], v[44:47]
	s_cbranch_vccz .Lgz5_a3
	global_load_lds_dwordx4 v131, s[10:11]
.Lgz5_a3:
	v_mfma_f32_16x16x32_bf16 v[40:43], v[248:251], v[156:159], v[40:43]
	s_waitcnt lgkmcnt(8)
	v_mfma_f32_16x16x32_bf16 v[124:127], v[252:255], v[160:163], v[124:127]
	v_mfma_f32_16x16x32_bf16 v[120:123], v[204:207], v[160:163], v[120:123]
	v_mfma_f32_16x16x32_bf16 v[84:87], v[208:211], v[160:163], v[84:87]
	v_mfma_f32_16x16x32_bf16 v[80:83], v[212:215], v[160:163], v[80:83]
	v_mfma_f32_16x16x32_bf16 v[116:119], v[252:255], v[164:167], v[116:119]
	v_mfma_f32_16x16x32_bf16 v[112:115], v[204:207], v[164:167], v[112:115]
	v_mfma_f32_16x16x32_bf16 v[76:79], v[208:211], v[164:167], v[76:79]
	v_mfma_f32_16x16x32_bf16 v[68:71], v[212:215], v[164:167], v[68:71]
	v_mfma_f32_16x16x32_bf16 v[108:111], v[252:255], v[168:171], v[108:111]
	v_mfma_f32_16x16x32_bf16 v[104:107], v[204:207], v[168:171], v[104:107]
	v_mfma_f32_16x16x32_bf16 v[60:63], v[208:211], v[168:171], v[60:63]
	v_mfma_f32_16x16x32_bf16 v[56:59], v[212:215], v[168:171], v[56:59]
	v_mfma_f32_16x16x32_bf16 v[100:103], v[252:255], v[172:175], v[100:103]
	v_mfma_f32_16x16x32_bf16 v[96:99], v[204:207], v[172:175], v[96:99]
	v_mfma_f32_16x16x32_bf16 v[44:47], v[208:211], v[172:175], v[44:47]
	v_mfma_f32_16x16x32_bf16 v[40:43], v[212:215], v[172:175], v[40:43]
	s_waitcnt vmcnt(0)
	s_waitcnt lgkmcnt(0)
	s_add_u32 s10, s10, 0x20000
	s_addc_u32 s11, s11, 0
	s_xor_b32 s17, s16, 0x4000
	s_barrier
	v_mfma_f32_16x16x32_bf16 v[92:95], v[236:239], v[176:179], v[92:95]
	ds_read_b128 v[144:147], v219 offset:32768
	v_mfma_f32_16x16x32_bf16 v[88:91], v[240:243], v[176:179], v[88:91]
	ds_read_b128 v[148:151], v219 offset:34816
	v_mfma_f32_16x16x32_bf16 v[28:31], v[244:247], v[176:179], v[28:31]
	ds_read_b128 v[152:155], v219 offset:36864
	v_mfma_f32_16x16x32_bf16 v[24:27], v[248:251], v[176:179], v[24:27]
	ds_read_b128 v[156:159], v219 offset:38912
	v_mfma_f32_16x16x32_bf16 v[72:75], v[236:239], v[180:183], v[72:75]
	ds_read_b128 v[160:163], v228 offset:32768
	v_mfma_f32_16x16x32_bf16 v[64:67], v[240:243], v[180:183], v[64:67]
	ds_read_b128 v[164:167], v228 offset:34816
	v_mfma_f32_16x16x32_bf16 v[20:23], v[244:247], v[180:183], v[20:23]
	ds_read_b128 v[168:171], v228 offset:36864
	v_mfma_f32_16x16x32_bf16 v[16:19], v[248:251], v[180:183], v[16:19]
	ds_read_b128 v[172:175], v228 offset:38912
	s_add_u32 m0, s94, 0xc000
	v_mfma_f32_16x16x32_bf16 v[52:55], v[236:239], v[184:187], v[52:55]
	s_cbranch_vccz .Lgz5_b0
	global_load_lds_dwordx4 v128, s[10:11]
.Lgz5_b0:
	v_mfma_f32_16x16x32_bf16 v[48:51], v[240:243], v[184:187], v[48:51]
	s_add_u32 m0, s94, 0xd000
	v_mfma_f32_16x16x32_bf16 v[12:15], v[244:247], v[184:187], v[12:15]
	s_cbranch_vccz .Lgz5_b1
	global_load_lds_dwordx4 v129, s[10:11]
.Lgz5_b1:
	v_mfma_f32_16x16x32_bf16 v[8:11], v[248:251], v[184:187], v[8:11]
	s_add_u32 m0, s94, 0xe000
	v_mfma_f32_16x16x32_bf16 v[36:39], v[236:239], v[188:191], v[36:39]
	s_cbranch_vccz .Lgz5_b2
	global_load_lds_dwordx4 v130, s[10:11]
.Lgz5_b2:
	v_mfma_f32_16x16x32_bf16 v[32:35], v[240:243], v[188:191], v[32:35]
	s_add_u32 m0, s94, 0xf000
	v_mfma_f32_16x16x32_bf16 v[4:7], v[244:247], v[188:191], v[4:7]
	s_cbranch_vccz .Lgz5_b3
	global_load_lds_dwordx4 v131, s[10:11]
.Lgz5_b3:
	v_mfma_f32_16x16x32_bf16 v[0:3], v[248:251], v[188:191], v[0:3]
	v_add_u32_e32 v248, s17, v231
	v_mfma_f32_16x16x32_bf16 v[92:95], v[252:255], v[192:195], v[92:95]
	ds_read_b128 v[236:239], v248 offset:0
	v_mfma_f32_16x16x32_bf16 v[88:91], v[204:207], v[192:195], v[88:91]
	ds_read_b128 v[240:243], v248 offset:512
	v_mfma_f32_16x16x32_bf16 v[28:31], v[208:211], v[192:195], v[28:31]
	ds_read_b128 v[244:247], v248 offset:4096
	v_mfma_f32_16x16x32_bf16 v[24:27], v[212:215], v[192:195], v[24:27]
	ds_read_b128 v[248:251], v248 offset:4608
	v_mfma_f32_16x16x32_bf16 v[72:75], v[252:255], v[220:223], v[72:75]
	v_mfma_f32_16x16x32_bf16 v[64:67], v[204:207], v[220:223], v[64:67]
	s_cmp_lt_u32 s93, 14
	s_cbranch_scc0 .Lgz5_w0
	s_add_u32 m0, s94, s16
	s_add_u32 m0, m0, 0x0
	s_nop 0
	global_load_lds_dwordx4 v134, s[14:15]
.Lgz5_w0:
	v_mfma_f32_16x16x32_bf16 v[20:23], v[208:211], v[220:223], v[20:23]
	v_mfma_f32_16x16x32_bf16 v[16:19], v[212:215], v[220:223], v[16:19]
	s_cmp_lt_u32 s93, 14
	s_cbranch_scc0 .Lgz5_w1
	s_add_u32 m0, s94, s16
	s_add_u32 m0, m0, 0x1000
	s_nop 0
	global_load_lds_dwordx4 v143, s[14:15]
.Lgz5_w1:
	v_mfma_f32_16x16x32_bf16 v[52:55], v[252:255], v[224:227], v[52:55]
	v_mfma_f32_16x16x32_bf16 v[48:51], v[204:207], v[224:227], v[48:51]
	s_cmp_lt_u32 s93, 14
	s_cbranch_scc0 .Lgz5_w2
	s_add_u32 m0, s94, s16
	s_add_u32 m0, m0, 0x2000
	s_nop 0
	global_load_lds_dwordx4 v196, s[14:15]
.Lgz5_w2:
	v_mfma_f32_16x16x32_bf16 v[12:15], v[208:211], v[224:227], v[12:15]
	v_mfma_f32_16x16x32_bf16 v[8:11], v[212:215], v[224:227], v[8:11]
	s_cmp_lt_u32 s93, 14
	s_cbranch_scc0 .Lgz5_w3
	s_add_u32 m0, s94, s16
	s_add_u32 m0, m0, 0x3000
	s_nop 0
	global_load_lds_dwordx4 v197, s[14:15]
.Lgz5_w3:
	v_mfma_f32_16x16x32_bf16 v[36:39], v[252:255], v[232:235], v[36:39]
	v_mfma_f32_16x16x32_bf16 v[32:35], v[204:207], v[232:235], v[32:35]
	v_mfma_f32_16x16x32_bf16 v[4:7], v[208:211], v[232:235], v[4:7]
	v_mfma_f32_16x16x32_bf16 v[0:3], v[212:215], v[232:235], v[0:3]
	s_cmp_lt_u32 s93, 14
	s_cbranch_scc0 .Lgz5_v0
	s_waitcnt vmcnt(4)
	s_branch .Lgz5_vj

; #define WAIT_V(n) asm volatile("s_waitcnt vmcnt(%0)" ::"n"(n) : "memory")
; #define RAW_BARRIER() do { asm volatile("s_waitcnt lgkmcnt(0)" ::: "memory"); __builtin_amdgcn_s_barrier(); } while (0)
; template <class F>
; __device__ __forceinline__ void gemm_big(const ALbf& al, const u16* __restrict__ Wt, int K, int m0, int n0, const F& f, u16* sm) {
;     ...
;   for (int kt = 0; kt < nk; ++kt) {
;     const int nxt2 = (cur >= 1) ? cur - 1 : 2;
;     gb_step(ga, gw, a64, w64, (kt + 2) * 32, kt + 2 < nk, sm + cur * GB_STAGE_EL, sm + nxt2 * GB_STAGE_EL, wave, wm, wn, lane, rsw, acc);
;     if (kt + 2 < nk) WAIT_V(6); else WAIT_V(0);
;     RAW_BARRIER();
;     cur = (cur == 2) ? 0 : cur + 1;
;   }
.Lgz5_vj:
	s_waitcnt lgkmcnt(0)
	s_add_u32 s10, s10, 0xfffe0080
	s_addc_u32 s11, s11, -1
	s_add_u32 s14, s14, 0x80
	s_addc_u32 s15, s15, 0
	s_mov_b32 s16, s17
	s_add_u32 s93, s93, 1
	s_cmp_lt_u32 s93, 16
	s_barrier
	s_cbranch_scc1 .Lgz5_loop
	v_mov_b32_e32 v204, 0x3ab69700
	v_mov_b32_e32 v205, 0xffffea00
	v_mov_b32_e32 v206, 0x41b17218
	v_mov_b32_e32 v207, 0xd000
	v_mov_b32_e32 v208, 0xf00
	v_mov_b32_e32 v209, 0x7f800000
	v_mov_b32_e32 v210, 0xffffffc0
	v_mov_b32_e32 v211, 0xffffffe0
	v_mov_b32_e32 v212, 0x7fc00000
	v_mov_b32_e32 v213, 0xac00
	v_mov_b32_e32 v214, 0x800
	v_mov_b32_e32 v215, 0x140
	v_mov_b32_e32 v216, 0x130
	s_nop 7
	s_branch .LBB0_321

; __device__ __forceinline__ int ltid() { int t = threadIdx.x; asm volatile("" : "+v"(t)); return t; }
; #define WAIT_V(n) asm volatile("s_waitcnt vmcnt(%0)" ::"n"(n) : "memory")
; #define RAW_BARRIER() do { asm volatile("s_waitcnt lgkmcnt(0)" ::: "memory"); __builtin_amdgcn_s_barrier(); } while (0)
; __device__ __forceinline__ void gb_issue(const u16* ga, const u16* gw, size_t a64, size_t w64, int ko, u16* __restrict__ wr, int wave) {
; #pragma unroll
;   for (int i = 0; i < 4; i++)
;     __builtin_amdgcn_global_load_lds((const unsigned*)(ga + i * a64 + ko), (lds_u32*)(wr + (i * 4 + wave) * 512), 16, 0, 0);
; #pragma unroll
;   for (int i = 0; i < 2; i++)
;     __builtin_amdgcn_global_load_lds((const unsigned*)(gw + i * w64 + ko), (lds_u32*)(wr + 256 * GST + (i * 4 + wave) * 512), 16, 0, 0);
; }
; template <class F>
; __device__ __forceinline__ void gemm_big(const ALbf& al, const u16* __restrict__ Wt, int K, int m0, int n0, const F& f, u16* sm) {
;   const int tid = ltid(), lane = tid & 63, wave = tid >> 6;
;   const int wm = wave >> 1, wn = wave & 1;
;   const int rsw = GSW(lane & 15, lane >> 4);
;   f32x4 acc[4][8];
; #pragma unroll
;   for (int i = 0; i < 4; i++)
; #pragma unroll
;     for (int j = 0; j < 8; j++) acc[i][j] = (f32x4){0.f, 0.f, 0.f, 0.f};
;   const int srow = lane >> 2;
;   const int scol = ((lane & 3) ^ ((0 - (srow >> 2)) & 3)) * 8;
;   const u16* ga = al.A + (size_t)(m0 + wave * 16 + srow) * al.lda + scol;
;   const u16* gw = Wt + (size_t)(n0 + wave * 16 + srow) * K + scol;
;   const size_t a64 = (size_t)64 * al.lda, w64 = (size_t)64 * K;
;   const int nk = K >> 5;
;   WAIT_V(0);
;   gb_issue(ga, gw, a64, w64, 0, sm, wave);
;   gb_issue(ga, gw, a64, w64, 32, sm + GB_STAGE_EL, wave);
;   WAIT_V(6);
;   RAW_BARRIER();
.LBB0_521:
	v_mov_b32_e32 v138, v132
	s_lshl_b32 s8, s13, 8
	v_lshrrev_b32_e32 v0, 2, v138
	v_bfe_u32 v140, v138, 4, 2
	v_sub_u32_e32 v0, 0, v0
	v_bitop3_b32 v0, v140, v0, 3 bitop3:0x78
	v_lshlrev_b32_e32 v6, 4, v0
	v_lshrrev_b32_e32 v0, 4, v138
	v_ashrrev_i32_e32 v4, 6, v138
	v_sub_u32_e32 v8, 0, v0
	s_and_b32 s15, s8, 0x3f00
	s_lshl_b32 s8, s13, 1
	v_bfe_u32 v7, v138, 2, 4
	v_xor_b32_e32 v2, v138, v8
	v_lshlrev_b32_e32 v9, 4, v4
	s_load_dwordx16 s[60:75], s[0:1], 0x160
	s_and_b32 s14, s8, 0xffffff80
	v_or_b32_e32 v3, v7, v9
	v_lshlrev_b32_e32 v2, 4, v2
	v_add_u32_e32 v0, s15, v3
	v_and_b32_e32 v134, 48, v2
	v_add_u32_e32 v2, s14, v3
	v_ashrrev_i32_e32 v1, 31, v0
	v_ashrrev_i32_e32 v3, 31, v2
	v_lshlrev_b64 v[0:1], 11, v[0:1]
	v_lshlrev_b64 v[2:3], 11, v[2:3]
	s_waitcnt lgkmcnt(0)
	v_lshl_add_u64 v[0:1], s[30:31], 0, v[0:1]
	v_lshl_add_u64 v[2:3], s[74:75], 0, v[2:3]
	v_lshl_add_u64 v[0:1], v[0:1], 0, v[134:135]
	v_lshl_add_u64 v[2:3], v[2:3], 0, v[134:135]
	v_lshlrev_b32_e32 v134, 10, v4
	v_add_u32_e32 v10, 0x1000, v134
	v_readfirstlane_b32 s8, v134
	s_waitcnt vmcnt(0)
	s_mov_b32 m0, s8
	v_readfirstlane_b32 s8, v10
	v_add_u32_e32 v10, 0x2000, v134
	v_lshl_add_u64 v[4:5], v[0:1], 0, s[96:97]
	s_mov_b32 m0, s8
	v_readfirstlane_b32 s8, v10
	v_lshl_add_u64 v[4:5], v[0:1], 0, s[86:87]
	s_mov_b32 m0, s8
	s_mov_b64 s[8:9], 0x60000
	v_add_u32_e32 v10, 0x3000, v134
	v_lshl_add_u64 v[4:5], v[0:1], 0, s[8:9]
	v_readfirstlane_b32 s8, v10
	s_mov_b32 m0, s8
	v_add_u32_e32 v10, 0x5000, v134
	v_add_u32_e32 v4, 0x4000, v134
	s_mov_b64 s[10:11], 0x20040
	v_readfirstlane_b32 s8, v4
	s_mov_b32 m0, s8
	v_readfirstlane_b32 s8, v10
	v_add_u32_e32 v10, 0x6000, v134
	v_lshl_add_u64 v[4:5], v[2:3], 0, s[96:97]
	s_mov_b32 m0, s8
	v_readfirstlane_b32 s8, v10
	v_add_u32_e32 v10, 0x7000, v134
	v_lshl_add_u64 v[4:5], v[0:1], 0, 64
	s_mov_b32 m0, s8
	v_readfirstlane_b32 s8, v10
	v_lshl_add_u64 v[4:5], v[0:1], 0, s[10:11]
	s_mov_b32 m0, s8
	s_mov_b64 s[8:9], 0x40040
	v_add_u32_e32 v10, 0x8000, v134
	v_lshl_add_u64 v[4:5], v[0:1], 0, s[8:9]
	v_readfirstlane_b32 s8, v10
	s_mov_b32 m0, s8
	s_mov_b64 s[8:9], 0x60040
	v_add_u32_e32 v4, 0x9000, v134
	v_lshl_add_u64 v[0:1], v[0:1], 0, s[8:9]
	v_readfirstlane_b32 s8, v4
	v_add_u32_e32 v4, 0xa000, v134
	s_mov_b32 m0, s8
	v_readfirstlane_b32 s8, v4
	v_lshl_add_u64 v[0:1], v[2:3], 0, 64
	s_mov_b32 m0, s8
	s_and_b32 s6, s4, 0xffffff80
	v_lshl_add_u64 v[0:1], v[2:3], 0, s[10:11]
	v_add_u32_e32 v2, 0xb000, v134
	s_and_b32 s7, s12, 0x3f00
	v_readfirstlane_b32 s8, v2
	s_mov_b32 m0, s8
	s_movk_i32 s8, 0xe3c0
	v_lshlrev_b32_e32 v0, 6, v138
	v_and_or_b32 v143, v0, s8, v6
	v_lshlrev_b32_e32 v0, 1, v138
	v_and_b32_e32 v1, 0x43, v138
	v_and_or_b32 v0, v0, 24, v1
	v_lshrrev_b32_e32 v1, 1, v138
	v_and_b32_e32 v1, 2, v1
	v_sub_u32_e32 v1, 0, v1
	v_bitop3_b32 v1, v1, v140, 2 bitop3:0x6c
	v_lshlrev_b32_e32 v1, 4, v1
	v_lshl_or_b32 v144, v0, 6, v1
	v_or_b32_e32 v0, 4, v0
	v_lshlrev_b32_e32 v1, 6, v0
	v_lshrrev_b32_e32 v0, 2, v0
	v_sub_u32_e32 v0, 0, v0
	v_bitop3_b32 v0, v0, v140, 3 bitop3:0x6c
	v_lshl_or_b32 v145, v0, 4, v1
	v_or_b32_e32 v0, s6, v7
	v_add_u32_e32 v0, v0, v9
	v_ashrrev_i32_e32 v1, 31, v0
	v_bitop3_b32 v2, v138, 3, v8 bitop3:0x48
	v_lshlrev_b64 v[0:1], 11, v[0:1]
	v_lshlrev_b32_e32 v2, 4, v2
	v_or_b32_e32 v0, v0, v2
	v_lshl_add_u64 v[128:129], s[74:75], 0, v[0:1]
	v_or_b32_e32 v0, s7, v7
	v_add_u32_e32 v0, v0, v9
	v_ashrrev_i32_e32 v1, 31, v0
	s_waitcnt vmcnt(6)
	v_lshlrev_b64 v[0:1], 11, v[0:1]
	s_waitcnt lgkmcnt(0)
; __device__ __forceinline__ int ltid() { int t = threadIdx.x; asm volatile("" : "+v"(t)); return t; }
; #define WAIT_V(n) asm volatile("s_waitcnt vmcnt(%0)" ::"n"(n) : "memory")
; #define RAW_BARRIER() do { asm volatile("s_waitcnt lgkmcnt(0)" ::: "memory"); __builtin_amdgcn_s_barrier(); } while (0)
; __device__ __forceinline__ void gb_issue(const u16* ga, const u16* gw, size_t a64, size_t w64, int ko, u16* __restrict__ wr, int wave) {
; #pragma unroll
;   for (int i = 0; i < 4; i++)
;     __builtin_amdgcn_global_load_lds((const unsigned*)(ga + i * a64 + ko), (lds_u32*)(wr + (i * 4 + wave) * 512), 16, 0, 0);
; #pragma unroll
;   for (int i = 0; i < 2; i++)
;     __builtin_amdgcn_global_load_lds((const unsigned*)(gw + i * w64 + ko), (lds_u32*)(wr + 256 * GST + (i * 4 + wave) * 512), 16, 0, 0);
; }
; template <class F>
; __device__ __forceinline__ void gemm_big(const ALbf& al, const u16* __restrict__ Wt, int K, int m0, int n0, const F& f, u16* sm) {
;   const int tid = ltid(), lane = tid & 63, wave = tid >> 6;
;   const int wm = wave >> 1, wn = wave & 1;
;   const int rsw = GSW(lane & 15, lane >> 4);
;   f32x4 acc[4][8];
; #pragma unroll
;   for (int i = 0; i < 4; i++)
; #pragma unroll
;     for (int j = 0; j < 8; j++) acc[i][j] = (f32x4){0.f, 0.f, 0.f, 0.f};
;   const int srow = lane >> 2;
;   const int scol = ((lane & 3) ^ ((0 - (srow >> 2)) & 3)) * 8;
;   const u16* ga = al.A + (size_t)(m0 + wave * 16 + srow) * al.lda + scol;
;   const u16* gw = Wt + (size_t)(n0 + wave * 16 + srow) * K + scol;
;   const size_t a64 = (size_t)64 * al.lda, w64 = (size_t)64 * K;
;   const int nk = K >> 5;
;   WAIT_V(0);
;   gb_issue(ga, gw, a64, w64, 0, sm, wave);
;   gb_issue(ga, gw, a64, w64, 32, sm + GB_STAGE_EL, wave);
;   WAIT_V(6);
;   RAW_BARRIER();
	v_or_b32_e32 v0, v0, v2
	v_lshl_add_u64 v[130:131], s[30:31], 0, v[0:1]
	v_mov_b32_e32 v0, 0
	s_mov_b32 s16, 0
	s_mov_b64 s[6:7], 0
	s_mov_b32 s17, 0
	v_mov_b32_e32 v1, v0
	v_mov_b32_e32 v2, v0
	v_mov_b32_e32 v3, v0
	v_mov_b32_e32 v4, v0
	v_mov_b32_e32 v5, v0
	v_mov_b32_e32 v6, v0
	v_mov_b32_e32 v7, v0
	v_mov_b32_e32 v32, v0
	v_mov_b32_e32 v33, v0
	v_mov_b32_e32 v34, v0
	v_mov_b32_e32 v35, v0
	v_mov_b32_e32 v36, v0
	v_mov_b32_e32 v37, v0
	v_mov_b32_e32 v38, v0
	v_mov_b32_e32 v39, v0
	v_mov_b32_e32 v8, v0
	v_mov_b32_e32 v9, v0
	v_mov_b32_e32 v10, v0
	v_mov_b32_e32 v11, v0
	v_mov_b32_e32 v12, v0
	v_mov_b32_e32 v13, v0
	v_mov_b32_e32 v14, v0
	v_mov_b32_e32 v15, v0
	v_mov_b32_e32 v48, v0
	v_mov_b32_e32 v49, v0
	v_mov_b32_e32 v50, v0
	v_mov_b32_e32 v51, v0
	v_mov_b32_e32 v52, v0
	v_mov_b32_e32 v53, v0
	v_mov_b32_e32 v54, v0
	v_mov_b32_e32 v55, v0
	v_mov_b32_e32 v16, v0
	v_mov_b32_e32 v17, v0
	v_mov_b32_e32 v18, v0
	v_mov_b32_e32 v19, v0
	v_mov_b32_e32 v20, v0
	v_mov_b32_e32 v21, v0
	v_mov_b32_e32 v22, v0
	v_mov_b32_e32 v23, v0
	v_mov_b32_e32 v64, v0
	v_mov_b32_e32 v65, v0
	v_mov_b32_e32 v66, v0
	v_mov_b32_e32 v67, v0
	v_mov_b32_e32 v68, v0
	v_mov_b32_e32 v69, v0
	v_mov_b32_e32 v70, v0
	v_mov_b32_e32 v71, v0
	v_mov_b32_e32 v24, v0
	v_mov_b32_e32 v25, v0
	v_mov_b32_e32 v26, v0
	v_mov_b32_e32 v27, v0
	v_mov_b32_e32 v28, v0
	v_mov_b32_e32 v29, v0
	v_mov_b32_e32 v30, v0
	v_mov_b32_e32 v31, v0
	v_mov_b32_e32 v80, v0
	v_mov_b32_e32 v81, v0
	v_mov_b32_e32 v82, v0
	v_mov_b32_e32 v83, v0
	v_mov_b32_e32 v84, v0
	v_mov_b32_e32 v85, v0
	v_mov_b32_e32 v86, v0
	v_mov_b32_e32 v87, v0
	v_mov_b32_e32 v40, v0
	v_mov_b32_e32 v41, v0
	v_mov_b32_e32 v42, v0
	v_mov_b32_e32 v43, v0
	v_mov_b32_e32 v44, v0
	v_mov_b32_e32 v45, v0
	v_mov_b32_e32 v46, v0
	v_mov_b32_e32 v47, v0
	v_mov_b32_e32 v96, v0
	v_mov_b32_e32 v97, v0
	v_mov_b32_e32 v98, v0
	v_mov_b32_e32 v99, v0
	v_mov_b32_e32 v100, v0
	v_mov_b32_e32 v101, v0
	v_mov_b32_e32 v102, v0
	v_mov_b32_e32 v103, v0
	v_mov_b32_e32 v56, v0
	v_mov_b32_e32 v57, v0
	v_mov_b32_e32 v58, v0
	v_mov_b32_e32 v59, v0
	v_mov_b32_e32 v60, v0
	v_mov_b32_e32 v61, v0
	v_mov_b32_e32 v62, v0
	v_mov_b32_e32 v63, v0
	v_mov_b32_e32 v104, v0
	v_mov_b32_e32 v105, v0
	v_mov_b32_e32 v106, v0
	v_mov_b32_e32 v107, v0
	v_mov_b32_e32 v108, v0
	v_mov_b32_e32 v109, v0
	v_mov_b32_e32 v110, v0
	v_mov_b32_e32 v111, v0
	v_mov_b32_e32 v72, v0
	v_mov_b32_e32 v73, v0
	v_mov_b32_e32 v74, v0
	v_mov_b32_e32 v75, v0
	v_mov_b32_e32 v76, v0
	v_mov_b32_e32 v77, v0
	v_mov_b32_e32 v78, v0
	v_mov_b32_e32 v79, v0
	v_mov_b32_e32 v112, v0
	v_mov_b32_e32 v113, v0
	v_mov_b32_e32 v114, v0
	v_mov_b32_e32 v115, v0
	v_mov_b32_e32 v116, v0
	v_mov_b32_e32 v117, v0
	v_mov_b32_e32 v118, v0
	v_mov_b32_e32 v119, v0
	v_mov_b32_e32 v88, v0
	v_mov_b32_e32 v89, v0
	v_mov_b32_e32 v90, v0
	v_mov_b32_e32 v91, v0
	v_mov_b32_e32 v92, v0
	v_mov_b32_e32 v93, v0
	v_mov_b32_e32 v94, v0
	v_mov_b32_e32 v95, v0
	v_mov_b32_e32 v120, v0
	v_mov_b32_e32 v121, v0
	v_mov_b32_e32 v122, v0
	v_mov_b32_e32 v123, v0
	v_mov_b32_e32 v124, v0
	v_mov_b32_e32 v125, v0
	v_mov_b32_e32 v126, v0
	v_mov_b32_e32 v127, v0
	v_readfirstlane_b32 s6, v130
	v_readfirstlane_b32 s7, v131
	v_readfirstlane_b32 s8, v128
	v_readfirstlane_b32 s9, v129
	v_readfirstlane_b32 s17, v134
	v_and_b32_e32 v176, 63, v132
	v_lshrrev_b32_e32 v177, 6, v132
	v_lshrrev_b32_e32 v178, 3, v176
	v_and_b32_e32 v179, 7, v176
	v_lshrrev_b32_e32 v180, 4, v176
	v_and_b32_e32 v181, 1, v177
	v_lshrrev_b32_e32 v182, 1, v177
	v_lshl_add_u32 v183, v181, 2, v180
	v_xor_b32_e32 v183, v179, v183
	v_lshl_add_u32 v184, v177, 3, v178
	v_lshlrev_b32_e32 v188, 11, v184
	v_lshl_add_u32 v128, v183, 4, v188
	v_add_u32_e32 v129, 0x10000, v128
	v_add_u32_e32 v130, 0x40000, v128
	v_add_u32_e32 v131, 0x50000, v128
	v_bfe_u32 v185, v178, 1, 1
	v_lshl_or_b32 v185, v181, 1, v185
	v_lshl_or_b32 v185, v182, 2, v185
	v_xor_b32_e32 v185, v179, v185
	v_lshl_add_u32 v134, v185, 4, v188
	v_add_u32_e32 v143, 0x10000, v134
	v_add_u32_e32 v196, 0x20000, v134
	v_add_u32_e32 v197, 0x30000, v134
	v_and_b32_e32 v186, 15, v176
	v_bfe_u32 v187, v176, 1, 3
	v_xor_b32_e32 v187, v180, v187
	v_lshlrev_b32_e32 v187, 4, v187
	v_lshl_add_u32 v188, v182, 6, v186
	v_lshl_add_u32 v219, v188, 7, v187
	v_xor_b32_e32 v228, 64, v219
	v_lshrrev_b32_e32 v189, 2, v186
	v_lshlrev_b32_e32 v189, 3, v189
	v_and_b32_e32 v188, 3, v186
	v_add_u32_e32 v189, v189, v188
	v_lshl_add_u32 v189, v181, 6, v189
	v_lshl_add_u32 v231, v189, 7, v187
	v_xor_b32_e32 v216, 64, v231
	s_lshl_b32 s11, s17, 5
	s_sub_u32 s6, s6, s11
	s_subb_u32 s7, s7, 0
	s_sub_u32 s8, s8, s11
	s_subb_u32 s9, s9, 0
	s_add_u32 m0, s17, 0x8000
	s_nop 0
	global_load_lds_dwordx4 v128, s[6:7]
	s_add_u32 m0, s17, 0x9000
	s_nop 0
	global_load_lds_dwordx4 v129, s[6:7]
	s_add_u32 m0, s17, 0xa000
	s_nop 0
	global_load_lds_dwordx4 v130, s[6:7]
	s_add_u32 m0, s17, 0xb000
	s_nop 0
	global_load_lds_dwordx4 v131, s[6:7]
	s_add_u32 s6, s6, 0x20000
	s_addc_u32 s7, s7, 0
	s_add_u32 m0, s17, 0xc000
	s_nop 0
	global_load_lds_dwordx4 v128, s[6:7]
	s_add_u32 m0, s17, 0xd000
	s_nop 0
	global_load_lds_dwordx4 v129, s[6:7]
	s_add_u32 m0, s17, 0xe000
	s_nop 0
	global_load_lds_dwordx4 v130, s[6:7]
	s_add_u32 m0, s17, 0xf000
	s_nop 0
	global_load_lds_dwordx4 v131, s[6:7]
	s_add_u32 s6, s6, 0xfffe0080
	s_addc_u32 s7, s7, -1
	s_add_u32 m0, s17, 0x0
	s_nop 0
	global_load_lds_dwordx4 v134, s[8:9]
	s_add_u32 m0, s17, 0x1000
	s_nop 0
	global_load_lds_dwordx4 v143, s[8:9]
	s_add_u32 m0, s17, 0x2000
	s_nop 0
	global_load_lds_dwordx4 v196, s[8:9]
	s_add_u32 m0, s17, 0x3000
	s_nop 0
	global_load_lds_dwordx4 v197, s[8:9]
	s_add_u32 s8, s8, 0x80
	s_addc_u32 s9, s9, 0
	s_add_u32 m0, s17, 0x4000
	s_nop 0
	global_load_lds_dwordx4 v134, s[8:9]
	s_add_u32 m0, s17, 0x5000
	s_nop 0
	global_load_lds_dwordx4 v143, s[8:9]
	s_add_u32 m0, s17, 0x6000
	s_nop 0
	global_load_lds_dwordx4 v196, s[8:9]
	s_add_u32 m0, s17, 0x7000
	s_nop 0
	global_load_lds_dwordx4 v197, s[8:9]
	s_add_u32 s8, s8, 0x80
	s_addc_u32 s9, s9, 0
	s_waitcnt vmcnt(0)
	s_barrier
	s_mov_b32 s10, 0
	s_mov_b32 s16, 0
	ds_read_b128 v[144:147], v219 offset:32768
	ds_read_b128 v[148:151], v219 offset:34816
	ds_read_b128 v[152:155], v219 offset:36864
	ds_read_b128 v[156:159], v219 offset:38912
	ds_read_b128 v[160:163], v228 offset:32768
	ds_read_b128 v[164:167], v228 offset:34816
	ds_read_b128 v[168:171], v228 offset:36864
	ds_read_b128 v[172:175], v228 offset:38912
	v_add_u32_e32 v248, s10, v231
	ds_read_b128 v[236:239], v248 offset:0
	ds_read_b128 v[240:243], v248 offset:512
	ds_read_b128 v[244:247], v248 offset:4096
	ds_read_b128 v[248:251], v248 offset:4608
	s_waitcnt lgkmcnt(0)
	s_barrier

; __global__ void __launch_bounds__(NTHR, 2) mega(P p, int ph_lo, int ph_hi) {
;   cg::grid_group grid = cg::this_grid();
;   __shared__ __attribute__((aligned(1024))) char smem[73728];
	.amdhsa_kernel _Z4mega1Pii
		.amdhsa_group_segment_fixed_size 73744
		.amdhsa_private_segment_fixed_size 0
		.amdhsa_kernarg_size 2456
		.amdhsa_user_sgpr_count 2
		.amdhsa_user_sgpr_dispatch_ptr 0
		.amdhsa_user_sgpr_queue_ptr 0
		.amdhsa_user_sgpr_kernarg_segment_ptr 1
		.amdhsa_user_sgpr_dispatch_id 0
		.amdhsa_user_sgpr_kernarg_preload_length 0
		.amdhsa_user_sgpr_kernarg_preload_offset 0
		.amdhsa_user_sgpr_private_segment_size 0
		.amdhsa_uses_dynamic_stack 0
		.amdhsa_enable_private_segment 0
		.amdhsa_system_sgpr_workgroup_id_x 1
		.amdhsa_system_sgpr_workgroup_id_y 0
		.amdhsa_system_sgpr_workgroup_id_z 0
		.amdhsa_system_sgpr_workgroup_info 0
		.amdhsa_system_vgpr_workitem_id 2
		.amdhsa_next_free_vgpr 256
		.amdhsa_next_free_sgpr 100
		.amdhsa_accum_offset 256
		.amdhsa_reserve_vcc 1
		.amdhsa_float_round_mode_32 0
		.amdhsa_float_round_mode_16_64 0
		.amdhsa_float_denorm_mode_32 3
		.amdhsa_float_denorm_mode_16_64 3
		.amdhsa_dx10_clamp 1
		.amdhsa_ieee_mode 1
		.amdhsa_fp16_overflow 0
		.amdhsa_tg_split 0
		.amdhsa_exception_fp_ieee_invalid_op 0
		.amdhsa_exception_fp_denorm_src 0
		.amdhsa_exception_fp_ieee_div_zero 0
		.amdhsa_exception_fp_ieee_overflow 0
		.amdhsa_exception_fp_ieee_underflow 0
		.amdhsa_exception_fp_ieee_inexact 0
		.amdhsa_exception_int_div_zero 0
	.end_amdhsa_kernel

; __global__ void __launch_bounds__(NTHR, 2) mega(P p, int ph_lo, int ph_hi) {
;   cg::grid_group grid = cg::this_grid();
;   __shared__ __attribute__((aligned(1024))) char smem[73728];
amdhsa.kernels:
  - .agpr_count:     0
    .args:
      - .offset:         0
        .size:           2192
        .value_kind:     by_value
      - .offset:         2192
        .size:           4
        .value_kind:     by_value
      - .offset:         2196
        .size:           4
        .value_kind:     by_value
      - .offset:         2200
        .size:           4
        .value_kind:     hidden_block_count_x
      - .offset:         2204
        .size:           4
        .value_kind:     hidden_block_count_y
      - .offset:         2208
        .size:           4
        .value_kind:     hidden_block_count_z
      - .offset:         2212
        .size:           2
        .value_kind:     hidden_group_size_x
      - .offset:         2214
        .size:           2
        .value_kind:     hidden_group_size_y
      - .offset:         2216
        .size:           2
        .value_kind:     hidden_group_size_z
      - .offset:         2218
        .size:           2
        .value_kind:     hidden_remainder_x
      - .offset:         2220
        .size:           2
        .value_kind:     hidden_remainder_y
      - .offset:         2222
        .size:           2
        .value_kind:     hidden_remainder_z
      - .offset:         2240
        .size:           8
        .value_kind:     hidden_global_offset_x
      - .offset:         2248
        .size:           8
        .value_kind:     hidden_global_offset_y
      - .offset:         2256
        .size:           8
        .value_kind:     hidden_global_offset_z
      - .offset:         2264
        .size:           2
        .value_kind:     hidden_grid_dims
      - .offset:         2288
        .size:           8
        .value_kind:     hidden_multigrid_sync_arg
    .group_segment_fixed_size: 73744
    .kernarg_segment_align: 8
    .kernarg_segment_size: 2456
    .language:       OpenCL C
    .language_version:
      - 2
      - 0
    .max_flat_workgroup_size: 256
    .name:           _Z4mega1Pii
    .private_segment_fixed_size: 0
    .sgpr_count:     106
    .sgpr_spill_count: 174
    .symbol:         _Z4mega1Pii.kd
    .uniform_work_group_size: 1
    .uses_dynamic_stack: false
    .vgpr_count:     256
    .vgpr_spill_count: 0
    .wavefront_size: 64
